# v9 + ssq row-statistic loads hoisted before the K loop in the four in-proj GEMMs + lambda dot-product loads software-pipelined
# speedup vs baseline: 1.0387x; 1.0044x over previous
.LBB0_114:
	s_lshl_b32 s98, s12, 8
	s_add_i32 s98, s98, s70
	v_or_b32_e32 v249, s98, v147
	v_lshlrev_b32_e32 v249, 2, v249
	global_load_dword v240, v249, s[16:17]
	global_load_dword v241, v249, s[16:17] offset:64
	global_load_dword v242, v249, s[16:17] offset:128
	global_load_dword v243, v249, s[16:17] offset:192
	global_load_dword v244, v249, s[16:17] offset:512
	global_load_dword v245, v249, s[16:17] offset:576
	global_load_dword v246, v249, s[16:17] offset:640
	global_load_dword v247, v249, s[16:17] offset:704
	s_ashr_i32 s41, s40, 31
	s_lshl_b64 s[42:43], s[40:41], 20
	s_add_u32 s42, s58, s42
	s_addc_u32 s43, s59, s43
	s_and_b64 s[52:53], s[2:3], exec
	s_cselect_b32 s5, s43, s15
	s_cselect_b32 s13, s42, s14
	s_ashr_i32 s39, s38, 31
	s_lshl_b64 s[52:53], s[38:39], 20
	s_add_u32 s52, s60, s52
	s_addc_u32 s53, s61, s53
	s_and_b64 s[54:55], s[2:3], exec
	s_cselect_b32 s33, s53, s19
	s_cselect_b32 s39, s52, s18
	s_add_u32 s14, s14, 0x80080
	s_addc_u32 s15, s15, 0
	s_add_u32 s41, s18, 0x100
	v_mov_b32_e32 v0, 0
	s_addc_u32 s80, s19, 0
	s_mov_b32 s81, -2
	v_mov_b32_e32 v1, v0
	v_mov_b32_e32 v2, v0
	v_mov_b32_e32 v3, v0
	v_mov_b32_e32 v4, v0
	v_mov_b32_e32 v5, v0
	v_mov_b32_e32 v6, v0
	v_mov_b32_e32 v7, v0
	v_mov_b32_e32 v16, v0
	v_mov_b32_e32 v17, v0
	v_mov_b32_e32 v18, v0
	v_mov_b32_e32 v19, v0
	v_mov_b32_e32 v20, v0
	v_mov_b32_e32 v21, v0
	v_mov_b32_e32 v22, v0
	v_mov_b32_e32 v23, v0
	v_mov_b32_e32 v32, v0
	v_mov_b32_e32 v33, v0
	v_mov_b32_e32 v34, v0
	v_mov_b32_e32 v35, v0
	v_mov_b32_e32 v36, v0
	v_mov_b32_e32 v37, v0
	v_mov_b32_e32 v38, v0
	v_mov_b32_e32 v39, v0
	v_mov_b32_e32 v48, v0
	v_mov_b32_e32 v49, v0
	v_mov_b32_e32 v50, v0
	v_mov_b32_e32 v51, v0
	v_mov_b32_e32 v52, v0
	v_mov_b32_e32 v53, v0
	v_mov_b32_e32 v54, v0
	v_mov_b32_e32 v55, v0
	v_mov_b32_e32 v8, v0
	v_mov_b32_e32 v9, v0
	v_mov_b32_e32 v10, v0
	v_mov_b32_e32 v11, v0
	v_mov_b32_e32 v12, v0
	v_mov_b32_e32 v13, v0
	v_mov_b32_e32 v14, v0
	v_mov_b32_e32 v15, v0
	v_mov_b32_e32 v24, v0
	v_mov_b32_e32 v25, v0
	v_mov_b32_e32 v26, v0
	v_mov_b32_e32 v27, v0
	v_mov_b32_e32 v28, v0
	v_mov_b32_e32 v29, v0
	v_mov_b32_e32 v30, v0
	v_mov_b32_e32 v31, v0
	v_mov_b32_e32 v40, v0
	v_mov_b32_e32 v41, v0
	v_mov_b32_e32 v42, v0
	v_mov_b32_e32 v43, v0
	v_mov_b32_e32 v44, v0
	v_mov_b32_e32 v45, v0
	v_mov_b32_e32 v46, v0
	v_mov_b32_e32 v47, v0
	v_mov_b32_e32 v56, v0
	v_mov_b32_e32 v57, v0
	v_mov_b32_e32 v58, v0
	v_mov_b32_e32 v59, v0
	v_mov_b32_e32 v60, v0
	v_mov_b32_e32 v61, v0
	v_mov_b32_e32 v62, v0
	v_mov_b32_e32 v63, v0
	v_mov_b32_e32 v64, v0
	v_mov_b32_e32 v65, v0
	v_mov_b32_e32 v66, v0
	v_mov_b32_e32 v67, v0
	v_mov_b32_e32 v68, v0
	v_mov_b32_e32 v69, v0
	v_mov_b32_e32 v70, v0
	v_mov_b32_e32 v71, v0
	v_mov_b32_e32 v80, v0
	v_mov_b32_e32 v81, v0
	v_mov_b32_e32 v82, v0
	v_mov_b32_e32 v83, v0
	v_mov_b32_e32 v84, v0
	v_mov_b32_e32 v85, v0
	v_mov_b32_e32 v86, v0
	v_mov_b32_e32 v87, v0
	v_mov_b32_e32 v96, v0
	v_mov_b32_e32 v97, v0
	v_mov_b32_e32 v98, v0
	v_mov_b32_e32 v99, v0
	v_mov_b32_e32 v100, v0
	v_mov_b32_e32 v101, v0
	v_mov_b32_e32 v102, v0
	v_mov_b32_e32 v103, v0
	v_mov_b32_e32 v112, v0
	v_mov_b32_e32 v113, v0
	v_mov_b32_e32 v114, v0
	v_mov_b32_e32 v115, v0
	v_mov_b32_e32 v116, v0
	v_mov_b32_e32 v117, v0
	v_mov_b32_e32 v118, v0
	v_mov_b32_e32 v119, v0
	v_mov_b32_e32 v72, v0
	v_mov_b32_e32 v73, v0
	v_mov_b32_e32 v74, v0
	v_mov_b32_e32 v75, v0
	v_mov_b32_e32 v76, v0
	v_mov_b32_e32 v77, v0
	v_mov_b32_e32 v78, v0
	v_mov_b32_e32 v79, v0
	v_mov_b32_e32 v88, v0
	v_mov_b32_e32 v89, v0
	v_mov_b32_e32 v90, v0
	v_mov_b32_e32 v91, v0
	v_mov_b32_e32 v92, v0
	v_mov_b32_e32 v93, v0
	v_mov_b32_e32 v94, v0
	v_mov_b32_e32 v95, v0
	v_mov_b32_e32 v104, v0
	v_mov_b32_e32 v105, v0
	v_mov_b32_e32 v106, v0
	v_mov_b32_e32 v107, v0
	v_mov_b32_e32 v108, v0
	v_mov_b32_e32 v109, v0
	v_mov_b32_e32 v110, v0
	v_mov_b32_e32 v111, v0
	v_mov_b32_e32 v120, v0
	v_mov_b32_e32 v121, v0
	v_mov_b32_e32 v122, v0
	v_mov_b32_e32 v123, v0
	v_mov_b32_e32 v124, v0
	v_mov_b32_e32 v125, v0
	v_mov_b32_e32 v126, v0
	v_mov_b32_e32 v127, v0

.LBB0_118:
	s_lshl_b32 s19, s12, 8
	s_add_i32 s19, s19, s70
	v_or_b32_e32 v156, s19, v147
	v_ashrrev_i32_e32 v157, 31, v156
	v_lshl_add_u64 v[128:129], v[156:157], 2, s[16:17]
	v_mov_b32_e32 v144, v240
	v_or_b32_e32 v164, 16, v156
	v_ashrrev_i32_e32 v165, 31, v164
	v_or_b32_e32 v162, 32, v156
	v_or_b32_e32 v160, 48, v156
	v_lshl_add_u64 v[130:131], v[164:165], 2, s[16:17]
	v_ashrrev_i32_e32 v163, 31, v162
	v_ashrrev_i32_e32 v161, 31, v160
	v_lshl_add_u64 v[132:133], v[162:163], 2, s[16:17]
	v_lshl_add_u64 v[134:135], v[160:161], 2, s[16:17]
	v_mov_b32_e32 v178, v241
	v_mov_b32_e32 v177, v242
	v_mov_b32_e32 v176, v243
	v_mov_b32_e32 v165, v244
	v_mov_b32_e32 v163, v245
	v_mov_b32_e32 v161, v246
	v_mov_b32_e32 v157, v247
	s_cmp_lt_u32 s4, 16
	s_cselect_b64 s[12:13], -1, 0
	s_cmp_gt_u32 s4, 7
	s_cselect_b64 s[14:15], -1, 0
	s_and_b64 s[12:13], s[14:15], s[12:13]
	s_and_b64 s[12:13], s[12:13], exec
	s_cselect_b32 s5, 2, 1
	s_cmp_gt_i32 s4, 3
	s_cselect_b64 s[12:13], -1, 0
	s_and_b64 s[14:15], s[12:13], exec
	s_cselect_b32 s18, s5, 0
	s_cmp_gt_i32 s18, 1
	s_mov_b64 s[14:15], -1
	s_waitcnt vmcnt(0)
	v_fmamk_f32 v128, v144, 0x3a000000, v175
	v_mul_f32_e32 v129, 0x4b800000, v128
	v_cmp_gt_f32_e32 vcc, s78, v128
	s_nop 1
	v_cndmask_b32_e32 v128, v128, v129, vcc
	v_rsq_f32_e32 v128, v128
	s_nop 0
	v_mul_f32_e32 v129, 0x45800000, v128
	v_cndmask_b32_e32 v168, v128, v129, vcc
	v_pk_mul_f32 v[126:127], v[126:127], v[168:169] op_sel_hi:[1,0]
	v_pk_mul_f32 v[124:125], v[124:125], v[168:169] op_sel_hi:[1,0]
	v_pk_mul_f32 v[122:123], v[122:123], v[168:169] op_sel_hi:[1,0]
	v_pk_mul_f32 v[120:121], v[120:121], v[168:169] op_sel_hi:[1,0]
	s_cbranch_scc0 .LBB0_120
	v_mul_f32_e32 v129, 0x3d372713, v120
	v_mul_f32_e32 v129, v120, v129
	v_mul_f32_e32 v130, 0x3d372713, v125
	v_fma_f32 v129, v120, v129, v120
	v_mul_f32_e32 v130, v125, v130
	v_mul_f32_e32 v129, 0x3f4c422a, v129
	v_fma_f32 v130, v125, v130, v125
	v_mul_f32_e32 v129, -2.0, v129
	v_mul_f32_e32 v130, 0x3f4c422a, v130
	v_mul_f32_e32 v129, 0x3fb8aa3b, v129
	v_mul_f32_e32 v130, -2.0, v130
	v_exp_f32_e32 v129, v129
	v_mul_f32_e32 v130, 0x3fb8aa3b, v130
	v_exp_f32_e32 v130, v130
	v_mul_f32_e32 v131, 0x3d372713, v126
	v_add_f32_e32 v129, 1.0, v129
	v_rcp_f32_e32 v158, v129
	v_add_f32_e32 v129, 1.0, v130
	v_mul_f32_e32 v130, 0x3d372713, v121
	v_mul_f32_e32 v132, 0x3d372713, v122
	v_mul_f32_e32 v130, v121, v130
	v_mul_f32_e32 v131, v126, v131
	v_mul_f32_e32 v132, v122, v132
	v_fma_f32 v130, v121, v130, v121
	v_fma_f32 v131, v126, v131, v126
	v_fma_f32 v132, v122, v132, v122
	v_mul_f32_e32 v130, 0x3f4c422a, v130
	v_mul_f32_e32 v131, 0x3f4c422a, v131
	v_mul_f32_e32 v132, 0x3f4c422a, v132
	v_mul_f32_e32 v130, -2.0, v130
	v_mul_f32_e32 v131, -2.0, v131
	v_mul_f32_e32 v132, -2.0, v132
	v_mul_f32_e32 v130, 0x3fb8aa3b, v130
	v_mul_f32_e32 v131, 0x3fb8aa3b, v131
	v_mul_f32_e32 v132, 0x3fb8aa3b, v132
	v_exp_f32_e32 v130, v130
	v_exp_f32_e32 v131, v131
	v_exp_f32_e32 v132, v132
	v_mul_f32_e32 v128, 0x3d372713, v124
	v_add_f32_e32 v133, 1.0, v130
	v_add_f32_e32 v130, 1.0, v131
	v_add_f32_e32 v131, 1.0, v132
	v_mul_f32_e32 v132, 0x3d372713, v127
	v_mul_f32_e32 v134, 0x3d372713, v123
	v_mul_f32_e32 v128, v124, v128
	v_mul_f32_e32 v132, v127, v132
	v_mul_f32_e32 v134, v123, v134
	v_fma_f32 v128, v124, v128, v124
	v_fma_f32 v132, v127, v132, v127
	v_fma_f32 v134, v123, v134, v123
	v_mul_f32_e32 v128, 0x3f4c422a, v128
	v_mul_f32_e32 v132, 0x3f4c422a, v132
	v_mul_f32_e32 v134, 0x3f4c422a, v134
	v_mul_f32_e32 v128, -2.0, v128
	v_mul_f32_e32 v132, -2.0, v132
	v_mul_f32_e32 v134, -2.0, v134
	v_mul_f32_e32 v128, 0x3fb8aa3b, v128
	v_mul_f32_e32 v132, 0x3fb8aa3b, v132
	v_mul_f32_e32 v134, 0x3fb8aa3b, v134
	v_exp_f32_e32 v128, v128
	v_exp_f32_e32 v132, v132
	v_exp_f32_e32 v134, v134
	v_rcp_f32_e32 v166, v131
	v_add_f32_e32 v128, 1.0, v128
	v_add_f32_e32 v131, 1.0, v132
	v_add_f32_e32 v132, 1.0, v134
	v_rcp_f32_e32 v128, v128
	v_rcp_f32_e32 v129, v129
	v_rcp_f32_e32 v130, v130
	v_rcp_f32_e32 v131, v131
	v_rcp_f32_e32 v167, v132
	v_rcp_f32_e32 v159, v133
	v_pk_mul_f32 v[132:133], v[124:125], v[128:129]
	v_pk_mul_f32 v[134:135], v[126:127], v[130:131]
	v_pk_mul_f32 v[130:131], v[122:123], v[166:167]
	v_pk_mul_f32 v[128:129], v[120:121], v[158:159]
	s_mov_b64 s[14:15], 0

.LBB0_603:
	v_lshl_add_u32 v249, s4, 8, v212
	v_lshlrev_b32_e32 v249, 2, v249
	global_load_dword v240, v249, s[34:35]
	global_load_dword v241, v249, s[34:35] offset:64
	global_load_dword v242, v249, s[34:35] offset:128
	global_load_dword v243, v249, s[34:35] offset:192
	global_load_dword v244, v249, s[34:35] offset:512
	global_load_dword v245, v249, s[34:35] offset:576
	global_load_dword v246, v249, s[34:35] offset:640
	global_load_dword v247, v249, s[34:35] offset:704
	s_ashr_i32 s69, s68, 31
	s_lshl_b64 s[12:13], s[68:69], 20
	s_add_u32 s70, s18, s12
	s_addc_u32 s71, s19, s13
	s_and_b64 s[12:13], s[2:3], exec
	s_cselect_b32 s5, s71, s7
	s_cselect_b32 s9, s70, s6
	s_ashr_i32 s67, s66, 31
	s_lshl_b64 s[12:13], s[66:67], 20
	s_add_u32 s72, s53, s12
	s_addc_u32 s73, s60, s13
	s_and_b64 s[12:13], s[2:3], exec
	s_cselect_b32 s33, s73, s11
	s_cselect_b32 s67, s72, s10
	s_add_u32 s6, s6, 0x80080
	s_addc_u32 s7, s7, 0
	s_add_u32 s69, s10, 0x100
	v_mov_b32_e32 v0, 0
	s_addc_u32 s74, s11, 0
	s_mov_b32 s75, -2
	v_mov_b32_e32 v1, v0
	v_mov_b32_e32 v2, v0
	v_mov_b32_e32 v3, v0
	v_mov_b32_e32 v4, v0
	v_mov_b32_e32 v5, v0
	v_mov_b32_e32 v6, v0
	v_mov_b32_e32 v7, v0
	v_mov_b32_e32 v16, v0
	v_mov_b32_e32 v17, v0
	v_mov_b32_e32 v18, v0
	v_mov_b32_e32 v19, v0
	v_mov_b32_e32 v20, v0
	v_mov_b32_e32 v21, v0
	v_mov_b32_e32 v22, v0
	v_mov_b32_e32 v23, v0
	v_mov_b32_e32 v48, v0
	v_mov_b32_e32 v49, v0
	v_mov_b32_e32 v50, v0
	v_mov_b32_e32 v51, v0
	v_mov_b32_e32 v52, v0
	v_mov_b32_e32 v53, v0
	v_mov_b32_e32 v54, v0
	v_mov_b32_e32 v55, v0
	v_mov_b32_e32 v80, v0
	v_mov_b32_e32 v81, v0
	v_mov_b32_e32 v82, v0
	v_mov_b32_e32 v83, v0
	v_mov_b32_e32 v84, v0
	v_mov_b32_e32 v85, v0
	v_mov_b32_e32 v86, v0
	v_mov_b32_e32 v87, v0
	v_mov_b32_e32 v8, v0
	v_mov_b32_e32 v9, v0
	v_mov_b32_e32 v10, v0
	v_mov_b32_e32 v11, v0
	v_mov_b32_e32 v12, v0
	v_mov_b32_e32 v13, v0
	v_mov_b32_e32 v14, v0
	v_mov_b32_e32 v15, v0
	v_mov_b32_e32 v28, v0
	v_mov_b32_e32 v29, v0
	v_mov_b32_e32 v30, v0
	v_mov_b32_e32 v31, v0
	v_mov_b32_e32 v36, v0
	v_mov_b32_e32 v37, v0
	v_mov_b32_e32 v38, v0
	v_mov_b32_e32 v39, v0
	v_mov_b32_e32 v72, v0
	v_mov_b32_e32 v73, v0
	v_mov_b32_e32 v74, v0
	v_mov_b32_e32 v75, v0
	v_mov_b32_e32 v76, v0
	v_mov_b32_e32 v77, v0
	v_mov_b32_e32 v78, v0
	v_mov_b32_e32 v79, v0
	v_mov_b32_e32 v88, v0
	v_mov_b32_e32 v89, v0
	v_mov_b32_e32 v90, v0
	v_mov_b32_e32 v91, v0
	v_mov_b32_e32 v92, v0
	v_mov_b32_e32 v93, v0
	v_mov_b32_e32 v94, v0
	v_mov_b32_e32 v95, v0
	v_mov_b32_e32 v96, v0
	v_mov_b32_e32 v97, v0
	v_mov_b32_e32 v98, v0
	v_mov_b32_e32 v99, v0
	v_mov_b32_e32 v100, v0
	v_mov_b32_e32 v101, v0
	v_mov_b32_e32 v102, v0
	v_mov_b32_e32 v103, v0
	v_mov_b32_e32 v112, v0
	v_mov_b32_e32 v113, v0
	v_mov_b32_e32 v114, v0
	v_mov_b32_e32 v115, v0
	v_mov_b32_e32 v116, v0
	v_mov_b32_e32 v117, v0
	v_mov_b32_e32 v118, v0
	v_mov_b32_e32 v119, v0
	v_mov_b32_e32 v128, v0
	v_mov_b32_e32 v129, v0
	v_mov_b32_e32 v130, v0
	v_mov_b32_e32 v131, v0
	v_mov_b32_e32 v132, v0
	v_mov_b32_e32 v133, v0
	v_mov_b32_e32 v134, v0
	v_mov_b32_e32 v135, v0
	v_mov_b32_e32 v144, v0
	v_mov_b32_e32 v145, v0
	v_mov_b32_e32 v146, v0
	v_mov_b32_e32 v147, v0
	v_mov_b32_e32 v148, v0
	v_mov_b32_e32 v149, v0
	v_mov_b32_e32 v150, v0
	v_mov_b32_e32 v151, v0
	v_mov_b32_e32 v104, v0
	v_mov_b32_e32 v105, v0
	v_mov_b32_e32 v106, v0
	v_mov_b32_e32 v107, v0
	v_mov_b32_e32 v108, v0
	v_mov_b32_e32 v109, v0
	v_mov_b32_e32 v110, v0
	v_mov_b32_e32 v111, v0
	v_mov_b32_e32 v120, v0
	v_mov_b32_e32 v121, v0
	v_mov_b32_e32 v122, v0
	v_mov_b32_e32 v123, v0
	v_mov_b32_e32 v124, v0
	v_mov_b32_e32 v125, v0
	v_mov_b32_e32 v126, v0
	v_mov_b32_e32 v127, v0
	v_mov_b32_e32 v136, v0
	v_mov_b32_e32 v137, v0
	v_mov_b32_e32 v138, v0
	v_mov_b32_e32 v139, v0
	v_mov_b32_e32 v140, v0
	v_mov_b32_e32 v141, v0
	v_mov_b32_e32 v142, v0
	v_mov_b32_e32 v143, v0
	v_mov_b32_e32 v156, v0
	v_mov_b32_e32 v157, v0
	v_mov_b32_e32 v158, v0
	v_mov_b32_e32 v159, v0
	v_mov_b32_e32 v160, v0
	v_mov_b32_e32 v161, v0
	v_mov_b32_e32 v162, v0
	v_mov_b32_e32 v163, v0

.LBB0_607:
	v_lshl_add_u32 v198, s4, 8, v212
	v_ashrrev_i32_e32 v199, 31, v198
	v_or_b32_e32 v206, 16, v198
	v_or_b32_e32 v204, 32, v198
	v_or_b32_e32 v202, 48, v198
	v_lshl_add_u64 v[24:25], v[198:199], 2, s[34:35]
	v_ashrrev_i32_e32 v207, 31, v206
	v_ashrrev_i32_e32 v205, 31, v204
	v_ashrrev_i32_e32 v203, 31, v202
	v_lshl_add_u64 v[26:27], v[206:207], 2, s[34:35]
	v_lshl_add_u64 v[32:33], v[204:205], 2, s[34:35]
	v_lshl_add_u64 v[34:35], v[202:203], 2, s[34:35]
	v_mov_b32_e32 v164, v240
	v_mov_b32_e32 v228, v241
	v_mov_b32_e32 v227, v242
	v_mov_b32_e32 v226, v243
	v_mov_b32_e32 v224, v244
	v_mov_b32_e32 v223, v245
	v_mov_b32_e32 v222, v246
	v_mov_b32_e32 v221, v247
	s_ashr_i32 s4, s8, 3
	s_cmp_gt_i32 s4, 1
	s_cselect_b64 s[12:13], -1, 0
	s_cmp_lt_i32 s4, 2
	s_cselect_b64 s[6:7], -1, 0
	s_and_b64 s[6:7], s[42:43], s[6:7]
	v_lshlrev_b32_e32 v225, 4, v198
	v_cndmask_b32_e64 v24, 0, 1, s[6:7]
	v_mov_b32_e32 v152, 0
	v_cmp_ne_u32_e64 s[10:11], 1, v24
	v_and_b32_e32 v24, 0xfcf0, v225
	s_andn2_b64 vcc, exec, s[6:7]
	v_lshlrev_b32_e32 v180, 2, v24
	v_mov_b32_e32 v153, v152
	v_mov_b32_e32 v154, v152
	v_mov_b32_e32 v155, v152
	v_mov_b32_e32 v60, v152
	v_mov_b32_e32 v61, v152
	v_mov_b32_e32 v62, v152
	v_mov_b32_e32 v63, v152
	v_mov_b32_e32 v56, v152
	v_mov_b32_e32 v57, v152
	v_mov_b32_e32 v58, v152
	v_mov_b32_e32 v59, v152
	v_mov_b32_e32 v68, v152
	v_mov_b32_e32 v69, v152
	v_mov_b32_e32 v70, v152
	v_mov_b32_e32 v71, v152
	v_mov_b32_e32 v64, v152
	v_mov_b32_e32 v65, v152
	v_mov_b32_e32 v66, v152
	v_mov_b32_e32 v67, v152
	v_mov_b32_e32 v32, v152
	v_mov_b32_e32 v33, v152
	v_mov_b32_e32 v34, v152
	v_mov_b32_e32 v35, v152
	v_mov_b32_e32 v24, v152
	v_mov_b32_e32 v25, v152
	v_mov_b32_e32 v26, v152
	v_mov_b32_e32 v27, v152
	v_mov_b32_e32 v40, v152
	v_mov_b32_e32 v41, v152
	v_mov_b32_e32 v42, v152
	v_mov_b32_e32 v43, v152
	v_mov_b32_e32 v44, v152
	v_mov_b32_e32 v45, v152
	v_mov_b32_e32 v46, v152
	v_mov_b32_e32 v47, v152
	s_cbranch_vccnz .LBB0_609
	v_lshl_add_u64 v[24:25], v[186:187], 0, v[180:181]
	global_load_dwordx4 v[60:63], v[24:25], off
	global_load_dwordx4 v[56:59], v[24:25], off offset:16
	v_lshl_add_u64 v[40:41], v[188:189], 0, v[180:181]
	global_load_dwordx4 v[152:155], v[40:41], off offset:1040
	global_load_dwordx4 v[68:71], v[40:41], off
	global_load_dwordx4 v[64:67], v[40:41], off offset:16
	global_load_dwordx4 v[32:35], v[24:25], off offset:1024
	s_nop 0
	global_load_dwordx4 v[24:27], v[24:25], off offset:1040
	s_nop 0
	global_load_dwordx4 v[40:43], v[40:41], off offset:1024
	s_waitcnt vmcnt(0)
	v_mov_b32_e32 v44, v152
	v_mov_b32_e32 v45, v153
	v_mov_b32_e32 v46, v154
	v_mov_b32_e32 v47, v155

.LBB0_837:
	s_waitcnt lgkmcnt(0)
	global_load_dwordx4 v[4:7], v2, s[44:45]
	global_load_dwordx4 v[36:39], v2, s[46:47]
	global_load_dwordx4 v[68:71], v2, s[48:49]
	global_load_dwordx4 v[100:103], v2, s[50:51]
	global_load_dwordx4 v[8:11], v2, s[44:45] offset:16
	global_load_dwordx4 v[40:43], v2, s[46:47] offset:16
	global_load_dwordx4 v[72:75], v2, s[48:49] offset:16
	global_load_dwordx4 v[104:107], v2, s[50:51] offset:16
	global_load_dwordx4 v[12:15], v2, s[44:45] offset:32
	global_load_dwordx4 v[44:47], v2, s[46:47] offset:32
	global_load_dwordx4 v[76:79], v2, s[48:49] offset:32
	global_load_dwordx4 v[108:111], v2, s[50:51] offset:32
	global_load_dwordx4 v[16:19], v2, s[44:45] offset:48
	global_load_dwordx4 v[48:51], v2, s[46:47] offset:48
	global_load_dwordx4 v[80:83], v2, s[48:49] offset:48
	global_load_dwordx4 v[112:115], v2, s[50:51] offset:48
	global_load_dwordx4 v[20:23], v2, s[44:45] offset:64
	global_load_dwordx4 v[52:55], v2, s[46:47] offset:64
	global_load_dwordx4 v[84:87], v2, s[48:49] offset:64
	global_load_dwordx4 v[116:119], v2, s[50:51] offset:64
	global_load_dwordx4 v[24:27], v2, s[44:45] offset:80
	global_load_dwordx4 v[56:59], v2, s[46:47] offset:80
	global_load_dwordx4 v[88:91], v2, s[48:49] offset:80
	global_load_dwordx4 v[120:123], v2, s[50:51] offset:80
	global_load_dwordx4 v[28:31], v2, s[44:45] offset:96
	global_load_dwordx4 v[60:63], v2, s[46:47] offset:96
	global_load_dwordx4 v[92:95], v2, s[48:49] offset:96
	global_load_dwordx4 v[124:127], v2, s[50:51] offset:96
	global_load_dwordx4 v[32:35], v2, s[44:45] offset:112
	global_load_dwordx4 v[64:67], v2, s[46:47] offset:112
	global_load_dwordx4 v[96:99], v2, s[48:49] offset:112
	global_load_dwordx4 v[128:131], v2, s[50:51] offset:112
	s_waitcnt vmcnt(28)
	v_fma_f32 v0, v4, v36, v0
	v_fma_f32 v1, v68, v100, v1
	v_fma_f32 v0, v5, v37, v0
	v_fma_f32 v1, v69, v101, v1
	v_fma_f32 v0, v6, v38, v0
	v_fma_f32 v1, v70, v102, v1
	v_fma_f32 v0, v7, v39, v0
	v_fma_f32 v1, v71, v103, v1
	global_load_dwordx4 v[4:7], v2, s[44:45] offset:128
	global_load_dwordx4 v[36:39], v2, s[46:47] offset:128
	global_load_dwordx4 v[68:71], v2, s[48:49] offset:128
	global_load_dwordx4 v[100:103], v2, s[50:51] offset:128
	s_waitcnt vmcnt(28)
	v_fma_f32 v0, v8, v40, v0
	v_fma_f32 v1, v72, v104, v1
	v_fma_f32 v0, v9, v41, v0
	v_fma_f32 v1, v73, v105, v1
	v_fma_f32 v0, v10, v42, v0
	v_fma_f32 v1, v74, v106, v1
	v_fma_f32 v0, v11, v43, v0
	v_fma_f32 v1, v75, v107, v1
	global_load_dwordx4 v[8:11], v2, s[44:45] offset:144
	global_load_dwordx4 v[40:43], v2, s[46:47] offset:144
	global_load_dwordx4 v[72:75], v2, s[48:49] offset:144
	global_load_dwordx4 v[104:107], v2, s[50:51] offset:144
	s_waitcnt vmcnt(28)
	v_fma_f32 v0, v12, v44, v0
	v_fma_f32 v1, v76, v108, v1
	v_fma_f32 v0, v13, v45, v0
	v_fma_f32 v1, v77, v109, v1
	v_fma_f32 v0, v14, v46, v0
	v_fma_f32 v1, v78, v110, v1
	v_fma_f32 v0, v15, v47, v0
	v_fma_f32 v1, v79, v111, v1
	global_load_dwordx4 v[12:15], v2, s[44:45] offset:160
	global_load_dwordx4 v[44:47], v2, s[46:47] offset:160
	global_load_dwordx4 v[76:79], v2, s[48:49] offset:160
	global_load_dwordx4 v[108:111], v2, s[50:51] offset:160
	s_waitcnt vmcnt(28)
	v_fma_f32 v0, v16, v48, v0
	v_fma_f32 v1, v80, v112, v1
	v_fma_f32 v0, v17, v49, v0
	v_fma_f32 v1, v81, v113, v1
	v_fma_f32 v0, v18, v50, v0
	v_fma_f32 v1, v82, v114, v1
	v_fma_f32 v0, v19, v51, v0
	v_fma_f32 v1, v83, v115, v1
	global_load_dwordx4 v[16:19], v2, s[44:45] offset:176
	global_load_dwordx4 v[48:51], v2, s[46:47] offset:176
	global_load_dwordx4 v[80:83], v2, s[48:49] offset:176
	global_load_dwordx4 v[112:115], v2, s[50:51] offset:176
	s_waitcnt vmcnt(28)
	v_fma_f32 v0, v20, v52, v0
	v_fma_f32 v1, v84, v116, v1
	v_fma_f32 v0, v21, v53, v0
	v_fma_f32 v1, v85, v117, v1
	v_fma_f32 v0, v22, v54, v0
	v_fma_f32 v1, v86, v118, v1
	v_fma_f32 v0, v23, v55, v0
	v_fma_f32 v1, v87, v119, v1
	global_load_dwordx4 v[20:23], v2, s[44:45] offset:192
	global_load_dwordx4 v[52:55], v2, s[46:47] offset:192
	global_load_dwordx4 v[84:87], v2, s[48:49] offset:192
	global_load_dwordx4 v[116:119], v2, s[50:51] offset:192
	s_waitcnt vmcnt(28)
	v_fma_f32 v0, v24, v56, v0
	v_fma_f32 v1, v88, v120, v1
	v_fma_f32 v0, v25, v57, v0
	v_fma_f32 v1, v89, v121, v1
	v_fma_f32 v0, v26, v58, v0
	v_fma_f32 v1, v90, v122, v1
	v_fma_f32 v0, v27, v59, v0
	v_fma_f32 v1, v91, v123, v1
	global_load_dwordx4 v[24:27], v2, s[44:45] offset:208
	global_load_dwordx4 v[56:59], v2, s[46:47] offset:208
	global_load_dwordx4 v[88:91], v2, s[48:49] offset:208
	global_load_dwordx4 v[120:123], v2, s[50:51] offset:208
	s_waitcnt vmcnt(28)
	v_fma_f32 v0, v28, v60, v0
	v_fma_f32 v1, v92, v124, v1
	v_fma_f32 v0, v29, v61, v0
	v_fma_f32 v1, v93, v125, v1
	v_fma_f32 v0, v30, v62, v0
	v_fma_f32 v1, v94, v126, v1
	v_fma_f32 v0, v31, v63, v0
	v_fma_f32 v1, v95, v127, v1
	global_load_dwordx4 v[28:31], v2, s[44:45] offset:224
	global_load_dwordx4 v[60:63], v2, s[46:47] offset:224
	global_load_dwordx4 v[92:95], v2, s[48:49] offset:224
	global_load_dwordx4 v[124:127], v2, s[50:51] offset:224
	s_waitcnt vmcnt(28)
	v_fma_f32 v0, v32, v64, v0
	v_fma_f32 v1, v96, v128, v1
	v_fma_f32 v0, v33, v65, v0
	v_fma_f32 v1, v97, v129, v1
	v_fma_f32 v0, v34, v66, v0
	v_fma_f32 v1, v98, v130, v1
	v_fma_f32 v0, v35, v67, v0
	v_fma_f32 v1, v99, v131, v1
	global_load_dwordx4 v[32:35], v2, s[44:45] offset:240
	global_load_dwordx4 v[64:67], v2, s[46:47] offset:240
	global_load_dwordx4 v[96:99], v2, s[48:49] offset:240
	global_load_dwordx4 v[128:131], v2, s[50:51] offset:240
	s_waitcnt vmcnt(28)
	v_fma_f32 v0, v4, v36, v0
	v_fma_f32 v1, v68, v100, v1
	v_fma_f32 v0, v5, v37, v0
	v_fma_f32 v1, v69, v101, v1
	v_fma_f32 v0, v6, v38, v0
	v_fma_f32 v1, v70, v102, v1
	v_fma_f32 v0, v7, v39, v0
	v_fma_f32 v1, v71, v103, v1
	global_load_dwordx4 v[4:7], v2, s[44:45] offset:256
	global_load_dwordx4 v[36:39], v2, s[46:47] offset:256
	global_load_dwordx4 v[68:71], v2, s[48:49] offset:256
	global_load_dwordx4 v[100:103], v2, s[50:51] offset:256
	s_waitcnt vmcnt(28)
	v_fma_f32 v0, v8, v40, v0
	v_fma_f32 v1, v72, v104, v1
	v_fma_f32 v0, v9, v41, v0
	v_fma_f32 v1, v73, v105, v1
	v_fma_f32 v0, v10, v42, v0
	v_fma_f32 v1, v74, v106, v1
	v_fma_f32 v0, v11, v43, v0
	v_fma_f32 v1, v75, v107, v1
	global_load_dwordx4 v[8:11], v2, s[44:45] offset:272
	global_load_dwordx4 v[40:43], v2, s[46:47] offset:272
	global_load_dwordx4 v[72:75], v2, s[48:49] offset:272
	global_load_dwordx4 v[104:107], v2, s[50:51] offset:272
	s_waitcnt vmcnt(28)
	v_fma_f32 v0, v12, v44, v0
	v_fma_f32 v1, v76, v108, v1
	v_fma_f32 v0, v13, v45, v0
	v_fma_f32 v1, v77, v109, v1
	v_fma_f32 v0, v14, v46, v0
	v_fma_f32 v1, v78, v110, v1
	v_fma_f32 v0, v15, v47, v0
	v_fma_f32 v1, v79, v111, v1
	global_load_dwordx4 v[12:15], v2, s[44:45] offset:288
	global_load_dwordx4 v[44:47], v2, s[46:47] offset:288
	global_load_dwordx4 v[76:79], v2, s[48:49] offset:288
	global_load_dwordx4 v[108:111], v2, s[50:51] offset:288
	s_waitcnt vmcnt(28)
	v_fma_f32 v0, v16, v48, v0
	v_fma_f32 v1, v80, v112, v1
	v_fma_f32 v0, v17, v49, v0
	v_fma_f32 v1, v81, v113, v1
	v_fma_f32 v0, v18, v50, v0
	v_fma_f32 v1, v82, v114, v1
	v_fma_f32 v0, v19, v51, v0
	v_fma_f32 v1, v83, v115, v1
	global_load_dwordx4 v[16:19], v2, s[44:45] offset:304
	global_load_dwordx4 v[48:51], v2, s[46:47] offset:304
	global_load_dwordx4 v[80:83], v2, s[48:49] offset:304
	global_load_dwordx4 v[112:115], v2, s[50:51] offset:304
	s_waitcnt vmcnt(28)
	v_fma_f32 v0, v20, v52, v0
	v_fma_f32 v1, v84, v116, v1
	v_fma_f32 v0, v21, v53, v0
	v_fma_f32 v1, v85, v117, v1
	v_fma_f32 v0, v22, v54, v0
	v_fma_f32 v1, v86, v118, v1
	v_fma_f32 v0, v23, v55, v0
	v_fma_f32 v1, v87, v119, v1
	global_load_dwordx4 v[20:23], v2, s[44:45] offset:320
	global_load_dwordx4 v[52:55], v2, s[46:47] offset:320
	global_load_dwordx4 v[84:87], v2, s[48:49] offset:320
	global_load_dwordx4 v[116:119], v2, s[50:51] offset:320
	s_waitcnt vmcnt(28)
	v_fma_f32 v0, v24, v56, v0
	v_fma_f32 v1, v88, v120, v1
	v_fma_f32 v0, v25, v57, v0
	v_fma_f32 v1, v89, v121, v1
	v_fma_f32 v0, v26, v58, v0
	v_fma_f32 v1, v90, v122, v1
	v_fma_f32 v0, v27, v59, v0
	v_fma_f32 v1, v91, v123, v1
	global_load_dwordx4 v[24:27], v2, s[44:45] offset:336
	global_load_dwordx4 v[56:59], v2, s[46:47] offset:336
	global_load_dwordx4 v[88:91], v2, s[48:49] offset:336
	global_load_dwordx4 v[120:123], v2, s[50:51] offset:336
	s_waitcnt vmcnt(28)
	v_fma_f32 v0, v28, v60, v0
	v_fma_f32 v1, v92, v124, v1
	v_fma_f32 v0, v29, v61, v0
	v_fma_f32 v1, v93, v125, v1
	v_fma_f32 v0, v30, v62, v0
	v_fma_f32 v1, v94, v126, v1
	v_fma_f32 v0, v31, v63, v0
	v_fma_f32 v1, v95, v127, v1
	global_load_dwordx4 v[28:31], v2, s[44:45] offset:352
	global_load_dwordx4 v[60:63], v2, s[46:47] offset:352
	global_load_dwordx4 v[92:95], v2, s[48:49] offset:352
	global_load_dwordx4 v[124:127], v2, s[50:51] offset:352
	s_waitcnt vmcnt(28)
	v_fma_f32 v0, v32, v64, v0
	v_fma_f32 v1, v96, v128, v1
	v_fma_f32 v0, v33, v65, v0
	v_fma_f32 v1, v97, v129, v1
	v_fma_f32 v0, v34, v66, v0
	v_fma_f32 v1, v98, v130, v1
	v_fma_f32 v0, v35, v67, v0
	v_fma_f32 v1, v99, v131, v1
	global_load_dwordx4 v[32:35], v2, s[44:45] offset:368
	global_load_dwordx4 v[64:67], v2, s[46:47] offset:368
	global_load_dwordx4 v[96:99], v2, s[48:49] offset:368
	global_load_dwordx4 v[128:131], v2, s[50:51] offset:368
	s_waitcnt vmcnt(28)
	v_fma_f32 v0, v4, v36, v0
	v_fma_f32 v1, v68, v100, v1
	v_fma_f32 v0, v5, v37, v0
	v_fma_f32 v1, v69, v101, v1
	v_fma_f32 v0, v6, v38, v0
	v_fma_f32 v1, v70, v102, v1
	v_fma_f32 v0, v7, v39, v0
	v_fma_f32 v1, v71, v103, v1
	global_load_dwordx4 v[4:7], v2, s[44:45] offset:384
	global_load_dwordx4 v[36:39], v2, s[46:47] offset:384
	global_load_dwordx4 v[68:71], v2, s[48:49] offset:384
	global_load_dwordx4 v[100:103], v2, s[50:51] offset:384
	s_waitcnt vmcnt(28)
	v_fma_f32 v0, v8, v40, v0
	v_fma_f32 v1, v72, v104, v1
	v_fma_f32 v0, v9, v41, v0
	v_fma_f32 v1, v73, v105, v1
	v_fma_f32 v0, v10, v42, v0
	v_fma_f32 v1, v74, v106, v1
	v_fma_f32 v0, v11, v43, v0
	v_fma_f32 v1, v75, v107, v1
	global_load_dwordx4 v[8:11], v2, s[44:45] offset:400
	global_load_dwordx4 v[40:43], v2, s[46:47] offset:400
	global_load_dwordx4 v[72:75], v2, s[48:49] offset:400
	global_load_dwordx4 v[104:107], v2, s[50:51] offset:400
	s_waitcnt vmcnt(28)
	v_fma_f32 v0, v12, v44, v0
	v_fma_f32 v1, v76, v108, v1
	v_fma_f32 v0, v13, v45, v0
	v_fma_f32 v1, v77, v109, v1
	v_fma_f32 v0, v14, v46, v0
	v_fma_f32 v1, v78, v110, v1
	v_fma_f32 v0, v15, v47, v0
	v_fma_f32 v1, v79, v111, v1
	global_load_dwordx4 v[12:15], v2, s[44:45] offset:416
	global_load_dwordx4 v[44:47], v2, s[46:47] offset:416
	global_load_dwordx4 v[76:79], v2, s[48:49] offset:416
	global_load_dwordx4 v[108:111], v2, s[50:51] offset:416
	s_waitcnt vmcnt(28)
	v_fma_f32 v0, v16, v48, v0
	v_fma_f32 v1, v80, v112, v1
	v_fma_f32 v0, v17, v49, v0
	v_fma_f32 v1, v81, v113, v1
	v_fma_f32 v0, v18, v50, v0
	v_fma_f32 v1, v82, v114, v1
	v_fma_f32 v0, v19, v51, v0
	v_fma_f32 v1, v83, v115, v1
	global_load_dwordx4 v[16:19], v2, s[44:45] offset:432
	global_load_dwordx4 v[48:51], v2, s[46:47] offset:432
	global_load_dwordx4 v[80:83], v2, s[48:49] offset:432
	global_load_dwordx4 v[112:115], v2, s[50:51] offset:432
	s_waitcnt vmcnt(28)
	v_fma_f32 v0, v20, v52, v0
	v_fma_f32 v1, v84, v116, v1
	v_fma_f32 v0, v21, v53, v0
	v_fma_f32 v1, v85, v117, v1
	v_fma_f32 v0, v22, v54, v0
	v_fma_f32 v1, v86, v118, v1
	v_fma_f32 v0, v23, v55, v0
	v_fma_f32 v1, v87, v119, v1
	global_load_dwordx4 v[20:23], v2, s[44:45] offset:448
	global_load_dwordx4 v[52:55], v2, s[46:47] offset:448
	global_load_dwordx4 v[84:87], v2, s[48:49] offset:448
	global_load_dwordx4 v[116:119], v2, s[50:51] offset:448
	s_waitcnt vmcnt(28)
	v_fma_f32 v0, v24, v56, v0
	v_fma_f32 v1, v88, v120, v1
	v_fma_f32 v0, v25, v57, v0
	v_fma_f32 v1, v89, v121, v1
	v_fma_f32 v0, v26, v58, v0
	v_fma_f32 v1, v90, v122, v1
	v_fma_f32 v0, v27, v59, v0
	v_fma_f32 v1, v91, v123, v1
	global_load_dwordx4 v[24:27], v2, s[44:45] offset:464
	global_load_dwordx4 v[56:59], v2, s[46:47] offset:464
	global_load_dwordx4 v[88:91], v2, s[48:49] offset:464
	global_load_dwordx4 v[120:123], v2, s[50:51] offset:464
	s_waitcnt vmcnt(28)
	v_fma_f32 v0, v28, v60, v0
	v_fma_f32 v1, v92, v124, v1
	v_fma_f32 v0, v29, v61, v0
	v_fma_f32 v1, v93, v125, v1
	v_fma_f32 v0, v30, v62, v0
	v_fma_f32 v1, v94, v126, v1
	v_fma_f32 v0, v31, v63, v0
	v_fma_f32 v1, v95, v127, v1
	global_load_dwordx4 v[28:31], v2, s[44:45] offset:480
	global_load_dwordx4 v[60:63], v2, s[46:47] offset:480
	global_load_dwordx4 v[92:95], v2, s[48:49] offset:480
	global_load_dwordx4 v[124:127], v2, s[50:51] offset:480
	s_waitcnt vmcnt(28)
	v_fma_f32 v0, v32, v64, v0
	v_fma_f32 v1, v96, v128, v1
	v_fma_f32 v0, v33, v65, v0
	v_fma_f32 v1, v97, v129, v1
	v_fma_f32 v0, v34, v66, v0
	v_fma_f32 v1, v98, v130, v1
	v_fma_f32 v0, v35, v67, v0
	v_fma_f32 v1, v99, v131, v1
	global_load_dwordx4 v[32:35], v2, s[44:45] offset:496
	global_load_dwordx4 v[64:67], v2, s[46:47] offset:496
	global_load_dwordx4 v[96:99], v2, s[48:49] offset:496
	global_load_dwordx4 v[128:131], v2, s[50:51] offset:496
	s_waitcnt vmcnt(28)
	v_fma_f32 v0, v4, v36, v0
	v_fma_f32 v1, v68, v100, v1
	v_fma_f32 v0, v5, v37, v0
	v_fma_f32 v1, v69, v101, v1
	v_fma_f32 v0, v6, v38, v0
	v_fma_f32 v1, v70, v102, v1
	v_fma_f32 v0, v7, v39, v0
	v_fma_f32 v1, v71, v103, v1
	s_waitcnt vmcnt(24)
	v_fma_f32 v0, v8, v40, v0
	v_fma_f32 v1, v72, v104, v1
	v_fma_f32 v0, v9, v41, v0
	v_fma_f32 v1, v73, v105, v1
	v_fma_f32 v0, v10, v42, v0
	v_fma_f32 v1, v74, v106, v1
	v_fma_f32 v0, v11, v43, v0
	v_fma_f32 v1, v75, v107, v1
	s_waitcnt vmcnt(20)
	v_fma_f32 v0, v12, v44, v0
	v_fma_f32 v1, v76, v108, v1
	v_fma_f32 v0, v13, v45, v0
	v_fma_f32 v1, v77, v109, v1
	v_fma_f32 v0, v14, v46, v0
	v_fma_f32 v1, v78, v110, v1
	v_fma_f32 v0, v15, v47, v0
	v_fma_f32 v1, v79, v111, v1
	s_waitcnt vmcnt(16)
	v_fma_f32 v0, v16, v48, v0
	v_fma_f32 v1, v80, v112, v1
	v_fma_f32 v0, v17, v49, v0
	v_fma_f32 v1, v81, v113, v1
	v_fma_f32 v0, v18, v50, v0
	v_fma_f32 v1, v82, v114, v1
	v_fma_f32 v0, v19, v51, v0
	v_fma_f32 v1, v83, v115, v1
	s_waitcnt vmcnt(12)
	v_fma_f32 v0, v20, v52, v0
	v_fma_f32 v1, v84, v116, v1
	v_fma_f32 v0, v21, v53, v0
	v_fma_f32 v1, v85, v117, v1
	v_fma_f32 v0, v22, v54, v0
	v_fma_f32 v1, v86, v118, v1
	v_fma_f32 v0, v23, v55, v0
	v_fma_f32 v1, v87, v119, v1
	s_waitcnt vmcnt(8)
	v_fma_f32 v0, v24, v56, v0
	v_fma_f32 v1, v88, v120, v1
	v_fma_f32 v0, v25, v57, v0
	v_fma_f32 v1, v89, v121, v1
	v_fma_f32 v0, v26, v58, v0
	v_fma_f32 v1, v90, v122, v1
	v_fma_f32 v0, v27, v59, v0
	v_fma_f32 v1, v91, v123, v1
	s_waitcnt vmcnt(4)
	v_fma_f32 v0, v28, v60, v0
	v_fma_f32 v1, v92, v124, v1
	v_fma_f32 v0, v29, v61, v0
	v_fma_f32 v1, v93, v125, v1
	v_fma_f32 v0, v30, v62, v0
	v_fma_f32 v1, v94, v126, v1
	v_fma_f32 v0, v31, v63, v0
	v_fma_f32 v1, v95, v127, v1
	s_waitcnt vmcnt(0)
	v_fma_f32 v0, v32, v64, v0
	v_fma_f32 v1, v96, v128, v1
	v_fma_f32 v0, v33, v65, v0
	v_fma_f32 v1, v97, v129, v1
	v_fma_f32 v0, v34, v66, v0
	v_fma_f32 v1, v98, v130, v1
	v_fma_f32 v0, v35, v67, v0
	v_fma_f32 v1, v99, v131, v1
	s_movk_i32 s2, 0x100
	v_cmp_gt_i32_e32 vcc, s2, v176
	s_and_saveexec_b64 s[2:3], vcc
	s_cbranch_execz .LBB0_840
	v_readlane_b32 s8, v248, 0
	v_ashrrev_i32_e32 v177, 31, v176
	v_readlane_b32 s9, v248, 1
	v_readlane_b32 s10, v248, 2
	v_readlane_b32 s11, v248, 3
	v_lshl_add_u64 v[2:3], v[176:177], 2, s[8:9]
	global_load_dword v2, v[2:3], off
	v_lshl_add_u32 v3, v176, 2, 0
	v_add_u32_e32 v3, 0x24000, v3
	v_readlane_b32 s12, v248, 4
	v_readlane_b32 s13, v248, 5
	v_readlane_b32 s14, v248, 6
	v_readlane_b32 s15, v248, 7
	s_waitcnt vmcnt(0)
	ds_write_b32 v3, v2

.Latt_nr0_0:
	v_sub_f32_e32 v128, v128, v190
	v_exp_f32_e32 v128, v128
	v_sub_f32_e32 v129, v129, v190
	v_exp_f32_e32 v129, v129
	v_sub_f32_e32 v130, v130, v190
	v_add_f32_e32 v254, 0, v128
	v_exp_f32_e32 v130, v130
	v_sub_f32_e32 v131, v131, v190
	v_add_f32_e32 v254, v129, v254
	v_exp_f32_e32 v131, v131
	v_sub_f32_e32 v132, v132, v190
	v_add_f32_e32 v254, v130, v254
	v_exp_f32_e32 v132, v132
	v_sub_f32_e32 v133, v133, v190
	v_add_f32_e32 v254, v131, v254
	v_exp_f32_e32 v133, v133
	v_sub_f32_e32 v134, v134, v190
	v_add_f32_e32 v254, v132, v254
	v_exp_f32_e32 v134, v134
	v_sub_f32_e32 v135, v135, v190
	v_add_f32_e32 v254, v133, v254
	v_exp_f32_e32 v135, v135
	v_sub_f32_e32 v136, v136, v190
	v_add_f32_e32 v254, v134, v254
	v_exp_f32_e32 v136, v136
	v_sub_f32_e32 v137, v137, v190
	v_add_f32_e32 v254, v135, v254
	v_exp_f32_e32 v137, v137
	v_sub_f32_e32 v138, v138, v190
	v_add_f32_e32 v254, v136, v254
	v_exp_f32_e32 v138, v138
	v_sub_f32_e32 v139, v139, v190
	v_add_f32_e32 v254, v137, v254
	v_exp_f32_e32 v139, v139
	v_sub_f32_e32 v140, v140, v190
	v_add_f32_e32 v254, v138, v254
	v_exp_f32_e32 v140, v140
	v_sub_f32_e32 v141, v141, v190
	v_add_f32_e32 v254, v139, v254
	v_exp_f32_e32 v141, v141
	v_sub_f32_e32 v142, v142, v190
	v_add_f32_e32 v254, v140, v254
	v_exp_f32_e32 v142, v142
	v_sub_f32_e32 v143, v143, v190
	v_add_f32_e32 v254, v141, v254
	v_exp_f32_e32 v143, v143
	v_add_f32_e32 v254, v142, v254
	v_add_f32_e32 v254, v143, v254
	v_cvt_pk_bf16_f32 v242, v128, v129
	v_cvt_pk_bf16_f32 v243, v130, v131
	v_cvt_pk_bf16_f32 v244, v132, v133
	v_cvt_pk_bf16_f32 v245, v134, v135
	v_cvt_pk_bf16_f32 v250, v136, v137
	v_cvt_pk_bf16_f32 v251, v138, v139
	v_cvt_pk_bf16_f32 v252, v140, v141
	v_cvt_pk_bf16_f32 v253, v142, v143
	v_add_f32_e32 v202, v202, v254
	s_nop 1
	s_waitcnt lgkmcnt(7)
	v_mfma_f32_32x32x16_bf16 v[128:143], v[206:209], v[144:147], 0
	s_waitcnt lgkmcnt(6)
	v_mfma_f32_32x32x16_bf16 v[128:143], v[210:213], v[148:151], v[128:143]
	ds_read_b64_tr_b16 v[206:207], v205
	ds_read_b64_tr_b16 v[208:209], v205 offset:4096
	s_waitcnt lgkmcnt(7)
	v_mfma_f32_32x32x16_bf16 v[128:143], v[214:217], v[152:155], v[128:143]
	s_waitcnt lgkmcnt(6)
	v_mfma_f32_32x32x16_bf16 v[128:143], v[222:225], v[156:159], v[128:143]
	ds_read_b64_tr_b16 v[210:211], v218
	ds_read_b64_tr_b16 v[212:213], v218 offset:4096
	s_waitcnt lgkmcnt(7)
	v_mfma_f32_32x32x16_bf16 v[128:143], v[226:229], v[160:163], v[128:143]
	s_waitcnt lgkmcnt(6)
	v_mfma_f32_32x32x16_bf16 v[128:143], v[230:233], v[164:167], v[128:143]
	ds_read_b64_tr_b16 v[214:215], v219
	ds_read_b64_tr_b16 v[216:217], v219 offset:4096
	s_waitcnt lgkmcnt(7)
	v_mfma_f32_32x32x16_bf16 v[128:143], v[234:237], v[168:171], v[128:143]
	s_waitcnt lgkmcnt(6)
	v_mfma_f32_32x32x16_bf16 v[128:143], v[238:241], v[172:175], v[128:143]
	ds_read_b64_tr_b16 v[222:223], v221
	ds_read_b64_tr_b16 v[224:225], v221 offset:4096
	s_waitcnt lgkmcnt(6)
	v_mfma_f32_32x32x16_bf16 v[112:127], v[206:209], v[242:245], v[112:127]
	ds_read_b64_tr_b16 v[226:227], v205 offset:256
	ds_read_b64_tr_b16 v[228:229], v205 offset:4352
	s_waitcnt lgkmcnt(6)
	v_mfma_f32_32x32x16_bf16 v[96:111], v[210:213], v[242:245], v[96:111]
	ds_read_b64_tr_b16 v[230:231], v218 offset:256
	ds_read_b64_tr_b16 v[232:233], v218 offset:4352
	s_waitcnt lgkmcnt(6)
	v_mfma_f32_32x32x16_bf16 v[80:95], v[214:217], v[242:245], v[80:95]
	ds_read_b64_tr_b16 v[234:235], v219 offset:256
	ds_read_b64_tr_b16 v[236:237], v219 offset:4352
	v_max3_f32 v246, v128, v129, v130
	v_max3_f32 v247, v131, v132, v133
	v_max3_f32 v246, v246, v134, v135
	v_max3_f32 v247, v247, v136, v137
	v_max3_f32 v246, v246, v138, v139
	v_max3_f32 v247, v247, v140, v141
	s_waitcnt lgkmcnt(6)
	v_mfma_f32_32x32x16_bf16 v[64:79], v[222:225], v[242:245], v[64:79]
	ds_read_b64_tr_b16 v[238:239], v221 offset:256
	ds_read_b64_tr_b16 v[240:241], v221 offset:4352
	v_max3_f32 v246, v246, v142, v143
	v_max_f32_e32 v246, v246, v247
	v_mov_b32_e32 v247, v246
	v_add_f32_e32 v249, 0x41000000, v190
	s_nop 1
	s_waitcnt lgkmcnt(6)
	v_mfma_f32_32x32x16_bf16 v[48:63], v[226:229], v[242:245], v[48:63]
	ds_read_b64_tr_b16 v[206:207], v205 offset:8192
	ds_read_b64_tr_b16 v[208:209], v205 offset:12288
	v_permlane32_swap_b32_e32 v246, v247
	v_max_f32_e32 v246, v246, v247
	v_cmp_gt_f32_e32 vcc, v246, v249
	s_cbranch_vccnz .Latt_rs1_0
	s_waitcnt lgkmcnt(6)
	v_mfma_f32_32x32x16_bf16 v[32:47], v[230:233], v[242:245], v[32:47]
	ds_read_b64_tr_b16 v[210:211], v218 offset:8192
	ds_read_b64_tr_b16 v[212:213], v218 offset:12288
	v_sub_f32_e32 v128, v128, v190
	v_exp_f32_e32 v128, v128
	v_sub_f32_e32 v129, v129, v190
	v_exp_f32_e32 v129, v129
	v_sub_f32_e32 v130, v130, v190
	s_waitcnt lgkmcnt(6)
	v_mfma_f32_32x32x16_bf16 v[16:31], v[234:237], v[242:245], v[16:31]
	ds_read_b64_tr_b16 v[214:215], v219 offset:8192
	ds_read_b64_tr_b16 v[216:217], v219 offset:12288
	v_add_f32_e32 v254, 0, v128
	v_exp_f32_e32 v130, v130
	v_sub_f32_e32 v131, v131, v190
	v_add_f32_e32 v254, v129, v254
	v_exp_f32_e32 v131, v131
	s_waitcnt lgkmcnt(6)
	v_mfma_f32_32x32x16_bf16 v[0:15], v[238:241], v[242:245], v[0:15]
	ds_read_b64_tr_b16 v[222:223], v221 offset:8192
	ds_read_b64_tr_b16 v[224:225], v221 offset:12288
	v_sub_f32_e32 v132, v132, v190
	v_add_f32_e32 v254, v130, v254
	v_exp_f32_e32 v132, v132
	v_sub_f32_e32 v133, v133, v190
	v_add_f32_e32 v254, v131, v254
	s_waitcnt lgkmcnt(6)
	v_mfma_f32_32x32x16_bf16 v[112:127], v[206:209], v[250:253], v[112:127]
	ds_read_b64_tr_b16 v[226:227], v205 offset:8448
	ds_read_b64_tr_b16 v[228:229], v205 offset:12544
	v_exp_f32_e32 v133, v133
	v_sub_f32_e32 v134, v134, v190
	v_add_f32_e32 v254, v132, v254
	v_exp_f32_e32 v134, v134
	v_sub_f32_e32 v135, v135, v190
	s_waitcnt lgkmcnt(6)
	v_mfma_f32_32x32x16_bf16 v[96:111], v[210:213], v[250:253], v[96:111]
	ds_read_b64_tr_b16 v[230:231], v218 offset:8448
	ds_read_b64_tr_b16 v[232:233], v218 offset:12544
	v_add_f32_e32 v254, v133, v254
	v_exp_f32_e32 v135, v135
	v_sub_f32_e32 v136, v136, v190
	v_add_f32_e32 v254, v134, v254
	s_waitcnt lgkmcnt(6)
	v_mfma_f32_32x32x16_bf16 v[80:95], v[214:217], v[250:253], v[80:95]
	ds_read_b64_tr_b16 v[234:235], v219 offset:8448
	ds_read_b64_tr_b16 v[236:237], v219 offset:12544
	v_exp_f32_e32 v136, v136
	v_sub_f32_e32 v137, v137, v190
	v_add_f32_e32 v254, v135, v254
	v_exp_f32_e32 v137, v137
	s_waitcnt lgkmcnt(6)
	v_mfma_f32_32x32x16_bf16 v[64:79], v[222:225], v[250:253], v[64:79]
	ds_read_b64_tr_b16 v[238:239], v221 offset:8448
	ds_read_b64_tr_b16 v[240:241], v221 offset:12544
	v_sub_f32_e32 v138, v138, v190
	v_add_f32_e32 v254, v136, v254
	v_exp_f32_e32 v138, v138
	v_sub_f32_e32 v139, v139, v190
	s_waitcnt lgkmcnt(6)
	v_mfma_f32_32x32x16_bf16 v[48:63], v[226:229], v[250:253], v[48:63]
	ds_read_b64_tr_b16 v[206:207], v205 offset:16384
	ds_read_b64_tr_b16 v[208:209], v205 offset:20480
	v_add_f32_e32 v254, v137, v254
	v_exp_f32_e32 v139, v139
	v_sub_f32_e32 v140, v140, v190
	v_add_f32_e32 v254, v138, v254
	s_waitcnt lgkmcnt(6)
	v_mfma_f32_32x32x16_bf16 v[32:47], v[230:233], v[250:253], v[32:47]
	ds_read_b64_tr_b16 v[210:211], v218 offset:16384
	ds_read_b64_tr_b16 v[212:213], v218 offset:20480
	v_exp_f32_e32 v140, v140
	v_sub_f32_e32 v141, v141, v190
	v_add_f32_e32 v254, v139, v254
	v_exp_f32_e32 v141, v141
	s_waitcnt lgkmcnt(6)
	v_mfma_f32_32x32x16_bf16 v[16:31], v[234:237], v[250:253], v[16:31]
	ds_read_b64_tr_b16 v[214:215], v219 offset:16384
	ds_read_b64_tr_b16 v[216:217], v219 offset:20480
	v_sub_f32_e32 v142, v142, v190
	v_add_f32_e32 v254, v140, v254
	v_exp_f32_e32 v142, v142
	v_sub_f32_e32 v143, v143, v190
	s_waitcnt lgkmcnt(6)
	v_mfma_f32_32x32x16_bf16 v[0:15], v[238:241], v[250:253], v[0:15]
	ds_read_b64_tr_b16 v[222:223], v221 offset:16384
	ds_read_b64_tr_b16 v[224:225], v221 offset:20480
	v_add_f32_e32 v254, v141, v254
	v_exp_f32_e32 v143, v143
	v_add_f32_e32 v254, v142, v254
	v_add_f32_e32 v254, v143, v254
	v_cvt_pk_bf16_f32 v242, v128, v129
	v_cvt_pk_bf16_f32 v243, v130, v131
	v_cvt_pk_bf16_f32 v244, v132, v133
	v_cvt_pk_bf16_f32 v245, v134, v135
	v_cvt_pk_bf16_f32 v250, v136, v137
	v_cvt_pk_bf16_f32 v251, v138, v139
	v_cvt_pk_bf16_f32 v252, v140, v141
	v_cvt_pk_bf16_f32 v253, v142, v143
	v_add_f32_e32 v202, v202, v254
	s_nop 1
.Latt_pv1_0:
	s_waitcnt lgkmcnt(6)
	v_mfma_f32_32x32x16_bf16 v[112:127], v[206:209], v[242:245], v[112:127]
	ds_read_b64_tr_b16 v[226:227], v205 offset:16640
	ds_read_b64_tr_b16 v[228:229], v205 offset:20736
	s_waitcnt lgkmcnt(6)
	v_mfma_f32_32x32x16_bf16 v[96:111], v[210:213], v[242:245], v[96:111]
	ds_read_b64_tr_b16 v[230:231], v218 offset:16640
	ds_read_b64_tr_b16 v[232:233], v218 offset:20736
	s_cmp_lg_u64 s[18:19], 0
	s_cbranch_scc1 .Latt_nd0_0
	s_sub_i32 s100, s88, 1
	s_cmp_eq_u32 s88, 0
	s_cselect_b32 s100, 2, s100
	s_lshl_b32 s101, s100, 14
	s_add_i32 m0, s85, s101
	s_nop 0
	global_load_lds_dwordx4 v178, s[14:15]
.Latt_nd0_0:
	s_waitcnt lgkmcnt(6)
	v_mfma_f32_32x32x16_bf16 v[80:95], v[214:217], v[242:245], v[80:95]
	ds_read_b64_tr_b16 v[234:235], v219 offset:16640
	ds_read_b64_tr_b16 v[236:237], v219 offset:20736
	s_waitcnt lgkmcnt(6)
	v_mfma_f32_32x32x16_bf16 v[64:79], v[222:225], v[242:245], v[64:79]
	ds_read_b64_tr_b16 v[238:239], v221 offset:16640
	ds_read_b64_tr_b16 v[240:241], v221 offset:20736
	s_cmp_lg_u64 s[18:19], 0
	s_cbranch_scc1 .Latt_nd1_0
	s_add_i32 m0, m0, 0x400
	s_nop 0
	global_load_lds_dwordx4 v180, s[14:15]
.Latt_nd1_0:
	s_waitcnt lgkmcnt(6)
	v_mfma_f32_32x32x16_bf16 v[48:63], v[226:229], v[242:245], v[48:63]
	ds_read_b64_tr_b16 v[206:207], v205 offset:24576
	ds_read_b64_tr_b16 v[208:209], v205 offset:28672
	s_waitcnt lgkmcnt(6)
	v_mfma_f32_32x32x16_bf16 v[32:47], v[230:233], v[242:245], v[32:47]
	ds_read_b64_tr_b16 v[210:211], v218 offset:24576
	ds_read_b64_tr_b16 v[212:213], v218 offset:28672
	s_cmp_lg_u64 s[18:19], 0
	s_cbranch_scc1 .Latt_nd2_0
	s_lshl_b32 s101, s100, 15
	s_add_i32 m0, s86, s101
	s_add_u32 s100, s14, 0x1000
	s_addc_u32 s101, s15, 0
	global_load_lds_dwordx4 v182, s[100:101]
.Latt_nd2_0:
	s_waitcnt lgkmcnt(6)
	v_mfma_f32_32x32x16_bf16 v[16:31], v[234:237], v[242:245], v[16:31]
	ds_read_b64_tr_b16 v[214:215], v219 offset:24576
	ds_read_b64_tr_b16 v[216:217], v219 offset:28672
	s_waitcnt lgkmcnt(6)
	v_mfma_f32_32x32x16_bf16 v[0:15], v[238:241], v[242:245], v[0:15]
	ds_read_b64_tr_b16 v[222:223], v221 offset:24576
	ds_read_b64_tr_b16 v[224:225], v221 offset:28672
	s_cmp_lg_u64 s[18:19], 0
	s_cbranch_scc1 .Latt_nd3_0
	s_add_i32 m0, m0, 0x400
	s_nop 0
	global_load_lds_dwordx4 v184, s[100:101]
.Latt_nd3_0:
	s_waitcnt lgkmcnt(6)
	v_mfma_f32_32x32x16_bf16 v[112:127], v[206:209], v[250:253], v[112:127]
	ds_read_b64_tr_b16 v[226:227], v205 offset:24832
	ds_read_b64_tr_b16 v[228:229], v205 offset:28928
	s_waitcnt lgkmcnt(6)
	v_mfma_f32_32x32x16_bf16 v[96:111], v[210:213], v[250:253], v[96:111]
	ds_read_b64_tr_b16 v[230:231], v218 offset:24832
	ds_read_b64_tr_b16 v[232:233], v218 offset:28928
	s_cmp_lg_u64 s[18:19], 0
	s_cbranch_scc1 .Latt_nd4_0
	s_add_i32 m0, m0, 0x400
	s_nop 0
	global_load_lds_dwordx4 v186, s[100:101]
.Latt_nd4_0:
	s_waitcnt lgkmcnt(6)
	v_mfma_f32_32x32x16_bf16 v[80:95], v[214:217], v[250:253], v[80:95]
	ds_read_b64_tr_b16 v[234:235], v219 offset:24832
	ds_read_b64_tr_b16 v[236:237], v219 offset:28928
	s_waitcnt lgkmcnt(6)
	v_mfma_f32_32x32x16_bf16 v[64:79], v[222:225], v[250:253], v[64:79]
	ds_read_b64_tr_b16 v[238:239], v221 offset:24832
	ds_read_b64_tr_b16 v[240:241], v221 offset:28928
	s_cmp_lg_u64 s[18:19], 0
	s_cbranch_scc1 .Latt_nd5_0
	s_add_i32 m0, m0, 0x400
	s_nop 0
	global_load_lds_dwordx4 v188, s[100:101]

.Latt_rs1_0:
	s_waitcnt lgkmcnt(6)
	v_mfma_f32_32x32x16_bf16 v[32:47], v[230:233], v[242:245], v[32:47]
	ds_read_b64_tr_b16 v[210:211], v218 offset:8192
	ds_read_b64_tr_b16 v[212:213], v218 offset:12288
	s_waitcnt lgkmcnt(6)
	v_mfma_f32_32x32x16_bf16 v[16:31], v[234:237], v[242:245], v[16:31]
	ds_read_b64_tr_b16 v[214:215], v219 offset:8192
	ds_read_b64_tr_b16 v[216:217], v219 offset:12288
	s_waitcnt lgkmcnt(6)
	v_mfma_f32_32x32x16_bf16 v[0:15], v[238:241], v[242:245], v[0:15]
	ds_read_b64_tr_b16 v[222:223], v221 offset:8192
	ds_read_b64_tr_b16 v[224:225], v221 offset:12288
	s_waitcnt lgkmcnt(6)
	v_mfma_f32_32x32x16_bf16 v[112:127], v[206:209], v[250:253], v[112:127]
	ds_read_b64_tr_b16 v[226:227], v205 offset:8448
	ds_read_b64_tr_b16 v[228:229], v205 offset:12544
	s_waitcnt lgkmcnt(6)
	v_mfma_f32_32x32x16_bf16 v[96:111], v[210:213], v[250:253], v[96:111]
	ds_read_b64_tr_b16 v[230:231], v218 offset:8448
	ds_read_b64_tr_b16 v[232:233], v218 offset:12544
	s_waitcnt lgkmcnt(6)
	v_mfma_f32_32x32x16_bf16 v[80:95], v[214:217], v[250:253], v[80:95]
	ds_read_b64_tr_b16 v[234:235], v219 offset:8448
	ds_read_b64_tr_b16 v[236:237], v219 offset:12544
	s_waitcnt lgkmcnt(6)
	v_mfma_f32_32x32x16_bf16 v[64:79], v[222:225], v[250:253], v[64:79]
	ds_read_b64_tr_b16 v[238:239], v221 offset:8448
	ds_read_b64_tr_b16 v[240:241], v221 offset:12544
	s_waitcnt lgkmcnt(6)
	v_mfma_f32_32x32x16_bf16 v[48:63], v[226:229], v[250:253], v[48:63]
	ds_read_b64_tr_b16 v[206:207], v205 offset:16384
	ds_read_b64_tr_b16 v[208:209], v205 offset:20480
	s_waitcnt lgkmcnt(6)
	v_mfma_f32_32x32x16_bf16 v[32:47], v[230:233], v[250:253], v[32:47]
	ds_read_b64_tr_b16 v[210:211], v218 offset:16384
	ds_read_b64_tr_b16 v[212:213], v218 offset:20480
	s_waitcnt lgkmcnt(6)
	v_mfma_f32_32x32x16_bf16 v[16:31], v[234:237], v[250:253], v[16:31]
	ds_read_b64_tr_b16 v[214:215], v219 offset:16384
	ds_read_b64_tr_b16 v[216:217], v219 offset:20480
	s_waitcnt lgkmcnt(6)
	v_mfma_f32_32x32x16_bf16 v[0:15], v[238:241], v[250:253], v[0:15]
	ds_read_b64_tr_b16 v[222:223], v221 offset:16384
	ds_read_b64_tr_b16 v[224:225], v221 offset:20480
	s_nop 11
	v_max_f32_e32 v246, v190, v246
	v_sub_f32_e32 v190, v190, v246
	v_exp_f32_e32 v190, v190
	s_nop 0
	v_pk_mul_f32 v[126:127], v[126:127], v[190:191] op_sel_hi:[1,0]
	v_pk_mul_f32 v[124:125], v[124:125], v[190:191] op_sel_hi:[1,0]
	v_pk_mul_f32 v[122:123], v[122:123], v[190:191] op_sel_hi:[1,0]
	v_pk_mul_f32 v[120:121], v[120:121], v[190:191] op_sel_hi:[1,0]
	v_pk_mul_f32 v[118:119], v[118:119], v[190:191] op_sel_hi:[1,0]
	v_pk_mul_f32 v[116:117], v[116:117], v[190:191] op_sel_hi:[1,0]
	v_pk_mul_f32 v[114:115], v[114:115], v[190:191] op_sel_hi:[1,0]
	v_pk_mul_f32 v[112:113], v[112:113], v[190:191] op_sel_hi:[1,0]
	v_pk_mul_f32 v[110:111], v[110:111], v[190:191] op_sel_hi:[1,0]
	v_pk_mul_f32 v[108:109], v[108:109], v[190:191] op_sel_hi:[1,0]
	v_pk_mul_f32 v[106:107], v[106:107], v[190:191] op_sel_hi:[1,0]
	v_pk_mul_f32 v[104:105], v[104:105], v[190:191] op_sel_hi:[1,0]
	v_pk_mul_f32 v[102:103], v[102:103], v[190:191] op_sel_hi:[1,0]
	v_pk_mul_f32 v[100:101], v[100:101], v[190:191] op_sel_hi:[1,0]
	v_pk_mul_f32 v[98:99], v[98:99], v[190:191] op_sel_hi:[1,0]
	v_pk_mul_f32 v[96:97], v[96:97], v[190:191] op_sel_hi:[1,0]
	v_pk_mul_f32 v[94:95], v[94:95], v[190:191] op_sel_hi:[1,0]
	v_pk_mul_f32 v[92:93], v[92:93], v[190:191] op_sel_hi:[1,0]
	v_pk_mul_f32 v[90:91], v[90:91], v[190:191] op_sel_hi:[1,0]
	v_pk_mul_f32 v[88:89], v[88:89], v[190:191] op_sel_hi:[1,0]
	v_pk_mul_f32 v[86:87], v[86:87], v[190:191] op_sel_hi:[1,0]
	v_pk_mul_f32 v[84:85], v[84:85], v[190:191] op_sel_hi:[1,0]
	v_pk_mul_f32 v[82:83], v[82:83], v[190:191] op_sel_hi:[1,0]
	v_pk_mul_f32 v[80:81], v[80:81], v[190:191] op_sel_hi:[1,0]
	v_pk_mul_f32 v[78:79], v[78:79], v[190:191] op_sel_hi:[1,0]
	v_pk_mul_f32 v[76:77], v[76:77], v[190:191] op_sel_hi:[1,0]
	v_pk_mul_f32 v[74:75], v[74:75], v[190:191] op_sel_hi:[1,0]
	v_pk_mul_f32 v[72:73], v[72:73], v[190:191] op_sel_hi:[1,0]
	v_pk_mul_f32 v[70:71], v[70:71], v[190:191] op_sel_hi:[1,0]
	v_pk_mul_f32 v[68:69], v[68:69], v[190:191] op_sel_hi:[1,0]
	v_pk_mul_f32 v[66:67], v[66:67], v[190:191] op_sel_hi:[1,0]
	v_pk_mul_f32 v[64:65], v[64:65], v[190:191] op_sel_hi:[1,0]
	v_pk_mul_f32 v[62:63], v[62:63], v[190:191] op_sel_hi:[1,0]
	v_pk_mul_f32 v[60:61], v[60:61], v[190:191] op_sel_hi:[1,0]
	v_pk_mul_f32 v[58:59], v[58:59], v[190:191] op_sel_hi:[1,0]
	v_pk_mul_f32 v[56:57], v[56:57], v[190:191] op_sel_hi:[1,0]
	v_pk_mul_f32 v[54:55], v[54:55], v[190:191] op_sel_hi:[1,0]
	v_pk_mul_f32 v[52:53], v[52:53], v[190:191] op_sel_hi:[1,0]
	v_pk_mul_f32 v[50:51], v[50:51], v[190:191] op_sel_hi:[1,0]
	v_pk_mul_f32 v[48:49], v[48:49], v[190:191] op_sel_hi:[1,0]
	v_pk_mul_f32 v[46:47], v[46:47], v[190:191] op_sel_hi:[1,0]
	v_pk_mul_f32 v[44:45], v[44:45], v[190:191] op_sel_hi:[1,0]
	v_pk_mul_f32 v[42:43], v[42:43], v[190:191] op_sel_hi:[1,0]
	v_pk_mul_f32 v[40:41], v[40:41], v[190:191] op_sel_hi:[1,0]
	v_pk_mul_f32 v[38:39], v[38:39], v[190:191] op_sel_hi:[1,0]
	v_pk_mul_f32 v[36:37], v[36:37], v[190:191] op_sel_hi:[1,0]
	v_pk_mul_f32 v[34:35], v[34:35], v[190:191] op_sel_hi:[1,0]
	v_pk_mul_f32 v[32:33], v[32:33], v[190:191] op_sel_hi:[1,0]
	v_pk_mul_f32 v[30:31], v[30:31], v[190:191] op_sel_hi:[1,0]
	v_pk_mul_f32 v[28:29], v[28:29], v[190:191] op_sel_hi:[1,0]
	v_pk_mul_f32 v[26:27], v[26:27], v[190:191] op_sel_hi:[1,0]
	v_pk_mul_f32 v[24:25], v[24:25], v[190:191] op_sel_hi:[1,0]
	v_pk_mul_f32 v[22:23], v[22:23], v[190:191] op_sel_hi:[1,0]
	v_pk_mul_f32 v[20:21], v[20:21], v[190:191] op_sel_hi:[1,0]
	v_pk_mul_f32 v[18:19], v[18:19], v[190:191] op_sel_hi:[1,0]
	v_pk_mul_f32 v[16:17], v[16:17], v[190:191] op_sel_hi:[1,0]
	v_pk_mul_f32 v[14:15], v[14:15], v[190:191] op_sel_hi:[1,0]
	v_pk_mul_f32 v[12:13], v[12:13], v[190:191] op_sel_hi:[1,0]
	v_pk_mul_f32 v[10:11], v[10:11], v[190:191] op_sel_hi:[1,0]
	v_pk_mul_f32 v[8:9], v[8:9], v[190:191] op_sel_hi:[1,0]
	v_pk_mul_f32 v[6:7], v[6:7], v[190:191] op_sel_hi:[1,0]
	v_pk_mul_f32 v[4:5], v[4:5], v[190:191] op_sel_hi:[1,0]
	v_pk_mul_f32 v[2:3], v[2:3], v[190:191] op_sel_hi:[1,0]
	v_pk_mul_f32 v[0:1], v[0:1], v[190:191] op_sel_hi:[1,0]
	v_mul_f32_e32 v202, v202, v190
	v_mov_b32_e32 v190, v246
	v_sub_f32_e32 v128, v128, v190
	v_exp_f32_e32 v128, v128
	v_sub_f32_e32 v129, v129, v190
	v_exp_f32_e32 v129, v129
	v_sub_f32_e32 v130, v130, v190
	v_add_f32_e32 v254, 0, v128
	v_exp_f32_e32 v130, v130
	v_sub_f32_e32 v131, v131, v190
	v_add_f32_e32 v254, v129, v254
	v_exp_f32_e32 v131, v131
	v_sub_f32_e32 v132, v132, v190
	v_add_f32_e32 v254, v130, v254
	v_exp_f32_e32 v132, v132
	v_sub_f32_e32 v133, v133, v190
	v_add_f32_e32 v254, v131, v254
	v_exp_f32_e32 v133, v133
	v_sub_f32_e32 v134, v134, v190
	v_add_f32_e32 v254, v132, v254
	v_exp_f32_e32 v134, v134
	v_sub_f32_e32 v135, v135, v190
	v_add_f32_e32 v254, v133, v254
	v_exp_f32_e32 v135, v135
	v_sub_f32_e32 v136, v136, v190
	v_add_f32_e32 v254, v134, v254
	v_exp_f32_e32 v136, v136
	v_sub_f32_e32 v137, v137, v190
	v_add_f32_e32 v254, v135, v254
	v_exp_f32_e32 v137, v137
	v_sub_f32_e32 v138, v138, v190
	v_add_f32_e32 v254, v136, v254
	v_exp_f32_e32 v138, v138
	v_sub_f32_e32 v139, v139, v190
	v_add_f32_e32 v254, v137, v254
	v_exp_f32_e32 v139, v139
	v_sub_f32_e32 v140, v140, v190
	v_add_f32_e32 v254, v138, v254
	v_exp_f32_e32 v140, v140
	v_sub_f32_e32 v141, v141, v190
	v_add_f32_e32 v254, v139, v254
	v_exp_f32_e32 v141, v141
	v_sub_f32_e32 v142, v142, v190
	v_add_f32_e32 v254, v140, v254
	v_exp_f32_e32 v142, v142
	v_sub_f32_e32 v143, v143, v190
	v_add_f32_e32 v254, v141, v254
	v_exp_f32_e32 v143, v143
	v_add_f32_e32 v254, v142, v254
	v_add_f32_e32 v254, v143, v254
	v_cvt_pk_bf16_f32 v242, v128, v129
	v_cvt_pk_bf16_f32 v243, v130, v131
	v_cvt_pk_bf16_f32 v244, v132, v133
	v_cvt_pk_bf16_f32 v245, v134, v135
	v_cvt_pk_bf16_f32 v250, v136, v137
	v_cvt_pk_bf16_f32 v251, v138, v139
	v_cvt_pk_bf16_f32 v252, v140, v141
	v_cvt_pk_bf16_f32 v253, v142, v143
	v_add_f32_e32 v202, v202, v254
	s_nop 1
	s_branch .Latt_pv1_0

.Latt_nr0_1:
	v_sub_f32_e32 v128, v128, v190
	v_exp_f32_e32 v128, v128
	v_sub_f32_e32 v129, v129, v190
	v_exp_f32_e32 v129, v129
	v_sub_f32_e32 v130, v130, v190
	v_add_f32_e32 v254, 0, v128
	v_exp_f32_e32 v130, v130
	v_sub_f32_e32 v131, v131, v190
	v_add_f32_e32 v254, v129, v254
	v_exp_f32_e32 v131, v131
	v_sub_f32_e32 v132, v132, v190
	v_add_f32_e32 v254, v130, v254
	v_exp_f32_e32 v132, v132
	v_sub_f32_e32 v133, v133, v190
	v_add_f32_e32 v254, v131, v254
	v_exp_f32_e32 v133, v133
	v_sub_f32_e32 v134, v134, v190
	v_add_f32_e32 v254, v132, v254
	v_exp_f32_e32 v134, v134
	v_sub_f32_e32 v135, v135, v190
	v_add_f32_e32 v254, v133, v254
	v_exp_f32_e32 v135, v135
	v_sub_f32_e32 v136, v136, v190
	v_add_f32_e32 v254, v134, v254
	v_exp_f32_e32 v136, v136
	v_sub_f32_e32 v137, v137, v190
	v_add_f32_e32 v254, v135, v254
	v_exp_f32_e32 v137, v137
	v_sub_f32_e32 v138, v138, v190
	v_add_f32_e32 v254, v136, v254
	v_exp_f32_e32 v138, v138
	v_sub_f32_e32 v139, v139, v190
	v_add_f32_e32 v254, v137, v254
	v_exp_f32_e32 v139, v139
	v_sub_f32_e32 v140, v140, v190
	v_add_f32_e32 v254, v138, v254
	v_exp_f32_e32 v140, v140
	v_sub_f32_e32 v141, v141, v190
	v_add_f32_e32 v254, v139, v254
	v_exp_f32_e32 v141, v141
	v_sub_f32_e32 v142, v142, v190
	v_add_f32_e32 v254, v140, v254
	v_exp_f32_e32 v142, v142
	v_sub_f32_e32 v143, v143, v190
	v_add_f32_e32 v254, v141, v254
	v_exp_f32_e32 v143, v143
	v_add_f32_e32 v254, v142, v254
	v_add_f32_e32 v254, v143, v254
	v_cvt_pk_bf16_f32 v242, v128, v129
	v_cvt_pk_bf16_f32 v243, v130, v131
	v_cvt_pk_bf16_f32 v244, v132, v133
	v_cvt_pk_bf16_f32 v245, v134, v135
	v_cvt_pk_bf16_f32 v250, v136, v137
	v_cvt_pk_bf16_f32 v251, v138, v139
	v_cvt_pk_bf16_f32 v252, v140, v141
	v_cvt_pk_bf16_f32 v253, v142, v143
	v_add_f32_e32 v195, v195, v254
	s_nop 1
	s_waitcnt lgkmcnt(7)
	v_mfma_f32_32x32x16_bf16 v[128:143], v[206:209], v[144:147], 0
	s_waitcnt lgkmcnt(6)
	v_mfma_f32_32x32x16_bf16 v[128:143], v[210:213], v[148:151], v[128:143]
	ds_read_b64_tr_b16 v[206:207], v205
	ds_read_b64_tr_b16 v[208:209], v205 offset:4096
	s_waitcnt lgkmcnt(7)
	v_mfma_f32_32x32x16_bf16 v[128:143], v[214:217], v[152:155], v[128:143]
	s_waitcnt lgkmcnt(6)
	v_mfma_f32_32x32x16_bf16 v[128:143], v[222:225], v[156:159], v[128:143]
	ds_read_b64_tr_b16 v[210:211], v218
	ds_read_b64_tr_b16 v[212:213], v218 offset:4096
	s_waitcnt lgkmcnt(7)
	v_mfma_f32_32x32x16_bf16 v[128:143], v[226:229], v[160:163], v[128:143]
	s_waitcnt lgkmcnt(6)
	v_mfma_f32_32x32x16_bf16 v[128:143], v[230:233], v[164:167], v[128:143]
	ds_read_b64_tr_b16 v[214:215], v219
	ds_read_b64_tr_b16 v[216:217], v219 offset:4096
	s_waitcnt lgkmcnt(7)
	v_mfma_f32_32x32x16_bf16 v[128:143], v[234:237], v[168:171], v[128:143]
	s_waitcnt lgkmcnt(6)
	v_mfma_f32_32x32x16_bf16 v[128:143], v[238:241], v[172:175], v[128:143]
	ds_read_b64_tr_b16 v[222:223], v221
	ds_read_b64_tr_b16 v[224:225], v221 offset:4096
	s_waitcnt lgkmcnt(6)
	v_mfma_f32_32x32x16_bf16 v[112:127], v[206:209], v[242:245], v[112:127]
	ds_read_b64_tr_b16 v[226:227], v205 offset:256
	ds_read_b64_tr_b16 v[228:229], v205 offset:4352
	s_waitcnt lgkmcnt(6)
	v_mfma_f32_32x32x16_bf16 v[96:111], v[210:213], v[242:245], v[96:111]
	ds_read_b64_tr_b16 v[230:231], v218 offset:256
	ds_read_b64_tr_b16 v[232:233], v218 offset:4352
	s_waitcnt lgkmcnt(6)
	v_mfma_f32_32x32x16_bf16 v[80:95], v[214:217], v[242:245], v[80:95]
	ds_read_b64_tr_b16 v[234:235], v219 offset:256
	ds_read_b64_tr_b16 v[236:237], v219 offset:4352
	v_max3_f32 v246, v128, v129, v130
	v_max3_f32 v247, v131, v132, v133
	v_max3_f32 v246, v246, v134, v135
	v_max3_f32 v247, v247, v136, v137
	v_max3_f32 v246, v246, v138, v139
	v_max3_f32 v247, v247, v140, v141
	s_waitcnt lgkmcnt(6)
	v_mfma_f32_32x32x16_bf16 v[64:79], v[222:225], v[242:245], v[64:79]
	ds_read_b64_tr_b16 v[238:239], v221 offset:256
	ds_read_b64_tr_b16 v[240:241], v221 offset:4352
	v_max3_f32 v246, v246, v142, v143
	v_max_f32_e32 v246, v246, v247
	v_mov_b32_e32 v247, v246
	v_add_f32_e32 v249, 0x41000000, v190
	s_nop 1
	s_waitcnt lgkmcnt(6)
	v_mfma_f32_32x32x16_bf16 v[48:63], v[226:229], v[242:245], v[48:63]
	ds_read_b64_tr_b16 v[206:207], v205 offset:8192
	ds_read_b64_tr_b16 v[208:209], v205 offset:12288
	v_permlane32_swap_b32_e32 v246, v247
	v_max_f32_e32 v246, v246, v247
	v_cmp_gt_f32_e32 vcc, v246, v249
	s_cbranch_vccnz .Latt_rs1_1
	s_waitcnt lgkmcnt(6)
	v_mfma_f32_32x32x16_bf16 v[32:47], v[230:233], v[242:245], v[32:47]
	ds_read_b64_tr_b16 v[210:211], v218 offset:8192
	ds_read_b64_tr_b16 v[212:213], v218 offset:12288
	v_sub_f32_e32 v128, v128, v190
	v_exp_f32_e32 v128, v128
	v_sub_f32_e32 v129, v129, v190
	v_exp_f32_e32 v129, v129
	v_sub_f32_e32 v130, v130, v190
	s_waitcnt lgkmcnt(6)
	v_mfma_f32_32x32x16_bf16 v[16:31], v[234:237], v[242:245], v[16:31]
	ds_read_b64_tr_b16 v[214:215], v219 offset:8192
	ds_read_b64_tr_b16 v[216:217], v219 offset:12288
	v_add_f32_e32 v254, 0, v128
	v_exp_f32_e32 v130, v130
	v_sub_f32_e32 v131, v131, v190
	v_add_f32_e32 v254, v129, v254
	v_exp_f32_e32 v131, v131
	s_waitcnt lgkmcnt(6)
	v_mfma_f32_32x32x16_bf16 v[0:15], v[238:241], v[242:245], v[0:15]
	ds_read_b64_tr_b16 v[222:223], v221 offset:8192
	ds_read_b64_tr_b16 v[224:225], v221 offset:12288
	v_sub_f32_e32 v132, v132, v190
	v_add_f32_e32 v254, v130, v254
	v_exp_f32_e32 v132, v132
	v_sub_f32_e32 v133, v133, v190
	v_add_f32_e32 v254, v131, v254
	s_waitcnt lgkmcnt(6)
	v_mfma_f32_32x32x16_bf16 v[112:127], v[206:209], v[250:253], v[112:127]
	ds_read_b64_tr_b16 v[226:227], v205 offset:8448
	ds_read_b64_tr_b16 v[228:229], v205 offset:12544
	v_exp_f32_e32 v133, v133
	v_sub_f32_e32 v134, v134, v190
	v_add_f32_e32 v254, v132, v254
	v_exp_f32_e32 v134, v134
	v_sub_f32_e32 v135, v135, v190
	s_waitcnt lgkmcnt(6)
	v_mfma_f32_32x32x16_bf16 v[96:111], v[210:213], v[250:253], v[96:111]
	ds_read_b64_tr_b16 v[230:231], v218 offset:8448
	ds_read_b64_tr_b16 v[232:233], v218 offset:12544
	v_add_f32_e32 v254, v133, v254
	v_exp_f32_e32 v135, v135
	v_sub_f32_e32 v136, v136, v190
	v_add_f32_e32 v254, v134, v254
	s_waitcnt lgkmcnt(6)
	v_mfma_f32_32x32x16_bf16 v[80:95], v[214:217], v[250:253], v[80:95]
	ds_read_b64_tr_b16 v[234:235], v219 offset:8448
	ds_read_b64_tr_b16 v[236:237], v219 offset:12544
	v_exp_f32_e32 v136, v136
	v_sub_f32_e32 v137, v137, v190
	v_add_f32_e32 v254, v135, v254
	v_exp_f32_e32 v137, v137
	s_waitcnt lgkmcnt(6)
	v_mfma_f32_32x32x16_bf16 v[64:79], v[222:225], v[250:253], v[64:79]
	ds_read_b64_tr_b16 v[238:239], v221 offset:8448
	ds_read_b64_tr_b16 v[240:241], v221 offset:12544
	v_sub_f32_e32 v138, v138, v190
	v_add_f32_e32 v254, v136, v254
	v_exp_f32_e32 v138, v138
	v_sub_f32_e32 v139, v139, v190
	s_waitcnt lgkmcnt(6)
	v_mfma_f32_32x32x16_bf16 v[48:63], v[226:229], v[250:253], v[48:63]
	ds_read_b64_tr_b16 v[206:207], v205 offset:16384
	ds_read_b64_tr_b16 v[208:209], v205 offset:20480
	v_add_f32_e32 v254, v137, v254
	v_exp_f32_e32 v139, v139
	v_sub_f32_e32 v140, v140, v190
	v_add_f32_e32 v254, v138, v254
	s_waitcnt lgkmcnt(6)
	v_mfma_f32_32x32x16_bf16 v[32:47], v[230:233], v[250:253], v[32:47]
	ds_read_b64_tr_b16 v[210:211], v218 offset:16384
	ds_read_b64_tr_b16 v[212:213], v218 offset:20480
	v_exp_f32_e32 v140, v140
	v_sub_f32_e32 v141, v141, v190
	v_add_f32_e32 v254, v139, v254
	v_exp_f32_e32 v141, v141
	s_waitcnt lgkmcnt(6)
	v_mfma_f32_32x32x16_bf16 v[16:31], v[234:237], v[250:253], v[16:31]
	ds_read_b64_tr_b16 v[214:215], v219 offset:16384
	ds_read_b64_tr_b16 v[216:217], v219 offset:20480
	v_sub_f32_e32 v142, v142, v190
	v_add_f32_e32 v254, v140, v254
	v_exp_f32_e32 v142, v142
	v_sub_f32_e32 v143, v143, v190
	s_waitcnt lgkmcnt(6)
	v_mfma_f32_32x32x16_bf16 v[0:15], v[238:241], v[250:253], v[0:15]
	ds_read_b64_tr_b16 v[222:223], v221 offset:16384
	ds_read_b64_tr_b16 v[224:225], v221 offset:20480
	v_add_f32_e32 v254, v141, v254
	v_exp_f32_e32 v143, v143
	v_add_f32_e32 v254, v142, v254
	v_add_f32_e32 v254, v143, v254
	v_cvt_pk_bf16_f32 v242, v128, v129
	v_cvt_pk_bf16_f32 v243, v130, v131
	v_cvt_pk_bf16_f32 v244, v132, v133
	v_cvt_pk_bf16_f32 v245, v134, v135
	v_cvt_pk_bf16_f32 v250, v136, v137
	v_cvt_pk_bf16_f32 v251, v138, v139
	v_cvt_pk_bf16_f32 v252, v140, v141
	v_cvt_pk_bf16_f32 v253, v142, v143
	v_add_f32_e32 v195, v195, v254
	s_nop 1
.Latt_pv1_1:
	s_waitcnt lgkmcnt(6)
	v_mfma_f32_32x32x16_bf16 v[112:127], v[206:209], v[242:245], v[112:127]
	ds_read_b64_tr_b16 v[226:227], v205 offset:16640
	ds_read_b64_tr_b16 v[228:229], v205 offset:20736
	s_waitcnt lgkmcnt(6)
	v_mfma_f32_32x32x16_bf16 v[96:111], v[210:213], v[242:245], v[96:111]
	ds_read_b64_tr_b16 v[230:231], v218 offset:16640
	ds_read_b64_tr_b16 v[232:233], v218 offset:20736
	s_cmp_lg_u64 s[18:19], 0
	s_cbranch_scc1 .Latt_nd0_1
	s_sub_i32 s100, s33, 1
	s_cmp_eq_u32 s33, 0
	s_cselect_b32 s100, 2, s100
	s_lshl_b32 s101, s100, 14
	s_add_i32 m0, s85, s101
	s_nop 0
	global_load_lds_dwordx4 v178, s[12:13]
.Latt_nd0_1:
	s_waitcnt lgkmcnt(6)
	v_mfma_f32_32x32x16_bf16 v[80:95], v[214:217], v[242:245], v[80:95]
	ds_read_b64_tr_b16 v[234:235], v219 offset:16640
	ds_read_b64_tr_b16 v[236:237], v219 offset:20736
	s_waitcnt lgkmcnt(6)
	v_mfma_f32_32x32x16_bf16 v[64:79], v[222:225], v[242:245], v[64:79]
	ds_read_b64_tr_b16 v[238:239], v221 offset:16640
	ds_read_b64_tr_b16 v[240:241], v221 offset:20736
	s_cmp_lg_u64 s[18:19], 0
	s_cbranch_scc1 .Latt_nd1_1
	s_add_i32 m0, m0, 0x400
	s_nop 0
	global_load_lds_dwordx4 v180, s[12:13]
.Latt_nd1_1:
	s_waitcnt lgkmcnt(6)
	v_mfma_f32_32x32x16_bf16 v[48:63], v[226:229], v[242:245], v[48:63]
	ds_read_b64_tr_b16 v[206:207], v205 offset:24576
	ds_read_b64_tr_b16 v[208:209], v205 offset:28672
	s_waitcnt lgkmcnt(6)
	v_mfma_f32_32x32x16_bf16 v[32:47], v[230:233], v[242:245], v[32:47]
	ds_read_b64_tr_b16 v[210:211], v218 offset:24576
	ds_read_b64_tr_b16 v[212:213], v218 offset:28672
	s_cmp_lg_u64 s[18:19], 0
	s_cbranch_scc1 .Latt_nd2_1
	s_lshl_b32 s101, s100, 15
	s_add_i32 m0, s86, s101
	s_add_u32 s100, s12, 0xf00
	s_addc_u32 s101, s13, 0
	global_load_lds_dwordx4 v182, s[100:101]

.Latt_rs1_1:
	s_waitcnt lgkmcnt(6)
	v_mfma_f32_32x32x16_bf16 v[32:47], v[230:233], v[242:245], v[32:47]
	ds_read_b64_tr_b16 v[210:211], v218 offset:8192
	ds_read_b64_tr_b16 v[212:213], v218 offset:12288
	s_waitcnt lgkmcnt(6)
	v_mfma_f32_32x32x16_bf16 v[16:31], v[234:237], v[242:245], v[16:31]
	ds_read_b64_tr_b16 v[214:215], v219 offset:8192
	ds_read_b64_tr_b16 v[216:217], v219 offset:12288
	s_waitcnt lgkmcnt(6)
	v_mfma_f32_32x32x16_bf16 v[0:15], v[238:241], v[242:245], v[0:15]
	ds_read_b64_tr_b16 v[222:223], v221 offset:8192
	ds_read_b64_tr_b16 v[224:225], v221 offset:12288
	s_waitcnt lgkmcnt(6)
	v_mfma_f32_32x32x16_bf16 v[112:127], v[206:209], v[250:253], v[112:127]
	ds_read_b64_tr_b16 v[226:227], v205 offset:8448
	ds_read_b64_tr_b16 v[228:229], v205 offset:12544
	s_waitcnt lgkmcnt(6)
	v_mfma_f32_32x32x16_bf16 v[96:111], v[210:213], v[250:253], v[96:111]
	ds_read_b64_tr_b16 v[230:231], v218 offset:8448
	ds_read_b64_tr_b16 v[232:233], v218 offset:12544
	s_waitcnt lgkmcnt(6)
	v_mfma_f32_32x32x16_bf16 v[80:95], v[214:217], v[250:253], v[80:95]
	ds_read_b64_tr_b16 v[234:235], v219 offset:8448
	ds_read_b64_tr_b16 v[236:237], v219 offset:12544
	s_waitcnt lgkmcnt(6)
	v_mfma_f32_32x32x16_bf16 v[64:79], v[222:225], v[250:253], v[64:79]
	ds_read_b64_tr_b16 v[238:239], v221 offset:8448
	ds_read_b64_tr_b16 v[240:241], v221 offset:12544
	s_waitcnt lgkmcnt(6)
	v_mfma_f32_32x32x16_bf16 v[48:63], v[226:229], v[250:253], v[48:63]
	ds_read_b64_tr_b16 v[206:207], v205 offset:16384
	ds_read_b64_tr_b16 v[208:209], v205 offset:20480
	s_waitcnt lgkmcnt(6)
	v_mfma_f32_32x32x16_bf16 v[32:47], v[230:233], v[250:253], v[32:47]
	ds_read_b64_tr_b16 v[210:211], v218 offset:16384
	ds_read_b64_tr_b16 v[212:213], v218 offset:20480
	s_waitcnt lgkmcnt(6)
	v_mfma_f32_32x32x16_bf16 v[16:31], v[234:237], v[250:253], v[16:31]
	ds_read_b64_tr_b16 v[214:215], v219 offset:16384
	ds_read_b64_tr_b16 v[216:217], v219 offset:20480
	s_waitcnt lgkmcnt(6)
	v_mfma_f32_32x32x16_bf16 v[0:15], v[238:241], v[250:253], v[0:15]
	ds_read_b64_tr_b16 v[222:223], v221 offset:16384
	ds_read_b64_tr_b16 v[224:225], v221 offset:20480
	s_nop 11
	v_max_f32_e32 v246, v190, v246
	v_sub_f32_e32 v190, v190, v246
	v_exp_f32_e32 v190, v190
	s_nop 0
	v_pk_mul_f32 v[126:127], v[126:127], v[190:191] op_sel_hi:[1,0]
	v_pk_mul_f32 v[124:125], v[124:125], v[190:191] op_sel_hi:[1,0]
	v_pk_mul_f32 v[122:123], v[122:123], v[190:191] op_sel_hi:[1,0]
	v_pk_mul_f32 v[120:121], v[120:121], v[190:191] op_sel_hi:[1,0]
	v_pk_mul_f32 v[118:119], v[118:119], v[190:191] op_sel_hi:[1,0]
	v_pk_mul_f32 v[116:117], v[116:117], v[190:191] op_sel_hi:[1,0]
	v_pk_mul_f32 v[114:115], v[114:115], v[190:191] op_sel_hi:[1,0]
	v_pk_mul_f32 v[112:113], v[112:113], v[190:191] op_sel_hi:[1,0]
	v_pk_mul_f32 v[110:111], v[110:111], v[190:191] op_sel_hi:[1,0]
	v_pk_mul_f32 v[108:109], v[108:109], v[190:191] op_sel_hi:[1,0]
	v_pk_mul_f32 v[106:107], v[106:107], v[190:191] op_sel_hi:[1,0]
	v_pk_mul_f32 v[104:105], v[104:105], v[190:191] op_sel_hi:[1,0]
	v_pk_mul_f32 v[102:103], v[102:103], v[190:191] op_sel_hi:[1,0]
	v_pk_mul_f32 v[100:101], v[100:101], v[190:191] op_sel_hi:[1,0]
	v_pk_mul_f32 v[98:99], v[98:99], v[190:191] op_sel_hi:[1,0]
	v_pk_mul_f32 v[96:97], v[96:97], v[190:191] op_sel_hi:[1,0]
	v_pk_mul_f32 v[94:95], v[94:95], v[190:191] op_sel_hi:[1,0]
	v_pk_mul_f32 v[92:93], v[92:93], v[190:191] op_sel_hi:[1,0]
	v_pk_mul_f32 v[90:91], v[90:91], v[190:191] op_sel_hi:[1,0]
	v_pk_mul_f32 v[88:89], v[88:89], v[190:191] op_sel_hi:[1,0]
	v_pk_mul_f32 v[86:87], v[86:87], v[190:191] op_sel_hi:[1,0]
	v_pk_mul_f32 v[84:85], v[84:85], v[190:191] op_sel_hi:[1,0]
	v_pk_mul_f32 v[82:83], v[82:83], v[190:191] op_sel_hi:[1,0]
	v_pk_mul_f32 v[80:81], v[80:81], v[190:191] op_sel_hi:[1,0]
	v_pk_mul_f32 v[78:79], v[78:79], v[190:191] op_sel_hi:[1,0]
	v_pk_mul_f32 v[76:77], v[76:77], v[190:191] op_sel_hi:[1,0]
	v_pk_mul_f32 v[74:75], v[74:75], v[190:191] op_sel_hi:[1,0]
	v_pk_mul_f32 v[72:73], v[72:73], v[190:191] op_sel_hi:[1,0]
	v_pk_mul_f32 v[70:71], v[70:71], v[190:191] op_sel_hi:[1,0]
	v_pk_mul_f32 v[68:69], v[68:69], v[190:191] op_sel_hi:[1,0]
	v_pk_mul_f32 v[66:67], v[66:67], v[190:191] op_sel_hi:[1,0]
	v_pk_mul_f32 v[64:65], v[64:65], v[190:191] op_sel_hi:[1,0]
	v_pk_mul_f32 v[62:63], v[62:63], v[190:191] op_sel_hi:[1,0]
	v_pk_mul_f32 v[60:61], v[60:61], v[190:191] op_sel_hi:[1,0]
	v_pk_mul_f32 v[58:59], v[58:59], v[190:191] op_sel_hi:[1,0]
	v_pk_mul_f32 v[56:57], v[56:57], v[190:191] op_sel_hi:[1,0]
	v_pk_mul_f32 v[54:55], v[54:55], v[190:191] op_sel_hi:[1,0]
	v_pk_mul_f32 v[52:53], v[52:53], v[190:191] op_sel_hi:[1,0]
	v_pk_mul_f32 v[50:51], v[50:51], v[190:191] op_sel_hi:[1,0]
	v_pk_mul_f32 v[48:49], v[48:49], v[190:191] op_sel_hi:[1,0]
	v_pk_mul_f32 v[46:47], v[46:47], v[190:191] op_sel_hi:[1,0]
	v_pk_mul_f32 v[44:45], v[44:45], v[190:191] op_sel_hi:[1,0]
	v_pk_mul_f32 v[42:43], v[42:43], v[190:191] op_sel_hi:[1,0]
	v_pk_mul_f32 v[40:41], v[40:41], v[190:191] op_sel_hi:[1,0]
	v_pk_mul_f32 v[38:39], v[38:39], v[190:191] op_sel_hi:[1,0]
	v_pk_mul_f32 v[36:37], v[36:37], v[190:191] op_sel_hi:[1,0]
	v_pk_mul_f32 v[34:35], v[34:35], v[190:191] op_sel_hi:[1,0]
	v_pk_mul_f32 v[32:33], v[32:33], v[190:191] op_sel_hi:[1,0]
	v_pk_mul_f32 v[30:31], v[30:31], v[190:191] op_sel_hi:[1,0]
	v_pk_mul_f32 v[28:29], v[28:29], v[190:191] op_sel_hi:[1,0]
	v_pk_mul_f32 v[26:27], v[26:27], v[190:191] op_sel_hi:[1,0]
	v_pk_mul_f32 v[24:25], v[24:25], v[190:191] op_sel_hi:[1,0]
	v_pk_mul_f32 v[22:23], v[22:23], v[190:191] op_sel_hi:[1,0]
	v_pk_mul_f32 v[20:21], v[20:21], v[190:191] op_sel_hi:[1,0]
	v_pk_mul_f32 v[18:19], v[18:19], v[190:191] op_sel_hi:[1,0]
	v_pk_mul_f32 v[16:17], v[16:17], v[190:191] op_sel_hi:[1,0]
	v_pk_mul_f32 v[14:15], v[14:15], v[190:191] op_sel_hi:[1,0]
	v_pk_mul_f32 v[12:13], v[12:13], v[190:191] op_sel_hi:[1,0]
	v_pk_mul_f32 v[10:11], v[10:11], v[190:191] op_sel_hi:[1,0]
	v_pk_mul_f32 v[8:9], v[8:9], v[190:191] op_sel_hi:[1,0]
	v_pk_mul_f32 v[6:7], v[6:7], v[190:191] op_sel_hi:[1,0]
	v_pk_mul_f32 v[4:5], v[4:5], v[190:191] op_sel_hi:[1,0]
	v_pk_mul_f32 v[2:3], v[2:3], v[190:191] op_sel_hi:[1,0]
	v_pk_mul_f32 v[0:1], v[0:1], v[190:191] op_sel_hi:[1,0]
	v_mul_f32_e32 v195, v195, v190
	v_mov_b32_e32 v190, v246
	v_sub_f32_e32 v128, v128, v190
	v_exp_f32_e32 v128, v128
	v_sub_f32_e32 v129, v129, v190
	v_exp_f32_e32 v129, v129
	v_sub_f32_e32 v130, v130, v190
	v_add_f32_e32 v254, 0, v128
	v_exp_f32_e32 v130, v130
	v_sub_f32_e32 v131, v131, v190
	v_add_f32_e32 v254, v129, v254
	v_exp_f32_e32 v131, v131
	v_sub_f32_e32 v132, v132, v190
	v_add_f32_e32 v254, v130, v254
	v_exp_f32_e32 v132, v132
	v_sub_f32_e32 v133, v133, v190
	v_add_f32_e32 v254, v131, v254
	v_exp_f32_e32 v133, v133
	v_sub_f32_e32 v134, v134, v190
	v_add_f32_e32 v254, v132, v254
	v_exp_f32_e32 v134, v134
	v_sub_f32_e32 v135, v135, v190
	v_add_f32_e32 v254, v133, v254
	v_exp_f32_e32 v135, v135
	v_sub_f32_e32 v136, v136, v190
	v_add_f32_e32 v254, v134, v254
	v_exp_f32_e32 v136, v136
	v_sub_f32_e32 v137, v137, v190
	v_add_f32_e32 v254, v135, v254
	v_exp_f32_e32 v137, v137
	v_sub_f32_e32 v138, v138, v190
	v_add_f32_e32 v254, v136, v254
	v_exp_f32_e32 v138, v138
	v_sub_f32_e32 v139, v139, v190
	v_add_f32_e32 v254, v137, v254
	v_exp_f32_e32 v139, v139
	v_sub_f32_e32 v140, v140, v190
	v_add_f32_e32 v254, v138, v254
	v_exp_f32_e32 v140, v140
	v_sub_f32_e32 v141, v141, v190
	v_add_f32_e32 v254, v139, v254
	v_exp_f32_e32 v141, v141
	v_sub_f32_e32 v142, v142, v190
	v_add_f32_e32 v254, v140, v254
	v_exp_f32_e32 v142, v142
	v_sub_f32_e32 v143, v143, v190
	v_add_f32_e32 v254, v141, v254
	v_exp_f32_e32 v143, v143
	v_add_f32_e32 v254, v142, v254
	v_add_f32_e32 v254, v143, v254
	v_cvt_pk_bf16_f32 v242, v128, v129
	v_cvt_pk_bf16_f32 v243, v130, v131
	v_cvt_pk_bf16_f32 v244, v132, v133
	v_cvt_pk_bf16_f32 v245, v134, v135
	v_cvt_pk_bf16_f32 v250, v136, v137
	v_cvt_pk_bf16_f32 v251, v138, v139
	v_cvt_pk_bf16_f32 v252, v140, v141
	v_cvt_pk_bf16_f32 v253, v142, v143
	v_add_f32_e32 v195, v195, v254
	s_nop 1
	s_branch .Latt_pv1_1

.Latt_nr0_2:
	v_sub_f32_e32 v128, v128, v190
	v_exp_f32_e32 v128, v128
	v_sub_f32_e32 v129, v129, v190
	v_exp_f32_e32 v129, v129
	v_sub_f32_e32 v130, v130, v190
	v_add_f32_e32 v254, 0, v128
	v_exp_f32_e32 v130, v130
	v_sub_f32_e32 v131, v131, v190
	v_add_f32_e32 v254, v129, v254
	v_exp_f32_e32 v131, v131
	v_sub_f32_e32 v132, v132, v190
	v_add_f32_e32 v254, v130, v254
	v_exp_f32_e32 v132, v132
	v_sub_f32_e32 v133, v133, v190
	v_add_f32_e32 v254, v131, v254
	v_exp_f32_e32 v133, v133
	v_sub_f32_e32 v134, v134, v190
	v_add_f32_e32 v254, v132, v254
	v_exp_f32_e32 v134, v134
	v_sub_f32_e32 v135, v135, v190
	v_add_f32_e32 v254, v133, v254
	v_exp_f32_e32 v135, v135
	v_sub_f32_e32 v136, v136, v190
	v_add_f32_e32 v254, v134, v254
	v_exp_f32_e32 v136, v136
	v_sub_f32_e32 v137, v137, v190
	v_add_f32_e32 v254, v135, v254
	v_exp_f32_e32 v137, v137
	v_sub_f32_e32 v138, v138, v190
	v_add_f32_e32 v254, v136, v254
	v_exp_f32_e32 v138, v138
	v_sub_f32_e32 v139, v139, v190
	v_add_f32_e32 v254, v137, v254
	v_exp_f32_e32 v139, v139
	v_sub_f32_e32 v140, v140, v190
	v_add_f32_e32 v254, v138, v254
	v_exp_f32_e32 v140, v140
	v_sub_f32_e32 v141, v141, v190
	v_add_f32_e32 v254, v139, v254
	v_exp_f32_e32 v141, v141
	v_sub_f32_e32 v142, v142, v190
	v_add_f32_e32 v254, v140, v254
	v_exp_f32_e32 v142, v142
	v_sub_f32_e32 v143, v143, v190
	v_add_f32_e32 v254, v141, v254
	v_exp_f32_e32 v143, v143
	v_add_f32_e32 v254, v142, v254
	v_add_f32_e32 v254, v143, v254
	v_cvt_pk_bf16_f32 v242, v128, v129
	v_cvt_pk_bf16_f32 v243, v130, v131
	v_cvt_pk_bf16_f32 v244, v132, v133
	v_cvt_pk_bf16_f32 v245, v134, v135
	v_cvt_pk_bf16_f32 v250, v136, v137
	v_cvt_pk_bf16_f32 v251, v138, v139
	v_cvt_pk_bf16_f32 v252, v140, v141
	v_cvt_pk_bf16_f32 v253, v142, v143
	v_add_f32_e32 v203, v203, v254
	s_nop 1
	s_waitcnt lgkmcnt(7)
	v_mfma_f32_32x32x16_bf16 v[128:143], v[206:209], v[144:147], 0
	s_waitcnt lgkmcnt(6)
	v_mfma_f32_32x32x16_bf16 v[128:143], v[210:213], v[148:151], v[128:143]
	ds_read_b64_tr_b16 v[206:207], v205
	ds_read_b64_tr_b16 v[208:209], v205 offset:4096
	s_waitcnt lgkmcnt(7)
	v_mfma_f32_32x32x16_bf16 v[128:143], v[214:217], v[152:155], v[128:143]
	s_waitcnt lgkmcnt(6)
	v_mfma_f32_32x32x16_bf16 v[128:143], v[222:225], v[156:159], v[128:143]
	ds_read_b64_tr_b16 v[210:211], v218
	ds_read_b64_tr_b16 v[212:213], v218 offset:4096
	s_waitcnt lgkmcnt(7)
	v_mfma_f32_32x32x16_bf16 v[128:143], v[226:229], v[160:163], v[128:143]
	s_waitcnt lgkmcnt(6)
	v_mfma_f32_32x32x16_bf16 v[128:143], v[230:233], v[164:167], v[128:143]
	ds_read_b64_tr_b16 v[214:215], v219
	ds_read_b64_tr_b16 v[216:217], v219 offset:4096
	s_waitcnt lgkmcnt(7)
	v_mfma_f32_32x32x16_bf16 v[128:143], v[234:237], v[168:171], v[128:143]
	s_waitcnt lgkmcnt(6)
	v_mfma_f32_32x32x16_bf16 v[128:143], v[238:241], v[172:175], v[128:143]
	ds_read_b64_tr_b16 v[222:223], v221
	ds_read_b64_tr_b16 v[224:225], v221 offset:4096
	s_waitcnt lgkmcnt(6)
	v_mfma_f32_32x32x16_bf16 v[112:127], v[206:209], v[242:245], v[112:127]
	ds_read_b64_tr_b16 v[226:227], v205 offset:256
	ds_read_b64_tr_b16 v[228:229], v205 offset:4352
	s_waitcnt lgkmcnt(6)
	v_mfma_f32_32x32x16_bf16 v[96:111], v[210:213], v[242:245], v[96:111]
	ds_read_b64_tr_b16 v[230:231], v218 offset:256
	ds_read_b64_tr_b16 v[232:233], v218 offset:4352
	s_waitcnt lgkmcnt(6)
	v_mfma_f32_32x32x16_bf16 v[80:95], v[214:217], v[242:245], v[80:95]
	ds_read_b64_tr_b16 v[234:235], v219 offset:256
	ds_read_b64_tr_b16 v[236:237], v219 offset:4352
	v_max3_f32 v246, v128, v129, v130
	v_max3_f32 v247, v131, v132, v133
	v_max3_f32 v246, v246, v134, v135
	v_max3_f32 v247, v247, v136, v137
	v_max3_f32 v246, v246, v138, v139
	v_max3_f32 v247, v247, v140, v141
	s_waitcnt lgkmcnt(6)
	v_mfma_f32_32x32x16_bf16 v[64:79], v[222:225], v[242:245], v[64:79]
	ds_read_b64_tr_b16 v[238:239], v221 offset:256
	ds_read_b64_tr_b16 v[240:241], v221 offset:4352
	v_max3_f32 v246, v246, v142, v143
	v_max_f32_e32 v246, v246, v247
	v_mov_b32_e32 v247, v246
	v_add_f32_e32 v249, 0x41000000, v190
	s_nop 1
	s_waitcnt lgkmcnt(6)
	v_mfma_f32_32x32x16_bf16 v[48:63], v[226:229], v[242:245], v[48:63]
	ds_read_b64_tr_b16 v[206:207], v205 offset:8192
	ds_read_b64_tr_b16 v[208:209], v205 offset:12288
	v_permlane32_swap_b32_e32 v246, v247
	v_max_f32_e32 v246, v246, v247
	v_cmp_gt_f32_e32 vcc, v246, v249
	s_cbranch_vccnz .Latt_rs1_2
	s_waitcnt lgkmcnt(6)
	v_mfma_f32_32x32x16_bf16 v[32:47], v[230:233], v[242:245], v[32:47]
	ds_read_b64_tr_b16 v[210:211], v218 offset:8192
	ds_read_b64_tr_b16 v[212:213], v218 offset:12288
	v_sub_f32_e32 v128, v128, v190
	v_exp_f32_e32 v128, v128
	v_sub_f32_e32 v129, v129, v190
	v_exp_f32_e32 v129, v129
	v_sub_f32_e32 v130, v130, v190
	s_waitcnt lgkmcnt(6)
	v_mfma_f32_32x32x16_bf16 v[16:31], v[234:237], v[242:245], v[16:31]
	ds_read_b64_tr_b16 v[214:215], v219 offset:8192
	ds_read_b64_tr_b16 v[216:217], v219 offset:12288
	v_add_f32_e32 v254, 0, v128
	v_exp_f32_e32 v130, v130
	v_sub_f32_e32 v131, v131, v190
	v_add_f32_e32 v254, v129, v254
	v_exp_f32_e32 v131, v131
	s_waitcnt lgkmcnt(6)
	v_mfma_f32_32x32x16_bf16 v[0:15], v[238:241], v[242:245], v[0:15]
	ds_read_b64_tr_b16 v[222:223], v221 offset:8192
	ds_read_b64_tr_b16 v[224:225], v221 offset:12288
	v_sub_f32_e32 v132, v132, v190
	v_add_f32_e32 v254, v130, v254
	v_exp_f32_e32 v132, v132
	v_sub_f32_e32 v133, v133, v190
	v_add_f32_e32 v254, v131, v254
	s_waitcnt lgkmcnt(6)
	v_mfma_f32_32x32x16_bf16 v[112:127], v[206:209], v[250:253], v[112:127]
	ds_read_b64_tr_b16 v[226:227], v205 offset:8448
	ds_read_b64_tr_b16 v[228:229], v205 offset:12544
	v_exp_f32_e32 v133, v133
	v_sub_f32_e32 v134, v134, v190
	v_add_f32_e32 v254, v132, v254
	v_exp_f32_e32 v134, v134
	v_sub_f32_e32 v135, v135, v190
	s_waitcnt lgkmcnt(6)
	v_mfma_f32_32x32x16_bf16 v[96:111], v[210:213], v[250:253], v[96:111]
	ds_read_b64_tr_b16 v[230:231], v218 offset:8448
	ds_read_b64_tr_b16 v[232:233], v218 offset:12544
	v_add_f32_e32 v254, v133, v254
	v_exp_f32_e32 v135, v135
	v_sub_f32_e32 v136, v136, v190
	v_add_f32_e32 v254, v134, v254
	s_waitcnt lgkmcnt(6)
	v_mfma_f32_32x32x16_bf16 v[80:95], v[214:217], v[250:253], v[80:95]
	ds_read_b64_tr_b16 v[234:235], v219 offset:8448
	ds_read_b64_tr_b16 v[236:237], v219 offset:12544
	v_exp_f32_e32 v136, v136
	v_sub_f32_e32 v137, v137, v190
	v_add_f32_e32 v254, v135, v254
	v_exp_f32_e32 v137, v137
	s_waitcnt lgkmcnt(6)
	v_mfma_f32_32x32x16_bf16 v[64:79], v[222:225], v[250:253], v[64:79]
	ds_read_b64_tr_b16 v[238:239], v221 offset:8448
	ds_read_b64_tr_b16 v[240:241], v221 offset:12544
	v_sub_f32_e32 v138, v138, v190
	v_add_f32_e32 v254, v136, v254
	v_exp_f32_e32 v138, v138
	v_sub_f32_e32 v139, v139, v190
	s_waitcnt lgkmcnt(6)
	v_mfma_f32_32x32x16_bf16 v[48:63], v[226:229], v[250:253], v[48:63]
	ds_read_b64_tr_b16 v[206:207], v205 offset:16384
	ds_read_b64_tr_b16 v[208:209], v205 offset:20480
	v_add_f32_e32 v254, v137, v254
	v_exp_f32_e32 v139, v139
	v_sub_f32_e32 v140, v140, v190
	v_add_f32_e32 v254, v138, v254
	s_waitcnt lgkmcnt(6)
	v_mfma_f32_32x32x16_bf16 v[32:47], v[230:233], v[250:253], v[32:47]
	ds_read_b64_tr_b16 v[210:211], v218 offset:16384
	ds_read_b64_tr_b16 v[212:213], v218 offset:20480
	v_exp_f32_e32 v140, v140
	v_sub_f32_e32 v141, v141, v190
	v_add_f32_e32 v254, v139, v254
	v_exp_f32_e32 v141, v141
	s_waitcnt lgkmcnt(6)
	v_mfma_f32_32x32x16_bf16 v[16:31], v[234:237], v[250:253], v[16:31]
	ds_read_b64_tr_b16 v[214:215], v219 offset:16384
	ds_read_b64_tr_b16 v[216:217], v219 offset:20480
	v_sub_f32_e32 v142, v142, v190
	v_add_f32_e32 v254, v140, v254
	v_exp_f32_e32 v142, v142
	v_sub_f32_e32 v143, v143, v190
	s_waitcnt lgkmcnt(6)
	v_mfma_f32_32x32x16_bf16 v[0:15], v[238:241], v[250:253], v[0:15]
	ds_read_b64_tr_b16 v[222:223], v221 offset:16384
	ds_read_b64_tr_b16 v[224:225], v221 offset:20480
	v_add_f32_e32 v254, v141, v254
	v_exp_f32_e32 v143, v143
	v_add_f32_e32 v254, v142, v254
	v_add_f32_e32 v254, v143, v254
	v_cvt_pk_bf16_f32 v242, v128, v129
	v_cvt_pk_bf16_f32 v243, v130, v131
	v_cvt_pk_bf16_f32 v244, v132, v133
	v_cvt_pk_bf16_f32 v245, v134, v135
	v_cvt_pk_bf16_f32 v250, v136, v137
	v_cvt_pk_bf16_f32 v251, v138, v139
	v_cvt_pk_bf16_f32 v252, v140, v141
	v_cvt_pk_bf16_f32 v253, v142, v143
	v_add_f32_e32 v203, v203, v254
	s_nop 1
.Latt_pv1_2:
	s_waitcnt lgkmcnt(6)
	v_mfma_f32_32x32x16_bf16 v[112:127], v[206:209], v[242:245], v[112:127]
	ds_read_b64_tr_b16 v[226:227], v205 offset:16640
	ds_read_b64_tr_b16 v[228:229], v205 offset:20736
	s_waitcnt lgkmcnt(6)
	v_mfma_f32_32x32x16_bf16 v[96:111], v[210:213], v[242:245], v[96:111]
	ds_read_b64_tr_b16 v[230:231], v218 offset:16640
	ds_read_b64_tr_b16 v[232:233], v218 offset:20736
	s_cmp_lg_u64 s[12:13], 0
	s_cbranch_scc1 .Latt_nd0_2
	s_sub_i32 s100, s38, 1
	s_cmp_eq_u32 s38, 0
	s_cselect_b32 s100, 2, s100
	s_lshl_b32 s101, s100, 14
	s_add_i32 m0, s40, s101
	s_nop 0
	global_load_lds_dwordx4 v178, s[22:23]
.Latt_nd0_2:
	s_waitcnt lgkmcnt(6)
	v_mfma_f32_32x32x16_bf16 v[80:95], v[214:217], v[242:245], v[80:95]
	ds_read_b64_tr_b16 v[234:235], v219 offset:16640
	ds_read_b64_tr_b16 v[236:237], v219 offset:20736
	s_waitcnt lgkmcnt(6)
	v_mfma_f32_32x32x16_bf16 v[64:79], v[222:225], v[242:245], v[64:79]
	ds_read_b64_tr_b16 v[238:239], v221 offset:16640
	ds_read_b64_tr_b16 v[240:241], v221 offset:20736
	s_cmp_lg_u64 s[12:13], 0
	s_cbranch_scc1 .Latt_nd1_2
	s_add_i32 m0, m0, 0x400
	s_nop 0
	global_load_lds_dwordx4 v180, s[22:23]
.Latt_nd1_2:
	s_waitcnt lgkmcnt(6)
	v_mfma_f32_32x32x16_bf16 v[48:63], v[226:229], v[242:245], v[48:63]
	ds_read_b64_tr_b16 v[206:207], v205 offset:24576
	ds_read_b64_tr_b16 v[208:209], v205 offset:28672
	s_waitcnt lgkmcnt(6)
	v_mfma_f32_32x32x16_bf16 v[32:47], v[230:233], v[242:245], v[32:47]
	ds_read_b64_tr_b16 v[210:211], v218 offset:24576
	ds_read_b64_tr_b16 v[212:213], v218 offset:28672
	s_cmp_lg_u64 s[12:13], 0
	s_cbranch_scc1 .Latt_nd2_2
	s_lshl_b32 s101, s100, 15
	s_add_i32 m0, s41, s101
	s_add_u32 s100, s22, 0x1000
	s_addc_u32 s101, s23, 0
	global_load_lds_dwordx4 v182, s[100:101]
.Latt_nd2_2:
	s_waitcnt lgkmcnt(6)
	v_mfma_f32_32x32x16_bf16 v[16:31], v[234:237], v[242:245], v[16:31]
	ds_read_b64_tr_b16 v[214:215], v219 offset:24576
	ds_read_b64_tr_b16 v[216:217], v219 offset:28672
	s_waitcnt lgkmcnt(6)
	v_mfma_f32_32x32x16_bf16 v[0:15], v[238:241], v[242:245], v[0:15]
	ds_read_b64_tr_b16 v[222:223], v221 offset:24576
	ds_read_b64_tr_b16 v[224:225], v221 offset:28672
	s_cmp_lg_u64 s[12:13], 0
	s_cbranch_scc1 .Latt_nd3_2
	s_add_i32 m0, m0, 0x400
	s_nop 0
	global_load_lds_dwordx4 v184, s[100:101]
.Latt_nd3_2:
	s_waitcnt lgkmcnt(6)
	v_mfma_f32_32x32x16_bf16 v[112:127], v[206:209], v[250:253], v[112:127]
	ds_read_b64_tr_b16 v[226:227], v205 offset:24832
	ds_read_b64_tr_b16 v[228:229], v205 offset:28928
	s_waitcnt lgkmcnt(6)
	v_mfma_f32_32x32x16_bf16 v[96:111], v[210:213], v[250:253], v[96:111]
	ds_read_b64_tr_b16 v[230:231], v218 offset:24832
	ds_read_b64_tr_b16 v[232:233], v218 offset:28928
	s_cmp_lg_u64 s[12:13], 0
	s_cbranch_scc1 .Latt_nd4_2
	s_add_i32 m0, m0, 0x400
	s_nop 0
	global_load_lds_dwordx4 v186, s[100:101]
.Latt_nd4_2:
	s_waitcnt lgkmcnt(6)
	v_mfma_f32_32x32x16_bf16 v[80:95], v[214:217], v[250:253], v[80:95]
	ds_read_b64_tr_b16 v[234:235], v219 offset:24832
	ds_read_b64_tr_b16 v[236:237], v219 offset:28928
	s_waitcnt lgkmcnt(6)
	v_mfma_f32_32x32x16_bf16 v[64:79], v[222:225], v[250:253], v[64:79]
	ds_read_b64_tr_b16 v[238:239], v221 offset:24832
	ds_read_b64_tr_b16 v[240:241], v221 offset:28928
	s_cmp_lg_u64 s[12:13], 0
	s_cbranch_scc1 .Latt_nd5_2
	s_add_i32 m0, m0, 0x400
	s_nop 0
	global_load_lds_dwordx4 v188, s[100:101]

.Latt_rs1_2:
	s_waitcnt lgkmcnt(6)
	v_mfma_f32_32x32x16_bf16 v[32:47], v[230:233], v[242:245], v[32:47]
	ds_read_b64_tr_b16 v[210:211], v218 offset:8192
	ds_read_b64_tr_b16 v[212:213], v218 offset:12288
	s_waitcnt lgkmcnt(6)
	v_mfma_f32_32x32x16_bf16 v[16:31], v[234:237], v[242:245], v[16:31]
	ds_read_b64_tr_b16 v[214:215], v219 offset:8192
	ds_read_b64_tr_b16 v[216:217], v219 offset:12288
	s_waitcnt lgkmcnt(6)
	v_mfma_f32_32x32x16_bf16 v[0:15], v[238:241], v[242:245], v[0:15]
	ds_read_b64_tr_b16 v[222:223], v221 offset:8192
	ds_read_b64_tr_b16 v[224:225], v221 offset:12288
	s_waitcnt lgkmcnt(6)
	v_mfma_f32_32x32x16_bf16 v[112:127], v[206:209], v[250:253], v[112:127]
	ds_read_b64_tr_b16 v[226:227], v205 offset:8448
	ds_read_b64_tr_b16 v[228:229], v205 offset:12544
	s_waitcnt lgkmcnt(6)
	v_mfma_f32_32x32x16_bf16 v[96:111], v[210:213], v[250:253], v[96:111]
	ds_read_b64_tr_b16 v[230:231], v218 offset:8448
	ds_read_b64_tr_b16 v[232:233], v218 offset:12544
	s_waitcnt lgkmcnt(6)
	v_mfma_f32_32x32x16_bf16 v[80:95], v[214:217], v[250:253], v[80:95]
	ds_read_b64_tr_b16 v[234:235], v219 offset:8448
	ds_read_b64_tr_b16 v[236:237], v219 offset:12544
	s_waitcnt lgkmcnt(6)
	v_mfma_f32_32x32x16_bf16 v[64:79], v[222:225], v[250:253], v[64:79]
	ds_read_b64_tr_b16 v[238:239], v221 offset:8448
	ds_read_b64_tr_b16 v[240:241], v221 offset:12544
	s_waitcnt lgkmcnt(6)
	v_mfma_f32_32x32x16_bf16 v[48:63], v[226:229], v[250:253], v[48:63]
	ds_read_b64_tr_b16 v[206:207], v205 offset:16384
	ds_read_b64_tr_b16 v[208:209], v205 offset:20480
	s_waitcnt lgkmcnt(6)
	v_mfma_f32_32x32x16_bf16 v[32:47], v[230:233], v[250:253], v[32:47]
	ds_read_b64_tr_b16 v[210:211], v218 offset:16384
	ds_read_b64_tr_b16 v[212:213], v218 offset:20480
	s_waitcnt lgkmcnt(6)
	v_mfma_f32_32x32x16_bf16 v[16:31], v[234:237], v[250:253], v[16:31]
	ds_read_b64_tr_b16 v[214:215], v219 offset:16384
	ds_read_b64_tr_b16 v[216:217], v219 offset:20480
	s_waitcnt lgkmcnt(6)
	v_mfma_f32_32x32x16_bf16 v[0:15], v[238:241], v[250:253], v[0:15]
	ds_read_b64_tr_b16 v[222:223], v221 offset:16384
	ds_read_b64_tr_b16 v[224:225], v221 offset:20480
	s_nop 11
	v_max_f32_e32 v246, v190, v246
	v_sub_f32_e32 v190, v190, v246
	v_exp_f32_e32 v190, v190
	s_nop 0
	v_pk_mul_f32 v[126:127], v[126:127], v[190:191] op_sel_hi:[1,0]
	v_pk_mul_f32 v[124:125], v[124:125], v[190:191] op_sel_hi:[1,0]
	v_pk_mul_f32 v[122:123], v[122:123], v[190:191] op_sel_hi:[1,0]
	v_pk_mul_f32 v[120:121], v[120:121], v[190:191] op_sel_hi:[1,0]
	v_pk_mul_f32 v[118:119], v[118:119], v[190:191] op_sel_hi:[1,0]
	v_pk_mul_f32 v[116:117], v[116:117], v[190:191] op_sel_hi:[1,0]
	v_pk_mul_f32 v[114:115], v[114:115], v[190:191] op_sel_hi:[1,0]
	v_pk_mul_f32 v[112:113], v[112:113], v[190:191] op_sel_hi:[1,0]
	v_pk_mul_f32 v[110:111], v[110:111], v[190:191] op_sel_hi:[1,0]
	v_pk_mul_f32 v[108:109], v[108:109], v[190:191] op_sel_hi:[1,0]
	v_pk_mul_f32 v[106:107], v[106:107], v[190:191] op_sel_hi:[1,0]
	v_pk_mul_f32 v[104:105], v[104:105], v[190:191] op_sel_hi:[1,0]
	v_pk_mul_f32 v[102:103], v[102:103], v[190:191] op_sel_hi:[1,0]
	v_pk_mul_f32 v[100:101], v[100:101], v[190:191] op_sel_hi:[1,0]
	v_pk_mul_f32 v[98:99], v[98:99], v[190:191] op_sel_hi:[1,0]
	v_pk_mul_f32 v[96:97], v[96:97], v[190:191] op_sel_hi:[1,0]
	v_pk_mul_f32 v[94:95], v[94:95], v[190:191] op_sel_hi:[1,0]
	v_pk_mul_f32 v[92:93], v[92:93], v[190:191] op_sel_hi:[1,0]
	v_pk_mul_f32 v[90:91], v[90:91], v[190:191] op_sel_hi:[1,0]
	v_pk_mul_f32 v[88:89], v[88:89], v[190:191] op_sel_hi:[1,0]
	v_pk_mul_f32 v[86:87], v[86:87], v[190:191] op_sel_hi:[1,0]
	v_pk_mul_f32 v[84:85], v[84:85], v[190:191] op_sel_hi:[1,0]
	v_pk_mul_f32 v[82:83], v[82:83], v[190:191] op_sel_hi:[1,0]
	v_pk_mul_f32 v[80:81], v[80:81], v[190:191] op_sel_hi:[1,0]
	v_pk_mul_f32 v[78:79], v[78:79], v[190:191] op_sel_hi:[1,0]
	v_pk_mul_f32 v[76:77], v[76:77], v[190:191] op_sel_hi:[1,0]
	v_pk_mul_f32 v[74:75], v[74:75], v[190:191] op_sel_hi:[1,0]
	v_pk_mul_f32 v[72:73], v[72:73], v[190:191] op_sel_hi:[1,0]
	v_pk_mul_f32 v[70:71], v[70:71], v[190:191] op_sel_hi:[1,0]
	v_pk_mul_f32 v[68:69], v[68:69], v[190:191] op_sel_hi:[1,0]
	v_pk_mul_f32 v[66:67], v[66:67], v[190:191] op_sel_hi:[1,0]
	v_pk_mul_f32 v[64:65], v[64:65], v[190:191] op_sel_hi:[1,0]
	v_pk_mul_f32 v[62:63], v[62:63], v[190:191] op_sel_hi:[1,0]
	v_pk_mul_f32 v[60:61], v[60:61], v[190:191] op_sel_hi:[1,0]
	v_pk_mul_f32 v[58:59], v[58:59], v[190:191] op_sel_hi:[1,0]
	v_pk_mul_f32 v[56:57], v[56:57], v[190:191] op_sel_hi:[1,0]
	v_pk_mul_f32 v[54:55], v[54:55], v[190:191] op_sel_hi:[1,0]
	v_pk_mul_f32 v[52:53], v[52:53], v[190:191] op_sel_hi:[1,0]
	v_pk_mul_f32 v[50:51], v[50:51], v[190:191] op_sel_hi:[1,0]
	v_pk_mul_f32 v[48:49], v[48:49], v[190:191] op_sel_hi:[1,0]
	v_pk_mul_f32 v[46:47], v[46:47], v[190:191] op_sel_hi:[1,0]
	v_pk_mul_f32 v[44:45], v[44:45], v[190:191] op_sel_hi:[1,0]
	v_pk_mul_f32 v[42:43], v[42:43], v[190:191] op_sel_hi:[1,0]
	v_pk_mul_f32 v[40:41], v[40:41], v[190:191] op_sel_hi:[1,0]
	v_pk_mul_f32 v[38:39], v[38:39], v[190:191] op_sel_hi:[1,0]
	v_pk_mul_f32 v[36:37], v[36:37], v[190:191] op_sel_hi:[1,0]
	v_pk_mul_f32 v[34:35], v[34:35], v[190:191] op_sel_hi:[1,0]
	v_pk_mul_f32 v[32:33], v[32:33], v[190:191] op_sel_hi:[1,0]
	v_pk_mul_f32 v[30:31], v[30:31], v[190:191] op_sel_hi:[1,0]
	v_pk_mul_f32 v[28:29], v[28:29], v[190:191] op_sel_hi:[1,0]
	v_pk_mul_f32 v[26:27], v[26:27], v[190:191] op_sel_hi:[1,0]
	v_pk_mul_f32 v[24:25], v[24:25], v[190:191] op_sel_hi:[1,0]
	v_pk_mul_f32 v[22:23], v[22:23], v[190:191] op_sel_hi:[1,0]
	v_pk_mul_f32 v[20:21], v[20:21], v[190:191] op_sel_hi:[1,0]
	v_pk_mul_f32 v[18:19], v[18:19], v[190:191] op_sel_hi:[1,0]
	v_pk_mul_f32 v[16:17], v[16:17], v[190:191] op_sel_hi:[1,0]
	v_pk_mul_f32 v[14:15], v[14:15], v[190:191] op_sel_hi:[1,0]
	v_pk_mul_f32 v[12:13], v[12:13], v[190:191] op_sel_hi:[1,0]
	v_pk_mul_f32 v[10:11], v[10:11], v[190:191] op_sel_hi:[1,0]
	v_pk_mul_f32 v[8:9], v[8:9], v[190:191] op_sel_hi:[1,0]
	v_pk_mul_f32 v[6:7], v[6:7], v[190:191] op_sel_hi:[1,0]
	v_pk_mul_f32 v[4:5], v[4:5], v[190:191] op_sel_hi:[1,0]
	v_pk_mul_f32 v[2:3], v[2:3], v[190:191] op_sel_hi:[1,0]
	v_pk_mul_f32 v[0:1], v[0:1], v[190:191] op_sel_hi:[1,0]
	v_mul_f32_e32 v203, v203, v190
	v_mov_b32_e32 v190, v246
	v_sub_f32_e32 v128, v128, v190
	v_exp_f32_e32 v128, v128
	v_sub_f32_e32 v129, v129, v190
	v_exp_f32_e32 v129, v129
	v_sub_f32_e32 v130, v130, v190
	v_add_f32_e32 v254, 0, v128
	v_exp_f32_e32 v130, v130
	v_sub_f32_e32 v131, v131, v190
	v_add_f32_e32 v254, v129, v254
	v_exp_f32_e32 v131, v131
	v_sub_f32_e32 v132, v132, v190
	v_add_f32_e32 v254, v130, v254
	v_exp_f32_e32 v132, v132
	v_sub_f32_e32 v133, v133, v190
	v_add_f32_e32 v254, v131, v254
	v_exp_f32_e32 v133, v133
	v_sub_f32_e32 v134, v134, v190
	v_add_f32_e32 v254, v132, v254
	v_exp_f32_e32 v134, v134
	v_sub_f32_e32 v135, v135, v190
	v_add_f32_e32 v254, v133, v254
	v_exp_f32_e32 v135, v135
	v_sub_f32_e32 v136, v136, v190
	v_add_f32_e32 v254, v134, v254
	v_exp_f32_e32 v136, v136
	v_sub_f32_e32 v137, v137, v190
	v_add_f32_e32 v254, v135, v254
	v_exp_f32_e32 v137, v137
	v_sub_f32_e32 v138, v138, v190
	v_add_f32_e32 v254, v136, v254
	v_exp_f32_e32 v138, v138
	v_sub_f32_e32 v139, v139, v190
	v_add_f32_e32 v254, v137, v254
	v_exp_f32_e32 v139, v139
	v_sub_f32_e32 v140, v140, v190
	v_add_f32_e32 v254, v138, v254
	v_exp_f32_e32 v140, v140
	v_sub_f32_e32 v141, v141, v190
	v_add_f32_e32 v254, v139, v254
	v_exp_f32_e32 v141, v141
	v_sub_f32_e32 v142, v142, v190
	v_add_f32_e32 v254, v140, v254
	v_exp_f32_e32 v142, v142
	v_sub_f32_e32 v143, v143, v190
	v_add_f32_e32 v254, v141, v254
	v_exp_f32_e32 v143, v143
	v_add_f32_e32 v254, v142, v254
	v_add_f32_e32 v254, v143, v254
	v_cvt_pk_bf16_f32 v242, v128, v129
	v_cvt_pk_bf16_f32 v243, v130, v131
	v_cvt_pk_bf16_f32 v244, v132, v133
	v_cvt_pk_bf16_f32 v245, v134, v135
	v_cvt_pk_bf16_f32 v250, v136, v137
	v_cvt_pk_bf16_f32 v251, v138, v139
	v_cvt_pk_bf16_f32 v252, v140, v141
	v_cvt_pk_bf16_f32 v253, v142, v143
	v_add_f32_e32 v203, v203, v254
	s_nop 1
	s_branch .Latt_pv1_2

.Latt_pv1_3:
	s_waitcnt lgkmcnt(6)
	v_mfma_f32_32x32x16_bf16 v[112:127], v[206:209], v[242:245], v[112:127]
	ds_read_b64_tr_b16 v[226:227], v205 offset:16640
	ds_read_b64_tr_b16 v[228:229], v205 offset:20736
	s_waitcnt lgkmcnt(6)
	v_mfma_f32_32x32x16_bf16 v[96:111], v[210:213], v[242:245], v[96:111]
	ds_read_b64_tr_b16 v[230:231], v218 offset:16640
	ds_read_b64_tr_b16 v[232:233], v218 offset:20736
	s_cmp_lg_u64 s[8:9], 0
	s_cbranch_scc1 .Latt_nd0_3
	s_sub_i32 s100, s11, 1
	s_cmp_eq_u32 s11, 0
	s_cselect_b32 s100, 2, s100
	s_lshl_b32 s101, s100, 14
	s_add_i32 m0, s40, s101
	s_nop 0
	global_load_lds_dwordx4 v178, s[34:35]
.Latt_nd0_3:
	s_waitcnt lgkmcnt(6)
	v_mfma_f32_32x32x16_bf16 v[80:95], v[214:217], v[242:245], v[80:95]
	ds_read_b64_tr_b16 v[234:235], v219 offset:16640
	ds_read_b64_tr_b16 v[236:237], v219 offset:20736
	s_waitcnt lgkmcnt(6)
	v_mfma_f32_32x32x16_bf16 v[64:79], v[222:225], v[242:245], v[64:79]
	ds_read_b64_tr_b16 v[238:239], v221 offset:16640
	ds_read_b64_tr_b16 v[240:241], v221 offset:20736
	s_cmp_lg_u64 s[8:9], 0
	s_cbranch_scc1 .Latt_nd1_3
	s_add_i32 m0, m0, 0x400
	s_nop 0
	global_load_lds_dwordx4 v180, s[34:35]
.Latt_nd1_3:
	s_waitcnt lgkmcnt(6)
	v_mfma_f32_32x32x16_bf16 v[48:63], v[226:229], v[242:245], v[48:63]
	ds_read_b64_tr_b16 v[206:207], v205 offset:24576
	ds_read_b64_tr_b16 v[208:209], v205 offset:28672
	s_waitcnt lgkmcnt(6)
	v_mfma_f32_32x32x16_bf16 v[32:47], v[230:233], v[242:245], v[32:47]
	ds_read_b64_tr_b16 v[210:211], v218 offset:24576
	ds_read_b64_tr_b16 v[212:213], v218 offset:28672
	s_cmp_lg_u64 s[8:9], 0
	s_cbranch_scc1 .Latt_nd2_3
	s_lshl_b32 s101, s100, 15
	s_add_i32 m0, s41, s101
	s_add_u32 s100, s34, 0xf00
	s_addc_u32 s101, s35, 0
	global_load_lds_dwordx4 v182, s[100:101]
.Latt_nd2_3:
	s_waitcnt lgkmcnt(6)
	v_mfma_f32_32x32x16_bf16 v[16:31], v[234:237], v[242:245], v[16:31]
	ds_read_b64_tr_b16 v[214:215], v219 offset:24576
	ds_read_b64_tr_b16 v[216:217], v219 offset:28672
	s_waitcnt lgkmcnt(6)
	v_mfma_f32_32x32x16_bf16 v[0:15], v[238:241], v[242:245], v[0:15]
	ds_read_b64_tr_b16 v[222:223], v221 offset:24576
	ds_read_b64_tr_b16 v[224:225], v221 offset:28672
	s_cmp_lg_u64 s[8:9], 0
	s_cbranch_scc1 .Latt_nd3_3
	s_add_i32 m0, m0, 0x400
	s_nop 0
	global_load_lds_dwordx4 v184, s[100:101]
.Latt_nd3_3:
	s_waitcnt lgkmcnt(6)
	v_mfma_f32_32x32x16_bf16 v[112:127], v[206:209], v[250:253], v[112:127]
	ds_read_b64_tr_b16 v[226:227], v205 offset:24832
	ds_read_b64_tr_b16 v[228:229], v205 offset:28928
	s_waitcnt lgkmcnt(6)
	v_mfma_f32_32x32x16_bf16 v[96:111], v[210:213], v[250:253], v[96:111]
	ds_read_b64_tr_b16 v[230:231], v218 offset:24832
	ds_read_b64_tr_b16 v[232:233], v218 offset:28928
	s_cmp_lg_u64 s[8:9], 0
	s_cbranch_scc1 .Latt_nd4_3
	s_add_i32 m0, m0, 0x400
	s_nop 0
	global_load_lds_dwordx4 v186, s[100:101]
.Latt_nd4_3:
	s_waitcnt lgkmcnt(6)
	v_mfma_f32_32x32x16_bf16 v[80:95], v[214:217], v[250:253], v[80:95]
	ds_read_b64_tr_b16 v[234:235], v219 offset:24832
	ds_read_b64_tr_b16 v[236:237], v219 offset:28928
	s_waitcnt lgkmcnt(6)
	v_mfma_f32_32x32x16_bf16 v[64:79], v[222:225], v[250:253], v[64:79]
	ds_read_b64_tr_b16 v[238:239], v221 offset:24832
	ds_read_b64_tr_b16 v[240:241], v221 offset:28928
	s_cmp_lg_u64 s[8:9], 0
	s_cbranch_scc1 .Latt_nd5_3
	s_add_i32 m0, m0, 0x400
	s_nop 0
	global_load_lds_dwordx4 v188, s[100:101]

.LBB0_1068:
	s_lshl_b32 s98, s12, 8
	s_add_i32 s98, s98, s68
	v_or_b32_e32 v249, s98, v147
	v_lshlrev_b32_e32 v249, 2, v249
	global_load_dword v240, v249, s[16:17]
	global_load_dword v241, v249, s[16:17] offset:64
	global_load_dword v242, v249, s[16:17] offset:128
	global_load_dword v243, v249, s[16:17] offset:192
	global_load_dword v244, v249, s[16:17] offset:512
	global_load_dword v245, v249, s[16:17] offset:576
	global_load_dword v246, v249, s[16:17] offset:640
	global_load_dword v247, v249, s[16:17] offset:704
	s_ashr_i32 s41, s40, 31
	s_lshl_b64 s[42:43], s[40:41], 20
	s_add_u32 s42, s58, s42
	s_addc_u32 s43, s59, s43
	s_and_b64 s[52:53], s[2:3], exec
	s_cselect_b32 s5, s43, s15
	s_cselect_b32 s13, s42, s14
	s_ashr_i32 s39, s38, 31
	s_lshl_b64 s[52:53], s[38:39], 20
	s_add_u32 s52, s60, s52
	s_addc_u32 s53, s61, s53
	s_and_b64 s[54:55], s[2:3], exec
	s_cselect_b32 s33, s53, s19
	s_cselect_b32 s39, s52, s18
	s_add_u32 s14, s14, 0x80080
	s_addc_u32 s15, s15, 0
	s_add_u32 s41, s18, 0x100
	v_mov_b32_e32 v0, 0
	s_addc_u32 s78, s19, 0
	s_mov_b32 s79, -2
	v_mov_b32_e32 v1, v0
	v_mov_b32_e32 v2, v0
	v_mov_b32_e32 v3, v0
	v_mov_b32_e32 v4, v0
	v_mov_b32_e32 v5, v0
	v_mov_b32_e32 v6, v0
	v_mov_b32_e32 v7, v0
	v_mov_b32_e32 v16, v0
	v_mov_b32_e32 v17, v0
	v_mov_b32_e32 v18, v0
	v_mov_b32_e32 v19, v0
	v_mov_b32_e32 v20, v0
	v_mov_b32_e32 v21, v0
	v_mov_b32_e32 v22, v0
	v_mov_b32_e32 v23, v0
	s_waitcnt vmcnt(0)
	v_mov_b32_e32 v32, v0
	v_mov_b32_e32 v33, v0
	v_mov_b32_e32 v34, v0
	v_mov_b32_e32 v35, v0
	v_mov_b32_e32 v36, v0
	v_mov_b32_e32 v37, v0
	v_mov_b32_e32 v38, v0
	v_mov_b32_e32 v39, v0
	v_mov_b32_e32 v48, v0
	v_mov_b32_e32 v49, v0
	v_mov_b32_e32 v50, v0
	v_mov_b32_e32 v51, v0
	v_mov_b32_e32 v52, v0
	v_mov_b32_e32 v53, v0
	v_mov_b32_e32 v54, v0
	v_mov_b32_e32 v55, v0
	v_mov_b32_e32 v8, v0
	v_mov_b32_e32 v9, v0
	v_mov_b32_e32 v10, v0
	v_mov_b32_e32 v11, v0
	v_mov_b32_e32 v12, v0
	v_mov_b32_e32 v13, v0
	v_mov_b32_e32 v14, v0
	v_mov_b32_e32 v15, v0
	v_mov_b32_e32 v24, v0
	v_mov_b32_e32 v25, v0
	v_mov_b32_e32 v26, v0
	v_mov_b32_e32 v27, v0
	v_mov_b32_e32 v28, v0
	v_mov_b32_e32 v29, v0
	v_mov_b32_e32 v30, v0
	v_mov_b32_e32 v31, v0
	v_mov_b32_e32 v40, v0
	v_mov_b32_e32 v41, v0
	v_mov_b32_e32 v42, v0
	v_mov_b32_e32 v43, v0
	v_mov_b32_e32 v44, v0
	v_mov_b32_e32 v45, v0
	v_mov_b32_e32 v46, v0
	v_mov_b32_e32 v47, v0
	v_mov_b32_e32 v56, v0
	v_mov_b32_e32 v57, v0
	v_mov_b32_e32 v58, v0
	v_mov_b32_e32 v59, v0
	v_mov_b32_e32 v60, v0
	v_mov_b32_e32 v61, v0
	v_mov_b32_e32 v62, v0
	v_mov_b32_e32 v63, v0
	v_mov_b32_e32 v64, v0
	v_mov_b32_e32 v65, v0
	v_mov_b32_e32 v66, v0
	v_mov_b32_e32 v67, v0
	v_mov_b32_e32 v68, v0
	v_mov_b32_e32 v69, v0
	v_mov_b32_e32 v70, v0
	v_mov_b32_e32 v71, v0
	v_mov_b32_e32 v80, v0
	v_mov_b32_e32 v81, v0
	v_mov_b32_e32 v82, v0
	v_mov_b32_e32 v83, v0
	v_mov_b32_e32 v84, v0
	v_mov_b32_e32 v85, v0
	v_mov_b32_e32 v86, v0
	v_mov_b32_e32 v87, v0
	v_mov_b32_e32 v96, v0
	v_mov_b32_e32 v97, v0
	v_mov_b32_e32 v98, v0
	v_mov_b32_e32 v99, v0
	v_mov_b32_e32 v100, v0
	v_mov_b32_e32 v101, v0
	v_mov_b32_e32 v102, v0
	v_mov_b32_e32 v103, v0
	v_mov_b32_e32 v112, v0
	v_mov_b32_e32 v113, v0
	v_mov_b32_e32 v114, v0
	v_mov_b32_e32 v115, v0
	v_mov_b32_e32 v116, v0
	v_mov_b32_e32 v117, v0
	v_mov_b32_e32 v118, v0
	v_mov_b32_e32 v119, v0
	v_mov_b32_e32 v72, v0
	v_mov_b32_e32 v73, v0
	v_mov_b32_e32 v74, v0
	v_mov_b32_e32 v75, v0
	v_mov_b32_e32 v76, v0
	v_mov_b32_e32 v77, v0
	v_mov_b32_e32 v78, v0
	v_mov_b32_e32 v79, v0
	v_mov_b32_e32 v88, v0
	v_mov_b32_e32 v89, v0
	v_mov_b32_e32 v90, v0
	v_mov_b32_e32 v91, v0
	v_mov_b32_e32 v92, v0
	v_mov_b32_e32 v93, v0
	v_mov_b32_e32 v94, v0
	v_mov_b32_e32 v95, v0
	v_mov_b32_e32 v104, v0
	v_mov_b32_e32 v105, v0
	v_mov_b32_e32 v106, v0
	v_mov_b32_e32 v107, v0
	v_mov_b32_e32 v108, v0
	v_mov_b32_e32 v109, v0
	v_mov_b32_e32 v110, v0
	v_mov_b32_e32 v111, v0
	v_mov_b32_e32 v120, v0
	v_mov_b32_e32 v121, v0
	v_mov_b32_e32 v122, v0
	v_mov_b32_e32 v123, v0
	v_mov_b32_e32 v124, v0
	v_mov_b32_e32 v125, v0
	v_mov_b32_e32 v126, v0
	v_mov_b32_e32 v127, v0

.LBB0_1072:
	s_lshl_b32 s19, s12, 8
	s_add_i32 s19, s19, s68
	v_or_b32_e32 v156, s19, v147
	v_ashrrev_i32_e32 v157, 31, v156
	v_lshl_add_u64 v[128:129], v[156:157], 2, s[16:17]
	v_mov_b32_e32 v144, v240
	v_or_b32_e32 v164, 16, v156
	v_ashrrev_i32_e32 v165, 31, v164
	v_or_b32_e32 v162, 32, v156
	v_or_b32_e32 v160, 48, v156
	v_lshl_add_u64 v[130:131], v[164:165], 2, s[16:17]
	v_ashrrev_i32_e32 v163, 31, v162
	v_ashrrev_i32_e32 v161, 31, v160
	v_lshl_add_u64 v[132:133], v[162:163], 2, s[16:17]
	v_lshl_add_u64 v[134:135], v[160:161], 2, s[16:17]
	v_mov_b32_e32 v178, v241
	v_mov_b32_e32 v177, v242
	v_mov_b32_e32 v176, v243
	v_mov_b32_e32 v165, v244
	v_mov_b32_e32 v163, v245
	v_mov_b32_e32 v161, v246
	v_mov_b32_e32 v157, v247
	s_cmp_lt_u32 s4, 16
	s_cselect_b64 s[12:13], -1, 0
	s_cmp_gt_u32 s4, 7
	s_cselect_b64 s[14:15], -1, 0
	s_and_b64 s[12:13], s[14:15], s[12:13]
	s_and_b64 s[12:13], s[12:13], exec
	s_cselect_b32 s5, 2, 1
	s_cmp_gt_i32 s4, 3
	s_cselect_b64 s[12:13], -1, 0
	s_and_b64 s[14:15], s[12:13], exec
	s_cselect_b32 s18, s5, 0
	s_cmp_gt_i32 s18, 1
	s_mov_b64 s[14:15], -1
	s_waitcnt vmcnt(0)
	v_fmamk_f32 v128, v144, 0x3a000000, v175
	v_mul_f32_e32 v129, 0x4b800000, v128
	v_cmp_gt_f32_e32 vcc, s76, v128
	s_nop 1
	v_cndmask_b32_e32 v128, v128, v129, vcc
	v_rsq_f32_e32 v128, v128
	s_nop 0
	v_mul_f32_e32 v129, 0x45800000, v128
	v_cndmask_b32_e32 v168, v128, v129, vcc
	v_pk_mul_f32 v[126:127], v[126:127], v[168:169] op_sel_hi:[1,0]
	v_pk_mul_f32 v[124:125], v[124:125], v[168:169] op_sel_hi:[1,0]
	v_pk_mul_f32 v[122:123], v[122:123], v[168:169] op_sel_hi:[1,0]
	v_pk_mul_f32 v[120:121], v[120:121], v[168:169] op_sel_hi:[1,0]
	s_cbranch_scc0 .LBB0_1074
	v_mul_f32_e32 v129, 0x3d372713, v120
	v_mul_f32_e32 v129, v120, v129
	v_mul_f32_e32 v130, 0x3d372713, v125
	v_fma_f32 v129, v120, v129, v120
	v_mul_f32_e32 v130, v125, v130
	v_mul_f32_e32 v129, 0x3f4c422a, v129
	v_fma_f32 v130, v125, v130, v125
	v_mul_f32_e32 v129, -2.0, v129
	v_mul_f32_e32 v130, 0x3f4c422a, v130
	v_mul_f32_e32 v129, 0x3fb8aa3b, v129
	v_mul_f32_e32 v130, -2.0, v130
	v_exp_f32_e32 v129, v129
	v_mul_f32_e32 v130, 0x3fb8aa3b, v130
	v_exp_f32_e32 v130, v130
	v_mul_f32_e32 v131, 0x3d372713, v126
	v_add_f32_e32 v129, 1.0, v129
	v_rcp_f32_e32 v158, v129
	v_add_f32_e32 v129, 1.0, v130
	v_mul_f32_e32 v130, 0x3d372713, v121
	v_mul_f32_e32 v132, 0x3d372713, v122
	v_mul_f32_e32 v130, v121, v130
	v_mul_f32_e32 v131, v126, v131
	v_mul_f32_e32 v132, v122, v132
	v_fma_f32 v130, v121, v130, v121
	v_fma_f32 v131, v126, v131, v126
	v_fma_f32 v132, v122, v132, v122
	v_mul_f32_e32 v130, 0x3f4c422a, v130
	v_mul_f32_e32 v131, 0x3f4c422a, v131
	v_mul_f32_e32 v132, 0x3f4c422a, v132
	v_mul_f32_e32 v130, -2.0, v130
	v_mul_f32_e32 v131, -2.0, v131
	v_mul_f32_e32 v132, -2.0, v132
	v_mul_f32_e32 v130, 0x3fb8aa3b, v130
	v_mul_f32_e32 v131, 0x3fb8aa3b, v131
	v_mul_f32_e32 v132, 0x3fb8aa3b, v132
	v_exp_f32_e32 v130, v130
	v_exp_f32_e32 v131, v131
	v_exp_f32_e32 v132, v132
	v_mul_f32_e32 v128, 0x3d372713, v124
	v_add_f32_e32 v133, 1.0, v130
	v_add_f32_e32 v130, 1.0, v131
	v_add_f32_e32 v131, 1.0, v132
	v_mul_f32_e32 v132, 0x3d372713, v127
	v_mul_f32_e32 v134, 0x3d372713, v123
	v_mul_f32_e32 v128, v124, v128
	v_mul_f32_e32 v132, v127, v132
	v_mul_f32_e32 v134, v123, v134
	v_fma_f32 v128, v124, v128, v124
	v_fma_f32 v132, v127, v132, v127
	v_fma_f32 v134, v123, v134, v123
	v_mul_f32_e32 v128, 0x3f4c422a, v128
	v_mul_f32_e32 v132, 0x3f4c422a, v132
	v_mul_f32_e32 v134, 0x3f4c422a, v134
	v_mul_f32_e32 v128, -2.0, v128
	v_mul_f32_e32 v132, -2.0, v132
	v_mul_f32_e32 v134, -2.0, v134
	v_mul_f32_e32 v128, 0x3fb8aa3b, v128
	v_mul_f32_e32 v132, 0x3fb8aa3b, v132
	v_mul_f32_e32 v134, 0x3fb8aa3b, v134
	v_exp_f32_e32 v128, v128
	v_exp_f32_e32 v132, v132
	v_exp_f32_e32 v134, v134
	v_rcp_f32_e32 v166, v131
	v_add_f32_e32 v128, 1.0, v128
	v_add_f32_e32 v131, 1.0, v132
	v_add_f32_e32 v132, 1.0, v134
	v_rcp_f32_e32 v128, v128
	v_rcp_f32_e32 v129, v129
	v_rcp_f32_e32 v130, v130
	v_rcp_f32_e32 v131, v131
	v_rcp_f32_e32 v167, v132
	v_rcp_f32_e32 v159, v133
	v_pk_mul_f32 v[132:133], v[124:125], v[128:129]
	v_pk_mul_f32 v[134:135], v[126:127], v[130:131]
	v_pk_mul_f32 v[130:131], v[122:123], v[166:167]
	v_pk_mul_f32 v[128:129], v[120:121], v[158:159]
	s_mov_b64 s[14:15], 0

.LBB0_1557:
	v_lshl_add_u32 v249, s4, 8, v212
	v_lshlrev_b32_e32 v249, 2, v249
	global_load_dword v240, v249, s[34:35]
	global_load_dword v241, v249, s[34:35] offset:64
	global_load_dword v242, v249, s[34:35] offset:128
	global_load_dword v243, v249, s[34:35] offset:192
	global_load_dword v244, v249, s[34:35] offset:512
	global_load_dword v245, v249, s[34:35] offset:576
	global_load_dword v246, v249, s[34:35] offset:640
	global_load_dword v247, v249, s[34:35] offset:704
	s_ashr_i32 s63, s62, 31
	s_lshl_b64 s[12:13], s[62:63], 20
	s_add_u32 s64, s18, s12
	s_addc_u32 s65, s19, s13
	s_and_b64 s[12:13], s[2:3], exec
	s_cselect_b32 s5, s65, s7
	s_cselect_b32 s9, s64, s6
	s_ashr_i32 s61, s60, 31
	s_lshl_b64 s[12:13], s[60:61], 20
	s_add_u32 s66, s43, s12
	s_addc_u32 s67, s70, s13
	s_and_b64 s[12:13], s[2:3], exec
	s_cselect_b32 s33, s67, s11
	s_cselect_b32 s61, s66, s10
	s_add_u32 s6, s6, 0x80080
	s_addc_u32 s7, s7, 0
	s_add_u32 s63, s10, 0x100
	v_mov_b32_e32 v0, 0
	s_addc_u32 s68, s11, 0
	s_mov_b32 s69, -2
	v_mov_b32_e32 v1, v0
	v_mov_b32_e32 v2, v0
	v_mov_b32_e32 v3, v0
	v_mov_b32_e32 v4, v0
	v_mov_b32_e32 v5, v0
	v_mov_b32_e32 v6, v0
	v_mov_b32_e32 v7, v0
	v_mov_b32_e32 v16, v0
	v_mov_b32_e32 v17, v0
	v_mov_b32_e32 v18, v0
	v_mov_b32_e32 v19, v0
	v_mov_b32_e32 v20, v0
	v_mov_b32_e32 v21, v0
	v_mov_b32_e32 v22, v0
	v_mov_b32_e32 v23, v0
	v_mov_b32_e32 v48, v0
	v_mov_b32_e32 v49, v0
	v_mov_b32_e32 v50, v0
	v_mov_b32_e32 v51, v0
	v_mov_b32_e32 v52, v0
	v_mov_b32_e32 v53, v0
	v_mov_b32_e32 v54, v0
	v_mov_b32_e32 v55, v0
	v_mov_b32_e32 v80, v0
	v_mov_b32_e32 v81, v0
	v_mov_b32_e32 v82, v0
	v_mov_b32_e32 v83, v0
	v_mov_b32_e32 v84, v0
	v_mov_b32_e32 v85, v0
	v_mov_b32_e32 v86, v0
	v_mov_b32_e32 v87, v0
	v_mov_b32_e32 v8, v0
	v_mov_b32_e32 v9, v0
	v_mov_b32_e32 v10, v0
	v_mov_b32_e32 v11, v0
	v_mov_b32_e32 v12, v0
	v_mov_b32_e32 v13, v0
	v_mov_b32_e32 v14, v0
	v_mov_b32_e32 v15, v0
	v_mov_b32_e32 v28, v0
	v_mov_b32_e32 v29, v0
	v_mov_b32_e32 v30, v0
	v_mov_b32_e32 v31, v0
	v_mov_b32_e32 v36, v0
	v_mov_b32_e32 v37, v0
	v_mov_b32_e32 v38, v0
	v_mov_b32_e32 v39, v0
	v_mov_b32_e32 v72, v0
	v_mov_b32_e32 v73, v0
	v_mov_b32_e32 v74, v0
	v_mov_b32_e32 v75, v0
	v_mov_b32_e32 v76, v0
	v_mov_b32_e32 v77, v0
	v_mov_b32_e32 v78, v0
	v_mov_b32_e32 v79, v0
	v_mov_b32_e32 v88, v0
	v_mov_b32_e32 v89, v0
	v_mov_b32_e32 v90, v0
	v_mov_b32_e32 v91, v0
	v_mov_b32_e32 v92, v0
	v_mov_b32_e32 v93, v0
	v_mov_b32_e32 v94, v0
	v_mov_b32_e32 v95, v0
	v_mov_b32_e32 v96, v0
	v_mov_b32_e32 v97, v0
	v_mov_b32_e32 v98, v0
	v_mov_b32_e32 v99, v0
	v_mov_b32_e32 v100, v0
	v_mov_b32_e32 v101, v0
	v_mov_b32_e32 v102, v0
	v_mov_b32_e32 v103, v0
	v_mov_b32_e32 v112, v0
	v_mov_b32_e32 v113, v0
	v_mov_b32_e32 v114, v0
	v_mov_b32_e32 v115, v0
	v_mov_b32_e32 v116, v0
	v_mov_b32_e32 v117, v0
	v_mov_b32_e32 v118, v0
	v_mov_b32_e32 v119, v0
	v_mov_b32_e32 v128, v0
	v_mov_b32_e32 v129, v0
	v_mov_b32_e32 v130, v0
	v_mov_b32_e32 v131, v0
	v_mov_b32_e32 v132, v0
	v_mov_b32_e32 v133, v0
	v_mov_b32_e32 v134, v0
	v_mov_b32_e32 v135, v0
	v_mov_b32_e32 v144, v0
	v_mov_b32_e32 v145, v0
	v_mov_b32_e32 v146, v0
	v_mov_b32_e32 v147, v0
	v_mov_b32_e32 v148, v0
	v_mov_b32_e32 v149, v0
	v_mov_b32_e32 v150, v0
	v_mov_b32_e32 v151, v0
	v_mov_b32_e32 v104, v0
	v_mov_b32_e32 v105, v0
	v_mov_b32_e32 v106, v0
	v_mov_b32_e32 v107, v0
	v_mov_b32_e32 v108, v0
	v_mov_b32_e32 v109, v0
	v_mov_b32_e32 v110, v0
	v_mov_b32_e32 v111, v0
	v_mov_b32_e32 v120, v0
	v_mov_b32_e32 v121, v0
	v_mov_b32_e32 v122, v0
	v_mov_b32_e32 v123, v0
	v_mov_b32_e32 v124, v0
	v_mov_b32_e32 v125, v0
	v_mov_b32_e32 v126, v0
	v_mov_b32_e32 v127, v0
	v_mov_b32_e32 v136, v0
	v_mov_b32_e32 v137, v0
	v_mov_b32_e32 v138, v0
	v_mov_b32_e32 v139, v0
	v_mov_b32_e32 v140, v0
	v_mov_b32_e32 v141, v0
	v_mov_b32_e32 v142, v0
	v_mov_b32_e32 v143, v0
	v_mov_b32_e32 v156, v0
	v_mov_b32_e32 v157, v0
	v_mov_b32_e32 v158, v0
	v_mov_b32_e32 v159, v0
	v_mov_b32_e32 v160, v0
	v_mov_b32_e32 v161, v0
	v_mov_b32_e32 v162, v0
	v_mov_b32_e32 v163, v0
	s_waitcnt vmcnt(0)

.LBB0_1561:
	v_lshl_add_u32 v198, s4, 8, v212
	v_ashrrev_i32_e32 v199, 31, v198
	v_or_b32_e32 v206, 16, v198
	v_or_b32_e32 v204, 32, v198
	v_or_b32_e32 v202, 48, v198
	v_lshl_add_u64 v[24:25], v[198:199], 2, s[34:35]
	v_ashrrev_i32_e32 v207, 31, v206
	v_ashrrev_i32_e32 v205, 31, v204
	v_ashrrev_i32_e32 v203, 31, v202
	v_lshl_add_u64 v[26:27], v[206:207], 2, s[34:35]
	v_lshl_add_u64 v[32:33], v[204:205], 2, s[34:35]
	v_lshl_add_u64 v[34:35], v[202:203], 2, s[34:35]
	v_mov_b32_e32 v164, v240
	v_mov_b32_e32 v228, v241
	v_mov_b32_e32 v227, v242
	v_mov_b32_e32 v226, v243
	v_mov_b32_e32 v224, v244
	v_mov_b32_e32 v223, v245
	v_mov_b32_e32 v222, v246
	v_mov_b32_e32 v221, v247
	s_ashr_i32 s4, s8, 3
	s_cmp_gt_i32 s4, 1
	s_cselect_b64 s[12:13], -1, 0
	s_cmp_lt_i32 s4, 2
	s_cselect_b64 s[6:7], -1, 0
	s_and_b64 s[6:7], s[40:41], s[6:7]
	v_lshlrev_b32_e32 v225, 4, v198
	v_cndmask_b32_e64 v24, 0, 1, s[6:7]
	v_mov_b32_e32 v152, 0
	v_cmp_ne_u32_e64 s[10:11], 1, v24
	v_and_b32_e32 v24, 0xfcf0, v225
	s_andn2_b64 vcc, exec, s[6:7]
	v_lshlrev_b32_e32 v180, 2, v24
	v_mov_b32_e32 v153, v152
	v_mov_b32_e32 v154, v152
	v_mov_b32_e32 v155, v152
	v_mov_b32_e32 v60, v152
	v_mov_b32_e32 v61, v152
	v_mov_b32_e32 v62, v152
	v_mov_b32_e32 v63, v152
	v_mov_b32_e32 v56, v152
	v_mov_b32_e32 v57, v152
	v_mov_b32_e32 v58, v152
	v_mov_b32_e32 v59, v152
	v_mov_b32_e32 v68, v152
	v_mov_b32_e32 v69, v152
	v_mov_b32_e32 v70, v152
	v_mov_b32_e32 v71, v152
	v_mov_b32_e32 v64, v152
	v_mov_b32_e32 v65, v152
	v_mov_b32_e32 v66, v152
	v_mov_b32_e32 v67, v152
	v_mov_b32_e32 v32, v152
	v_mov_b32_e32 v33, v152
	v_mov_b32_e32 v34, v152
	v_mov_b32_e32 v35, v152
	v_mov_b32_e32 v24, v152
	v_mov_b32_e32 v25, v152
	v_mov_b32_e32 v26, v152
	v_mov_b32_e32 v27, v152
	v_mov_b32_e32 v40, v152
	v_mov_b32_e32 v41, v152
	v_mov_b32_e32 v42, v152
	v_mov_b32_e32 v43, v152
	v_mov_b32_e32 v44, v152
	v_mov_b32_e32 v45, v152
	v_mov_b32_e32 v46, v152
	v_mov_b32_e32 v47, v152
	s_cbranch_vccnz .LBB0_1563
	v_lshl_add_u64 v[24:25], v[186:187], 0, v[180:181]
	global_load_dwordx4 v[60:63], v[24:25], off
	global_load_dwordx4 v[56:59], v[24:25], off offset:16
	v_lshl_add_u64 v[40:41], v[188:189], 0, v[180:181]
	global_load_dwordx4 v[152:155], v[40:41], off offset:1040
	global_load_dwordx4 v[68:71], v[40:41], off
	global_load_dwordx4 v[64:67], v[40:41], off offset:16
	global_load_dwordx4 v[32:35], v[24:25], off offset:1024
	s_nop 0
	global_load_dwordx4 v[24:27], v[24:25], off offset:1040
	s_nop 0
	global_load_dwordx4 v[40:43], v[40:41], off offset:1024
	s_waitcnt vmcnt(0)
	v_mov_b32_e32 v44, v152
	v_mov_b32_e32 v45, v153
	v_mov_b32_e32 v46, v154
	v_mov_b32_e32 v47, v155

.LBB0_1791:
	s_waitcnt lgkmcnt(0)
	global_load_dwordx4 v[4:7], v2, s[44:45] offset:512
	global_load_dwordx4 v[36:39], v2, s[46:47] offset:512
	global_load_dwordx4 v[68:71], v2, s[48:49] offset:512
	global_load_dwordx4 v[100:103], v2, s[50:51] offset:512
	global_load_dwordx4 v[8:11], v2, s[44:45] offset:528
	global_load_dwordx4 v[40:43], v2, s[46:47] offset:528
	global_load_dwordx4 v[72:75], v2, s[48:49] offset:528
	global_load_dwordx4 v[104:107], v2, s[50:51] offset:528
	global_load_dwordx4 v[12:15], v2, s[44:45] offset:544
	global_load_dwordx4 v[44:47], v2, s[46:47] offset:544
	global_load_dwordx4 v[76:79], v2, s[48:49] offset:544
	global_load_dwordx4 v[108:111], v2, s[50:51] offset:544
	global_load_dwordx4 v[16:19], v2, s[44:45] offset:560
	global_load_dwordx4 v[48:51], v2, s[46:47] offset:560
	global_load_dwordx4 v[80:83], v2, s[48:49] offset:560
	global_load_dwordx4 v[112:115], v2, s[50:51] offset:560
	global_load_dwordx4 v[20:23], v2, s[44:45] offset:576
	global_load_dwordx4 v[52:55], v2, s[46:47] offset:576
	global_load_dwordx4 v[84:87], v2, s[48:49] offset:576
	global_load_dwordx4 v[116:119], v2, s[50:51] offset:576
	global_load_dwordx4 v[24:27], v2, s[44:45] offset:592
	global_load_dwordx4 v[56:59], v2, s[46:47] offset:592
	global_load_dwordx4 v[88:91], v2, s[48:49] offset:592
	global_load_dwordx4 v[120:123], v2, s[50:51] offset:592
	global_load_dwordx4 v[28:31], v2, s[44:45] offset:608
	global_load_dwordx4 v[60:63], v2, s[46:47] offset:608
	global_load_dwordx4 v[92:95], v2, s[48:49] offset:608
	global_load_dwordx4 v[124:127], v2, s[50:51] offset:608
	global_load_dwordx4 v[32:35], v2, s[44:45] offset:624
	global_load_dwordx4 v[64:67], v2, s[46:47] offset:624
	global_load_dwordx4 v[96:99], v2, s[48:49] offset:624
	global_load_dwordx4 v[128:131], v2, s[50:51] offset:624
	s_waitcnt vmcnt(28)
	v_fma_f32 v1, v4, v36, v1
	v_fma_f32 v0, v68, v100, v0
	v_fma_f32 v1, v5, v37, v1
	v_fma_f32 v0, v69, v101, v0
	v_fma_f32 v1, v6, v38, v1
	v_fma_f32 v0, v70, v102, v0
	v_fma_f32 v1, v7, v39, v1
	v_fma_f32 v0, v71, v103, v0
	global_load_dwordx4 v[4:7], v2, s[44:45] offset:640
	global_load_dwordx4 v[36:39], v2, s[46:47] offset:640
	global_load_dwordx4 v[68:71], v2, s[48:49] offset:640
	global_load_dwordx4 v[100:103], v2, s[50:51] offset:640
	s_waitcnt vmcnt(28)
	v_fma_f32 v1, v8, v40, v1
	v_fma_f32 v0, v72, v104, v0
	v_fma_f32 v1, v9, v41, v1
	v_fma_f32 v0, v73, v105, v0
	v_fma_f32 v1, v10, v42, v1
	v_fma_f32 v0, v74, v106, v0
	v_fma_f32 v1, v11, v43, v1
	v_fma_f32 v0, v75, v107, v0
	global_load_dwordx4 v[8:11], v2, s[44:45] offset:656
	global_load_dwordx4 v[40:43], v2, s[46:47] offset:656
	global_load_dwordx4 v[72:75], v2, s[48:49] offset:656
	global_load_dwordx4 v[104:107], v2, s[50:51] offset:656
	s_waitcnt vmcnt(28)
	v_fma_f32 v1, v12, v44, v1
	v_fma_f32 v0, v76, v108, v0
	v_fma_f32 v1, v13, v45, v1
	v_fma_f32 v0, v77, v109, v0
	v_fma_f32 v1, v14, v46, v1
	v_fma_f32 v0, v78, v110, v0
	v_fma_f32 v1, v15, v47, v1
	v_fma_f32 v0, v79, v111, v0
	global_load_dwordx4 v[12:15], v2, s[44:45] offset:672
	global_load_dwordx4 v[44:47], v2, s[46:47] offset:672
	global_load_dwordx4 v[76:79], v2, s[48:49] offset:672
	global_load_dwordx4 v[108:111], v2, s[50:51] offset:672
	s_waitcnt vmcnt(28)
	v_fma_f32 v1, v16, v48, v1
	v_fma_f32 v0, v80, v112, v0
	v_fma_f32 v1, v17, v49, v1
	v_fma_f32 v0, v81, v113, v0
	v_fma_f32 v1, v18, v50, v1
	v_fma_f32 v0, v82, v114, v0
	v_fma_f32 v1, v19, v51, v1
	v_fma_f32 v0, v83, v115, v0
	global_load_dwordx4 v[16:19], v2, s[44:45] offset:688
	global_load_dwordx4 v[48:51], v2, s[46:47] offset:688
	global_load_dwordx4 v[80:83], v2, s[48:49] offset:688
	global_load_dwordx4 v[112:115], v2, s[50:51] offset:688
	s_waitcnt vmcnt(28)
	v_fma_f32 v1, v20, v52, v1
	v_fma_f32 v0, v84, v116, v0
	v_fma_f32 v1, v21, v53, v1
	v_fma_f32 v0, v85, v117, v0
	v_fma_f32 v1, v22, v54, v1
	v_fma_f32 v0, v86, v118, v0
	v_fma_f32 v1, v23, v55, v1
	v_fma_f32 v0, v87, v119, v0
	global_load_dwordx4 v[20:23], v2, s[44:45] offset:704
	global_load_dwordx4 v[52:55], v2, s[46:47] offset:704
	global_load_dwordx4 v[84:87], v2, s[48:49] offset:704
	global_load_dwordx4 v[116:119], v2, s[50:51] offset:704
	s_waitcnt vmcnt(28)
	v_fma_f32 v1, v24, v56, v1
	v_fma_f32 v0, v88, v120, v0
	v_fma_f32 v1, v25, v57, v1
	v_fma_f32 v0, v89, v121, v0
	v_fma_f32 v1, v26, v58, v1
	v_fma_f32 v0, v90, v122, v0
	v_fma_f32 v1, v27, v59, v1
	v_fma_f32 v0, v91, v123, v0
	global_load_dwordx4 v[24:27], v2, s[44:45] offset:720
	global_load_dwordx4 v[56:59], v2, s[46:47] offset:720
	global_load_dwordx4 v[88:91], v2, s[48:49] offset:720
	global_load_dwordx4 v[120:123], v2, s[50:51] offset:720
	s_waitcnt vmcnt(28)
	v_fma_f32 v1, v28, v60, v1
	v_fma_f32 v0, v92, v124, v0
	v_fma_f32 v1, v29, v61, v1
	v_fma_f32 v0, v93, v125, v0
	v_fma_f32 v1, v30, v62, v1
	v_fma_f32 v0, v94, v126, v0
	v_fma_f32 v1, v31, v63, v1
	v_fma_f32 v0, v95, v127, v0
	global_load_dwordx4 v[28:31], v2, s[44:45] offset:736
	global_load_dwordx4 v[60:63], v2, s[46:47] offset:736
	global_load_dwordx4 v[92:95], v2, s[48:49] offset:736
	global_load_dwordx4 v[124:127], v2, s[50:51] offset:736
	s_waitcnt vmcnt(28)
	v_fma_f32 v1, v32, v64, v1
	v_fma_f32 v0, v96, v128, v0
	v_fma_f32 v1, v33, v65, v1
	v_fma_f32 v0, v97, v129, v0
	v_fma_f32 v1, v34, v66, v1
	v_fma_f32 v0, v98, v130, v0
	v_fma_f32 v1, v35, v67, v1
	v_fma_f32 v0, v99, v131, v0
	global_load_dwordx4 v[32:35], v2, s[44:45] offset:752
	global_load_dwordx4 v[64:67], v2, s[46:47] offset:752
	global_load_dwordx4 v[96:99], v2, s[48:49] offset:752
	global_load_dwordx4 v[128:131], v2, s[50:51] offset:752
	s_waitcnt vmcnt(28)
	v_fma_f32 v1, v4, v36, v1
	v_fma_f32 v0, v68, v100, v0
	v_fma_f32 v1, v5, v37, v1
	v_fma_f32 v0, v69, v101, v0
	v_fma_f32 v1, v6, v38, v1
	v_fma_f32 v0, v70, v102, v0
	v_fma_f32 v1, v7, v39, v1
	v_fma_f32 v0, v71, v103, v0
	global_load_dwordx4 v[4:7], v2, s[44:45] offset:768
	global_load_dwordx4 v[36:39], v2, s[46:47] offset:768
	global_load_dwordx4 v[68:71], v2, s[48:49] offset:768
	global_load_dwordx4 v[100:103], v2, s[50:51] offset:768
	s_waitcnt vmcnt(28)
	v_fma_f32 v1, v8, v40, v1
	v_fma_f32 v0, v72, v104, v0
	v_fma_f32 v1, v9, v41, v1
	v_fma_f32 v0, v73, v105, v0
	v_fma_f32 v1, v10, v42, v1
	v_fma_f32 v0, v74, v106, v0
	v_fma_f32 v1, v11, v43, v1
	v_fma_f32 v0, v75, v107, v0
	global_load_dwordx4 v[8:11], v2, s[44:45] offset:784
	global_load_dwordx4 v[40:43], v2, s[46:47] offset:784
	global_load_dwordx4 v[72:75], v2, s[48:49] offset:784
	global_load_dwordx4 v[104:107], v2, s[50:51] offset:784
	s_waitcnt vmcnt(28)
	v_fma_f32 v1, v12, v44, v1
	v_fma_f32 v0, v76, v108, v0
	v_fma_f32 v1, v13, v45, v1
	v_fma_f32 v0, v77, v109, v0
	v_fma_f32 v1, v14, v46, v1
	v_fma_f32 v0, v78, v110, v0
	v_fma_f32 v1, v15, v47, v1
	v_fma_f32 v0, v79, v111, v0
	global_load_dwordx4 v[12:15], v2, s[44:45] offset:800
	global_load_dwordx4 v[44:47], v2, s[46:47] offset:800
	global_load_dwordx4 v[76:79], v2, s[48:49] offset:800
	global_load_dwordx4 v[108:111], v2, s[50:51] offset:800
	s_waitcnt vmcnt(28)
	v_fma_f32 v1, v16, v48, v1
	v_fma_f32 v0, v80, v112, v0
	v_fma_f32 v1, v17, v49, v1
	v_fma_f32 v0, v81, v113, v0
	v_fma_f32 v1, v18, v50, v1
	v_fma_f32 v0, v82, v114, v0
	v_fma_f32 v1, v19, v51, v1
	v_fma_f32 v0, v83, v115, v0
	global_load_dwordx4 v[16:19], v2, s[44:45] offset:816
	global_load_dwordx4 v[48:51], v2, s[46:47] offset:816
	global_load_dwordx4 v[80:83], v2, s[48:49] offset:816
	global_load_dwordx4 v[112:115], v2, s[50:51] offset:816
	s_waitcnt vmcnt(28)
	v_fma_f32 v1, v20, v52, v1
	v_fma_f32 v0, v84, v116, v0
	v_fma_f32 v1, v21, v53, v1
	v_fma_f32 v0, v85, v117, v0
	v_fma_f32 v1, v22, v54, v1
	v_fma_f32 v0, v86, v118, v0
	v_fma_f32 v1, v23, v55, v1
	v_fma_f32 v0, v87, v119, v0
	global_load_dwordx4 v[20:23], v2, s[44:45] offset:832
	global_load_dwordx4 v[52:55], v2, s[46:47] offset:832
	global_load_dwordx4 v[84:87], v2, s[48:49] offset:832
	global_load_dwordx4 v[116:119], v2, s[50:51] offset:832
	s_waitcnt vmcnt(28)
	v_fma_f32 v1, v24, v56, v1
	v_fma_f32 v0, v88, v120, v0
	v_fma_f32 v1, v25, v57, v1
	v_fma_f32 v0, v89, v121, v0
	v_fma_f32 v1, v26, v58, v1
	v_fma_f32 v0, v90, v122, v0
	v_fma_f32 v1, v27, v59, v1
	v_fma_f32 v0, v91, v123, v0
	global_load_dwordx4 v[24:27], v2, s[44:45] offset:848
	global_load_dwordx4 v[56:59], v2, s[46:47] offset:848
	global_load_dwordx4 v[88:91], v2, s[48:49] offset:848
	global_load_dwordx4 v[120:123], v2, s[50:51] offset:848
	s_waitcnt vmcnt(28)
	v_fma_f32 v1, v28, v60, v1
	v_fma_f32 v0, v92, v124, v0
	v_fma_f32 v1, v29, v61, v1
	v_fma_f32 v0, v93, v125, v0
	v_fma_f32 v1, v30, v62, v1
	v_fma_f32 v0, v94, v126, v0
	v_fma_f32 v1, v31, v63, v1
	v_fma_f32 v0, v95, v127, v0
	global_load_dwordx4 v[28:31], v2, s[44:45] offset:864
	global_load_dwordx4 v[60:63], v2, s[46:47] offset:864
	global_load_dwordx4 v[92:95], v2, s[48:49] offset:864
	global_load_dwordx4 v[124:127], v2, s[50:51] offset:864
	s_waitcnt vmcnt(28)
	v_fma_f32 v1, v32, v64, v1
	v_fma_f32 v0, v96, v128, v0
	v_fma_f32 v1, v33, v65, v1
	v_fma_f32 v0, v97, v129, v0
	v_fma_f32 v1, v34, v66, v1
	v_fma_f32 v0, v98, v130, v0
	v_fma_f32 v1, v35, v67, v1
	v_fma_f32 v0, v99, v131, v0
	global_load_dwordx4 v[32:35], v2, s[44:45] offset:880
	global_load_dwordx4 v[64:67], v2, s[46:47] offset:880
	global_load_dwordx4 v[96:99], v2, s[48:49] offset:880
	global_load_dwordx4 v[128:131], v2, s[50:51] offset:880
	s_waitcnt vmcnt(28)
	v_fma_f32 v1, v4, v36, v1
	v_fma_f32 v0, v68, v100, v0
	v_fma_f32 v1, v5, v37, v1
	v_fma_f32 v0, v69, v101, v0
	v_fma_f32 v1, v6, v38, v1
	v_fma_f32 v0, v70, v102, v0
	v_fma_f32 v1, v7, v39, v1
	v_fma_f32 v0, v71, v103, v0
	global_load_dwordx4 v[4:7], v2, s[44:45] offset:896
	global_load_dwordx4 v[36:39], v2, s[46:47] offset:896
	global_load_dwordx4 v[68:71], v2, s[48:49] offset:896
	global_load_dwordx4 v[100:103], v2, s[50:51] offset:896
	s_waitcnt vmcnt(28)
	v_fma_f32 v1, v8, v40, v1
	v_fma_f32 v0, v72, v104, v0
	v_fma_f32 v1, v9, v41, v1
	v_fma_f32 v0, v73, v105, v0
	v_fma_f32 v1, v10, v42, v1
	v_fma_f32 v0, v74, v106, v0
	v_fma_f32 v1, v11, v43, v1
	v_fma_f32 v0, v75, v107, v0
	global_load_dwordx4 v[8:11], v2, s[44:45] offset:912
	global_load_dwordx4 v[40:43], v2, s[46:47] offset:912
	global_load_dwordx4 v[72:75], v2, s[48:49] offset:912
	global_load_dwordx4 v[104:107], v2, s[50:51] offset:912
	s_waitcnt vmcnt(28)
	v_fma_f32 v1, v12, v44, v1
	v_fma_f32 v0, v76, v108, v0
	v_fma_f32 v1, v13, v45, v1
	v_fma_f32 v0, v77, v109, v0
	v_fma_f32 v1, v14, v46, v1
	v_fma_f32 v0, v78, v110, v0
	v_fma_f32 v1, v15, v47, v1
	v_fma_f32 v0, v79, v111, v0
	global_load_dwordx4 v[12:15], v2, s[44:45] offset:928
	global_load_dwordx4 v[44:47], v2, s[46:47] offset:928
	global_load_dwordx4 v[76:79], v2, s[48:49] offset:928
	global_load_dwordx4 v[108:111], v2, s[50:51] offset:928
	s_waitcnt vmcnt(28)
	v_fma_f32 v1, v16, v48, v1
	v_fma_f32 v0, v80, v112, v0
	v_fma_f32 v1, v17, v49, v1
	v_fma_f32 v0, v81, v113, v0
	v_fma_f32 v1, v18, v50, v1
	v_fma_f32 v0, v82, v114, v0
	v_fma_f32 v1, v19, v51, v1
	v_fma_f32 v0, v83, v115, v0
	global_load_dwordx4 v[16:19], v2, s[44:45] offset:944
	global_load_dwordx4 v[48:51], v2, s[46:47] offset:944
	global_load_dwordx4 v[80:83], v2, s[48:49] offset:944
	global_load_dwordx4 v[112:115], v2, s[50:51] offset:944
	s_waitcnt vmcnt(28)
	v_fma_f32 v1, v20, v52, v1
	v_fma_f32 v0, v84, v116, v0
	v_fma_f32 v1, v21, v53, v1
	v_fma_f32 v0, v85, v117, v0
	v_fma_f32 v1, v22, v54, v1
	v_fma_f32 v0, v86, v118, v0
	v_fma_f32 v1, v23, v55, v1
	v_fma_f32 v0, v87, v119, v0
	global_load_dwordx4 v[20:23], v2, s[44:45] offset:960
	global_load_dwordx4 v[52:55], v2, s[46:47] offset:960
	global_load_dwordx4 v[84:87], v2, s[48:49] offset:960
	global_load_dwordx4 v[116:119], v2, s[50:51] offset:960
	s_waitcnt vmcnt(28)
	v_fma_f32 v1, v24, v56, v1
	v_fma_f32 v0, v88, v120, v0
	v_fma_f32 v1, v25, v57, v1
	v_fma_f32 v0, v89, v121, v0
	v_fma_f32 v1, v26, v58, v1
	v_fma_f32 v0, v90, v122, v0
	v_fma_f32 v1, v27, v59, v1
	v_fma_f32 v0, v91, v123, v0
	global_load_dwordx4 v[24:27], v2, s[44:45] offset:976
	global_load_dwordx4 v[56:59], v2, s[46:47] offset:976
	global_load_dwordx4 v[88:91], v2, s[48:49] offset:976
	global_load_dwordx4 v[120:123], v2, s[50:51] offset:976
	s_waitcnt vmcnt(28)
	v_fma_f32 v1, v28, v60, v1
	v_fma_f32 v0, v92, v124, v0
	v_fma_f32 v1, v29, v61, v1
	v_fma_f32 v0, v93, v125, v0
	v_fma_f32 v1, v30, v62, v1
	v_fma_f32 v0, v94, v126, v0
	v_fma_f32 v1, v31, v63, v1
	v_fma_f32 v0, v95, v127, v0
	global_load_dwordx4 v[28:31], v2, s[44:45] offset:992
	global_load_dwordx4 v[60:63], v2, s[46:47] offset:992
	global_load_dwordx4 v[92:95], v2, s[48:49] offset:992
	global_load_dwordx4 v[124:127], v2, s[50:51] offset:992
	s_waitcnt vmcnt(28)
	v_fma_f32 v1, v32, v64, v1
	v_fma_f32 v0, v96, v128, v0
	v_fma_f32 v1, v33, v65, v1
	v_fma_f32 v0, v97, v129, v0
	v_fma_f32 v1, v34, v66, v1
	v_fma_f32 v0, v98, v130, v0
	v_fma_f32 v1, v35, v67, v1
	v_fma_f32 v0, v99, v131, v0
	global_load_dwordx4 v[32:35], v2, s[44:45] offset:1008
	global_load_dwordx4 v[64:67], v2, s[46:47] offset:1008
	global_load_dwordx4 v[96:99], v2, s[48:49] offset:1008
	global_load_dwordx4 v[128:131], v2, s[50:51] offset:1008
	s_waitcnt vmcnt(28)
	v_fma_f32 v1, v4, v36, v1
	v_fma_f32 v0, v68, v100, v0
	v_fma_f32 v1, v5, v37, v1
	v_fma_f32 v0, v69, v101, v0
	v_fma_f32 v1, v6, v38, v1
	v_fma_f32 v0, v70, v102, v0
	v_fma_f32 v1, v7, v39, v1
	v_fma_f32 v0, v71, v103, v0
	s_waitcnt vmcnt(24)
	v_fma_f32 v1, v8, v40, v1
	v_fma_f32 v0, v72, v104, v0
	v_fma_f32 v1, v9, v41, v1
	v_fma_f32 v0, v73, v105, v0
	v_fma_f32 v1, v10, v42, v1
	v_fma_f32 v0, v74, v106, v0
	v_fma_f32 v1, v11, v43, v1
	v_fma_f32 v0, v75, v107, v0
	s_waitcnt vmcnt(20)
	v_fma_f32 v1, v12, v44, v1
	v_fma_f32 v0, v76, v108, v0
	v_fma_f32 v1, v13, v45, v1
	v_fma_f32 v0, v77, v109, v0
	v_fma_f32 v1, v14, v46, v1
	v_fma_f32 v0, v78, v110, v0
	v_fma_f32 v1, v15, v47, v1
	v_fma_f32 v0, v79, v111, v0
	s_waitcnt vmcnt(16)
	v_fma_f32 v1, v16, v48, v1
	v_fma_f32 v0, v80, v112, v0
	v_fma_f32 v1, v17, v49, v1
	v_fma_f32 v0, v81, v113, v0
	v_fma_f32 v1, v18, v50, v1
	v_fma_f32 v0, v82, v114, v0
	v_fma_f32 v1, v19, v51, v1
	v_fma_f32 v0, v83, v115, v0
	s_waitcnt vmcnt(12)
	v_fma_f32 v1, v20, v52, v1
	v_fma_f32 v0, v84, v116, v0
	v_fma_f32 v1, v21, v53, v1
	v_fma_f32 v0, v85, v117, v0
	v_fma_f32 v1, v22, v54, v1
	v_fma_f32 v0, v86, v118, v0
	v_fma_f32 v1, v23, v55, v1
	v_fma_f32 v0, v87, v119, v0
	s_waitcnt vmcnt(8)
	v_fma_f32 v1, v24, v56, v1
	v_fma_f32 v0, v88, v120, v0
	v_fma_f32 v1, v25, v57, v1
	v_fma_f32 v0, v89, v121, v0
	v_fma_f32 v1, v26, v58, v1
	v_fma_f32 v0, v90, v122, v0
	v_fma_f32 v1, v27, v59, v1
	v_fma_f32 v0, v91, v123, v0
	s_waitcnt vmcnt(4)
	v_fma_f32 v1, v28, v60, v1
	v_fma_f32 v0, v92, v124, v0
	v_fma_f32 v1, v29, v61, v1
	v_fma_f32 v0, v93, v125, v0
	v_fma_f32 v1, v30, v62, v1
	v_fma_f32 v0, v94, v126, v0
	v_fma_f32 v1, v31, v63, v1
	v_fma_f32 v0, v95, v127, v0
	s_waitcnt vmcnt(0)
	v_fma_f32 v1, v32, v64, v1
	v_fma_f32 v0, v96, v128, v0
	v_fma_f32 v1, v33, v65, v1
	v_fma_f32 v0, v97, v129, v0
	v_fma_f32 v1, v34, v66, v1
	v_fma_f32 v0, v98, v130, v0
	v_fma_f32 v1, v35, v67, v1
	v_fma_f32 v0, v99, v131, v0
	s_movk_i32 s2, 0x100
	v_cmp_gt_i32_e32 vcc, s2, v176
	s_and_saveexec_b64 s[2:3], vcc
	s_cbranch_execz .LBB0_1794
	v_readlane_b32 s8, v248, 0
	v_ashrrev_i32_e32 v177, 31, v176
	v_readlane_b32 s9, v248, 1
	v_readlane_b32 s10, v248, 2
	v_readlane_b32 s11, v248, 3
	v_lshl_add_u64 v[2:3], v[176:177], 2, s[8:9]
	global_load_dword v2, v[2:3], off offset:1024
	v_lshl_add_u32 v3, v176, 2, 0
	v_add_u32_e32 v3, 0x24000, v3
	v_readlane_b32 s12, v248, 4
	v_readlane_b32 s13, v248, 5
	v_readlane_b32 s14, v248, 6
	v_readlane_b32 s15, v248, 7
	s_waitcnt vmcnt(0)
	ds_write_b32 v3, v2

.Latt_pv1_4:
	s_waitcnt lgkmcnt(6)
	v_mfma_f32_32x32x16_bf16 v[112:127], v[206:209], v[242:245], v[112:127]
	ds_read_b64_tr_b16 v[226:227], v205 offset:16640
	ds_read_b64_tr_b16 v[228:229], v205 offset:20736
	s_waitcnt lgkmcnt(6)
	v_mfma_f32_32x32x16_bf16 v[96:111], v[210:213], v[242:245], v[96:111]
	ds_read_b64_tr_b16 v[230:231], v218 offset:16640
	ds_read_b64_tr_b16 v[232:233], v218 offset:20736
	s_cmp_lg_u64 s[18:19], 0
	s_cbranch_scc1 .Latt_nd0_4
	s_sub_i32 s100, s76, 1
	s_cmp_eq_u32 s76, 0
	s_cselect_b32 s100, 2, s100
	s_lshl_b32 s101, s100, 14
	s_add_i32 m0, s73, s101
	s_nop 0
	global_load_lds_dwordx4 v178, s[14:15]

.Latt_nd1_4:
	s_waitcnt lgkmcnt(6)
	v_mfma_f32_32x32x16_bf16 v[48:63], v[226:229], v[242:245], v[48:63]
	ds_read_b64_tr_b16 v[206:207], v205 offset:24576
	ds_read_b64_tr_b16 v[208:209], v205 offset:28672
	s_waitcnt lgkmcnt(6)
	v_mfma_f32_32x32x16_bf16 v[32:47], v[230:233], v[242:245], v[32:47]
	ds_read_b64_tr_b16 v[210:211], v218 offset:24576
	ds_read_b64_tr_b16 v[212:213], v218 offset:28672
	s_cmp_lg_u64 s[18:19], 0
	s_cbranch_scc1 .Latt_nd2_4
	s_lshl_b32 s101, s100, 15
	s_add_i32 m0, s74, s101
	s_add_u32 s100, s14, 0x1000
	s_addc_u32 s101, s15, 0
	global_load_lds_dwordx4 v182, s[100:101]

.Latt_pv1_5:
	s_waitcnt lgkmcnt(6)
	v_mfma_f32_32x32x16_bf16 v[112:127], v[206:209], v[242:245], v[112:127]
	ds_read_b64_tr_b16 v[226:227], v205 offset:16640
	ds_read_b64_tr_b16 v[228:229], v205 offset:20736
	s_waitcnt lgkmcnt(6)
	v_mfma_f32_32x32x16_bf16 v[96:111], v[210:213], v[242:245], v[96:111]
	ds_read_b64_tr_b16 v[230:231], v218 offset:16640
	ds_read_b64_tr_b16 v[232:233], v218 offset:20736
	s_cmp_lg_u64 s[18:19], 0
	s_cbranch_scc1 .Latt_nd0_5
	s_sub_i32 s100, s33, 1
	s_cmp_eq_u32 s33, 0
	s_cselect_b32 s100, 2, s100
	s_lshl_b32 s101, s100, 14
	s_add_i32 m0, s73, s101
	s_nop 0
	global_load_lds_dwordx4 v178, s[12:13]

.Latt_nd1_5:
	s_waitcnt lgkmcnt(6)
	v_mfma_f32_32x32x16_bf16 v[48:63], v[226:229], v[242:245], v[48:63]
	ds_read_b64_tr_b16 v[206:207], v205 offset:24576
	ds_read_b64_tr_b16 v[208:209], v205 offset:28672
	s_waitcnt lgkmcnt(6)
	v_mfma_f32_32x32x16_bf16 v[32:47], v[230:233], v[242:245], v[32:47]
	ds_read_b64_tr_b16 v[210:211], v218 offset:24576
	ds_read_b64_tr_b16 v[212:213], v218 offset:28672
	s_cmp_lg_u64 s[18:19], 0
	s_cbranch_scc1 .Latt_nd2_5
	s_lshl_b32 s101, s100, 15
	s_add_i32 m0, s74, s101
	s_add_u32 s100, s12, 0xf00
	s_addc_u32 s101, s13, 0
	global_load_lds_dwordx4 v182, s[100:101]

.Latt_pv1_6:
	s_waitcnt lgkmcnt(6)
	v_mfma_f32_32x32x16_bf16 v[112:127], v[206:209], v[242:245], v[112:127]
	ds_read_b64_tr_b16 v[226:227], v205 offset:16640
	ds_read_b64_tr_b16 v[228:229], v205 offset:20736
	s_waitcnt lgkmcnt(6)
	v_mfma_f32_32x32x16_bf16 v[96:111], v[210:213], v[242:245], v[96:111]
	ds_read_b64_tr_b16 v[230:231], v218 offset:16640
	ds_read_b64_tr_b16 v[232:233], v218 offset:20736
	s_cmp_lg_u64 s[12:13], 0
	s_cbranch_scc1 .Latt_nd0_6
	s_sub_i32 s100, s34, 1
	s_cmp_eq_u32 s34, 0
	s_cselect_b32 s100, 2, s100
	s_lshl_b32 s101, s100, 14
	s_add_i32 m0, s36, s101
	s_nop 0
	global_load_lds_dwordx4 v178, s[20:21]
.Latt_nd0_6:
	s_waitcnt lgkmcnt(6)
	v_mfma_f32_32x32x16_bf16 v[80:95], v[214:217], v[242:245], v[80:95]
	ds_read_b64_tr_b16 v[234:235], v219 offset:16640
	ds_read_b64_tr_b16 v[236:237], v219 offset:20736
	s_waitcnt lgkmcnt(6)
	v_mfma_f32_32x32x16_bf16 v[64:79], v[222:225], v[242:245], v[64:79]
	ds_read_b64_tr_b16 v[238:239], v221 offset:16640
	ds_read_b64_tr_b16 v[240:241], v221 offset:20736
	s_cmp_lg_u64 s[12:13], 0
	s_cbranch_scc1 .Latt_nd1_6
	s_add_i32 m0, m0, 0x400
	s_nop 0
	global_load_lds_dwordx4 v180, s[20:21]
.Latt_nd1_6:
	s_waitcnt lgkmcnt(6)
	v_mfma_f32_32x32x16_bf16 v[48:63], v[226:229], v[242:245], v[48:63]
	ds_read_b64_tr_b16 v[206:207], v205 offset:24576
	ds_read_b64_tr_b16 v[208:209], v205 offset:28672
	s_waitcnt lgkmcnt(6)
	v_mfma_f32_32x32x16_bf16 v[32:47], v[230:233], v[242:245], v[32:47]
	ds_read_b64_tr_b16 v[210:211], v218 offset:24576
	ds_read_b64_tr_b16 v[212:213], v218 offset:28672
	s_cmp_lg_u64 s[12:13], 0
	s_cbranch_scc1 .Latt_nd2_6
	s_lshl_b32 s101, s100, 15
	s_add_i32 m0, s37, s101
	s_add_u32 s100, s20, 0x1000
	s_addc_u32 s101, s21, 0
	global_load_lds_dwordx4 v182, s[100:101]

.Latt_pv1_7:
	s_waitcnt lgkmcnt(6)
	v_mfma_f32_32x32x16_bf16 v[112:127], v[206:209], v[242:245], v[112:127]
	ds_read_b64_tr_b16 v[226:227], v205 offset:16640
	ds_read_b64_tr_b16 v[228:229], v205 offset:20736
	s_waitcnt lgkmcnt(6)
	v_mfma_f32_32x32x16_bf16 v[96:111], v[210:213], v[242:245], v[96:111]
	ds_read_b64_tr_b16 v[230:231], v218 offset:16640
	ds_read_b64_tr_b16 v[232:233], v218 offset:20736
	s_cmp_lg_u64 s[8:9], 0
	s_cbranch_scc1 .Latt_nd0_7
	s_sub_i32 s100, s11, 1
	s_cmp_eq_u32 s11, 0
	s_cselect_b32 s100, 2, s100
	s_lshl_b32 s101, s100, 14
	s_add_i32 m0, s36, s101
	s_nop 0
	global_load_lds_dwordx4 v178, s[22:23]
.Latt_nd0_7:
	s_waitcnt lgkmcnt(6)
	v_mfma_f32_32x32x16_bf16 v[80:95], v[214:217], v[242:245], v[80:95]
	ds_read_b64_tr_b16 v[234:235], v219 offset:16640
	ds_read_b64_tr_b16 v[236:237], v219 offset:20736
	s_waitcnt lgkmcnt(6)
	v_mfma_f32_32x32x16_bf16 v[64:79], v[222:225], v[242:245], v[64:79]
	ds_read_b64_tr_b16 v[238:239], v221 offset:16640
	ds_read_b64_tr_b16 v[240:241], v221 offset:20736
	s_cmp_lg_u64 s[8:9], 0
	s_cbranch_scc1 .Latt_nd1_7
	s_add_i32 m0, m0, 0x400
	s_nop 0
	global_load_lds_dwordx4 v180, s[22:23]
.Latt_nd1_7:
	s_waitcnt lgkmcnt(6)
	v_mfma_f32_32x32x16_bf16 v[48:63], v[226:229], v[242:245], v[48:63]
	ds_read_b64_tr_b16 v[206:207], v205 offset:24576
	ds_read_b64_tr_b16 v[208:209], v205 offset:28672
	s_waitcnt lgkmcnt(6)
	v_mfma_f32_32x32x16_bf16 v[32:47], v[230:233], v[242:245], v[32:47]
	ds_read_b64_tr_b16 v[210:211], v218 offset:24576
	ds_read_b64_tr_b16 v[212:213], v218 offset:28672
	s_cmp_lg_u64 s[8:9], 0
	s_cbranch_scc1 .Latt_nd2_7
	s_lshl_b32 s101, s100, 15
	s_add_i32 m0, s37, s101
	s_add_u32 s100, s22, 0xf00
	s_addc_u32 s101, s23, 0
	global_load_lds_dwordx4 v182, s[100:101]
